# epilogue vmcnt drain waits relaxed (epi1), wconv ticket prefetch, silu/sigmoid f32 division via v_rcp_f32*mul in conv epilogue+prep (f32 kept)
# speedup vs baseline: 1.0227x; 1.0227x over previous
; DI void phase_conv(const P& p, int layer) {
;     ...
;   for (int idx = bid_ * 512 + tid_; idx < total; idx += gridDim.x * 512) {
;     const int f = (idx % (DFF / 4)) * 4, rowi = idx / (DFF / 4), pm = rowi >> 1, rr = rowi & 1, t = pm * 256 + rr;
;     const float* hc = halo + (size_t)pm * 4 * NUP; const float* hp = halo + (size_t)(pm > 0 ? pm - 1 : 0) * 4 * NUP;
;     const float4 gc = *reinterpret_cast<const float4*>(hc + (size_t)rr * NUP + f), vc = *reinterpret_cast<const float4*>(hc + (size_t)rr * NUP + DFF + f);
;     const float pz = (pm > 0) ? 1.f : 0.f;
;     float4 p3g = *reinterpret_cast<const float4*>(hp + (size_t)3 * NUP + f), p3v = *reinterpret_cast<const float4*>(hp + (size_t)3 * NUP + DFF + f);
;     float4 p2g = *reinterpret_cast<const float4*>(hp + (size_t)2 * NUP + f), p2v = *reinterpret_cast<const float4*>(hp + (size_t)2 * NUP + DFF + f);
;     p3g.x *= pz; p3g.y *= pz; p3g.z *= pz; p3g.w *= pz; p3v.x *= pz; p3v.y *= pz; p3v.z *= pz; p3v.w *= pz;
;     p2g.x *= pz; p2g.y *= pz; p2g.z *= pz; p2g.w *= pz; p2v.x *= pz; p2v.y *= pz; p2v.z *= pz; p2v.w *= pz;
;     const float4 c0g = *reinterpret_cast<const float4*>(hc + f), c0v = *reinterpret_cast<const float4*>(hc + DFF + f);
;     float4 g1, v1, g2, v2;
;     if (rr == 0) { g1 = p3g; v1 = p3v; g2 = p2g; v2 = p2v; }
;     else { g1 = c0g; v1 = c0v; g2 = p3g; v2 = p3v; }
;     const float4 wg0 = *reinterpret_cast<const float4*>(cw + f), wg1 = *reinterpret_cast<const float4*>(cw + NUP + f), wg2 = *reinterpret_cast<const float4*>(cw + 2 * NUP + f);
;     const float4 wv0 = *reinterpret_cast<const float4*>(cw + DFF + f), wv1 = *reinterpret_cast<const float4*>(cw + NUP + DFF + f), wv2 = *reinterpret_cast<const float4*>(cw + 2 * NUP + DFF + f);
;     const float4 bg = *reinterpret_cast<const float4*>(cb + f), bv = *reinterpret_cast<const float4*>(cb + DFF + f);
;     const float a0 = siluf_(bg.x + wg0.x * g2.x + wg1.x * g1.x + wg2.x * gc.x) * (bv.x + wv0.x * v2.x + wv1.x * v1.x + wv2.x * vc.x);
;     const float a1 = siluf_(bg.y + wg0.y * g2.y + wg1.y * g1.y + wg2.y * gc.y) * (bv.y + wv0.y * v2.y + wv1.y * v1.y + wv2.y * vc.y);
;     const float a2 = siluf_(bg.z + wg0.z * g2.z + wg1.z * g1.z + wg2.z * gc.z) * (bv.z + wv0.z * v2.z + wv1.z * v1.z + wv2.z * vc.z);
;     const float a3 = siluf_(bg.w + wg0.w * g2.w + wg1.w * g1.w + wg2.w * gc.w) * (bv.w + wv0.w * v2.w + wv1.w * v1.w + wv2.w * vc.w);
.LBB0_39:
	s_or_b64 exec, exec, s[2:3]
	v_lshl_or_b32 v0, v38, 8, v39
	v_lshl_add_u64 v[20:21], s[8:9], 0, v[28:29]
	v_lshl_add_u64 v[38:39], s[12:13], 0, v[28:29]
	v_lshl_add_u64 v[42:43], s[14:15], 0, v[28:29]
	v_lshl_add_u64 v[46:47], s[16:17], 0, v[28:29]
	v_lshl_add_u64 v[50:51], s[20:21], 0, v[28:29]
	v_lshl_add_u64 v[54:55], s[22:23], 0, v[28:29]
	v_lshl_add_u64 v[58:59], s[10:11], 0, v[28:29]
	v_lshl_add_u64 v[28:29], s[24:25], 0, v[28:29]
	global_load_dwordx4 v[32:35], v[20:21], off
	s_nop 0
	global_load_dwordx4 v[38:41], v[38:39], off
	s_nop 0
	global_load_dwordx4 v[42:45], v[42:43], off
	s_nop 0
	global_load_dwordx4 v[46:49], v[46:47], off
	s_nop 0
	global_load_dwordx4 v[50:53], v[50:51], off
	s_nop 0
	global_load_dwordx4 v[54:57], v[54:55], off
	s_nop 0
	global_load_dwordx4 v[58:61], v[58:59], off
	s_nop 0
	global_load_dwordx4 v[62:65], v[28:29], off
	v_add_u32_e32 v36, s26, v36
	v_add_u32_e32 v37, s27, v37
	s_waitcnt vmcnt(1)
	v_pk_fma_f32 v[20:21], v[30:31], v[32:33], v[58:59]
	s_nop 0
	v_pk_fma_f32 v[14:15], v[14:15], v[38:39], v[20:21]
	s_nop 0
	v_pk_fma_f32 v[6:7], v[6:7], v[42:43], v[14:15]
	s_nop 0
	v_mul_f32_e32 v14, 0xbfb8aa3b, v6
	v_mul_f32_e32 v15, 0xbfb8aa3b, v7
	v_exp_f32_e32 v14, v14
	v_exp_f32_e32 v15, v15
	s_nop 0
	v_pk_add_f32 v[14:15], v[14:15], 1.0 op_sel_hi:[1,0]
	s_nop 0
	s_nop 0
	v_rcp_f32_e32 v20, v15
	s_nop 0
	v_mul_f32_e32 v7, v7, v20
	s_nop 0
	v_rcp_f32_e32 v15, v14
	s_nop 0
	v_mul_f32_e32 v6, v6, v15
	s_waitcnt vmcnt(0)
	v_pk_fma_f32 v[14:15], v[24:25], v[46:47], v[62:63]
	s_nop 0
	v_pk_fma_f32 v[10:11], v[10:11], v[50:51], v[14:15]
	s_nop 0
	v_pk_fma_f32 v[2:3], v[2:3], v[54:55], v[10:11]
	s_nop 0
	v_pk_mul_f32 v[2:3], v[6:7], v[2:3]
	v_pk_fma_f32 v[6:7], v[22:23], v[34:35], v[60:61]
	v_cvt_pk_bf16_f32 v2, v2, v3
	v_pk_fma_f32 v[6:7], v[16:17], v[40:41], v[6:7]
	s_nop 0
	v_pk_fma_f32 v[6:7], v[8:9], v[44:45], v[6:7]
	s_nop 0
	v_mul_f32_e32 v8, 0xbfb8aa3b, v6
	v_mul_f32_e32 v9, 0xbfb8aa3b, v7
	v_exp_f32_e32 v8, v8
	v_exp_f32_e32 v9, v9
	s_nop 0
	v_pk_add_f32 v[8:9], v[8:9], 1.0 op_sel_hi:[1,0]
	s_nop 0
	s_nop 0
	v_rcp_f32_e32 v10, v9
	s_nop 0
	v_mul_f32_e32 v7, v7, v10
	v_readlane_b32 s0, v252, 22
	v_readlane_b32 s1, v252, 23
	v_rcp_f32_e32 v9, v8
	s_nop 0
	v_mul_f32_e32 v6, v6, v9
	v_pk_fma_f32 v[8:9], v[18:19], v[48:49], v[64:65]
	s_nop 0
	v_pk_fma_f32 v[8:9], v[12:13], v[52:53], v[8:9]
	s_nop 0
	v_pk_fma_f32 v[4:5], v[4:5], v[56:57], v[8:9]
	s_nop 0
	v_pk_mul_f32 v[4:5], v[6:7], v[4:5]
	s_nop 0
	v_cvt_pk_bf16_f32 v3, v4, v5
	v_mov_b64_e32 v[4:5], s[0:1]
	s_movk_i32 s0, 0x2c00
	v_mad_i64_i32 v[4:5], s[0:1], v0, s0, v[4:5]
	s_mov_b32 s0, 0x15fff
	s_nop 0
	v_cmp_lt_i32_e32 vcc, s0, v36
	v_lshl_add_u64 v[4:5], v[26:27], 1, v[4:5]
	s_or_b64 s[28:29], vcc, s[28:29]
	global_store_dwordx2 v[4:5], v[2:3], off
	s_andn2_b64 exec, exec, s[28:29]
	s_cbranch_execz .LBB0_44

; DI void wconv_task(const P& p, int layer, int t, float* ldsf) {
;   char* ws = p.ws;
;     char* wl = ws + OFF_W + (size_t)layer * W_LAYER;
;     const float* src; int K, N, Np; bf16_t* dst; int tt;
;     if (t < 896) { tt = t; src = p.w_in + (size_t)layer * 2048 * NIN; K = 2048; N = NIN; Np = NPJ; dst = (bf16_t*)(wl + W_IN); }
;     else if (t < 1152) { tt = t - 896; src = p.w_out + (size_t)layer * 2048 * 2048; K = 2048; N = 2048; Np = 2048; dst = (bf16_t*)(wl + W_OUT); }
;     else if (t < 1216) { tt = t - 1152; src = p.wq + (size_t)layer * 2048 * 512; K = 2048; N = 512; Np = 512; dst = (bf16_t*)(wl + W_Q); }
;     else if (t < 1280) { tt = t - 1216; src = p.wk + (size_t)layer * 2048 * 512; K = 2048; N = 512; Np = 512; dst = (bf16_t*)(wl + W_K); }
;     else if (t < 1344) { tt = t - 1280; src = p.wv + (size_t)layer * 2048 * 512; K = 2048; N = 512; Np = 512; dst = (bf16_t*)(wl + W_V); }
;     else if (t < 1408) { tt = t - 1344; src = p.wo + (size_t)layer * 512 * 2048; K = 512; N = 2048; Np = 2048; dst = (bf16_t*)(wl + W_O); }
;     else if (t < 2816) { tt = t - 1408; src = p.w_up + (size_t)layer * 2048 * NUP; K = 2048; N = NUP; Np = NUP; dst = (bf16_t*)(wl + W_UP); }
;     else if (t < 3520) { tt = t - 2816; src = p.w_down + (size_t)layer * DFF * 2048; K = DFF; N = 2048; Np = 2048; dst = (bf16_t*)(wl + W_DN); }
;     else if (t < 3584) { tt = t - 3520; src = p.w_ck + (size_t)layer * 4096 * 128; K = 4096; N = 128; Np = 128; dst = (bf16_t*)(wl + W_CK); }
;     else { tt = t - 3584; src = p.w_cv + (size_t)layer * 4096 * 128; K = 4096; N = 128; Np = 128; dst = (bf16_t*)(wl + W_CV); }
;     int nk = K / 64;
;     tconv_tile(src, K, N, Np, dst, tt % nk, tt / nk, ldsf);
; DI void phase_l6(const P& p, int layer, float* ldsf) {
;     ...
;   if (layer + 1 < NL) {
;     unsigned* cnt = (unsigned*)(p.ws + OFF_BAR) + 1 + layer;
;     int* tk = (int*)ldsf + 20000;
;     while (true) {
;       if (tid_ == 0) *tk = (int)atomicAdd(cnt, 1u);
;       __syncthreads();
;       const int t = *tk;
;       __syncthreads();
;       if (t >= 3648) break;
;       wconv_task(p, layer + 1, t, ldsf);
;     }
.LBB0_217:
	s_cmp_gt_i32 s44, 33
	s_cbranch_scc1 .LBB0_286
	v_readlane_b32 s0, v255, 1
	v_readlane_b32 s1, v255, 2
	s_add_i32 s2, s0, 1
	v_readlane_b32 s0, v252, 55
	s_add_u32 s0, s0, s18
	v_readlane_b32 s1, v252, 56
	s_addc_u32 s1, s1, s19
	s_ashr_i32 s3, s2, 31
	s_mul_i32 s6, s2, 0x7000000
	s_lshl_b64 s[12:13], s[2:3], 21
	s_lshl_b64 s[40:41], s[2:3], 22
	s_lshl_b64 s[54:55], s[2:3], 24
	v_readlane_b32 s3, v252, 20
	s_mul_hi_i32 s7, s2, 0x7000000
	s_add_u32 s6, s3, s6
	v_readlane_b32 s3, v252, 21
	v_readlane_b32 s16, v253, 61
	s_addc_u32 s7, s3, s7
	v_readlane_b32 s22, v254, 3
	v_readlane_b32 s23, v254, 4
	s_add_u32 s14, s22, s12
	s_addc_u32 s15, s23, s13
	v_writelane_b32 v255, s14, 13
	v_readlane_b32 s20, v254, 1
	v_readlane_b32 s21, v254, 2
	v_writelane_b32 v255, s15, 14
	s_add_u32 s14, s6, 0x6f00000
	s_addc_u32 s15, s7, 0
	v_writelane_b32 v255, s14, 7
	s_add_u32 s12, s20, s12
	s_addc_u32 s13, s21, s13
	v_writelane_b32 v255, s15, 8
	v_writelane_b32 v255, s12, 19
	v_readlane_b32 s56, v254, 13
	s_mul_i32 s9, s2, 0x2c00000
	v_writelane_b32 v255, s13, 20
	s_add_u32 s12, s6, 0x6e00000
	s_addc_u32 s13, s7, 0
	v_writelane_b32 v255, s12, 21
	v_readlane_b32 s70, v254, 27
	s_mul_hi_i32 s8, s2, 0x2c00000
	v_writelane_b32 v255, s13, 22
	v_readlane_b32 s71, v254, 28
	s_add_u32 s12, s70, s9
	s_addc_u32 s13, s71, s8
	v_writelane_b32 v255, s12, 23
	s_add_u32 s8, s6, 0x5800000
	s_addc_u32 s9, s7, 0
	v_writelane_b32 v255, s13, 24
	s_mul_i32 s11, s2, 0x5800000
	v_readlane_b32 s64, v254, 21
	v_writelane_b32 v255, s8, 25
	s_mul_hi_i32 s10, s2, 0x5800000
	v_readlane_b32 s65, v254, 22
	v_writelane_b32 v255, s9, 26
	s_add_u32 s8, s64, s11
	v_readlane_b32 s26, v254, 7
	s_addc_u32 s9, s65, s10
	v_readlane_b32 s27, v254, 8
	s_add_u32 s26, s6, 0x2c00000
	v_readlane_b32 s28, v254, 9
	v_readlane_b32 s60, v254, 17
	s_addc_u32 s27, s7, 0
	v_readlane_b32 s29, v254, 10
	v_readlane_b32 s61, v254, 18
	s_add_u32 s28, s60, s40
	s_addc_u32 s29, s61, s41
	s_add_u32 s70, s6, 0x2a00000
	v_readlane_b32 s58, v254, 15
	v_writelane_b32 v255, s8, 15
	s_addc_u32 s71, s7, 0
	v_readlane_b32 s59, v254, 16
	v_writelane_b32 v255, s9, 16
	s_add_u32 s8, s58, s40
	s_addc_u32 s9, s59, s41
	s_add_u32 s34, s6, 0x2800000
	s_addc_u32 s35, s7, 0
	v_readlane_b32 s57, v254, 14
	s_add_u32 s42, s56, s40
	s_addc_u32 s43, s57, s41
	s_add_u32 s48, s6, 0x2600000
	v_readlane_b32 s30, v254, 11
	s_addc_u32 s49, s7, 0
	v_readlane_b32 s31, v254, 12
	s_add_u32 s50, s30, s40
	s_addc_u32 s51, s31, s41
	s_add_u32 s52, s6, 0x2400000
	v_readlane_b32 s24, v254, 5
	s_addc_u32 s53, s7, 0
	v_readlane_b32 s25, v254, 6
	s_add_u32 s54, s24, s54
	v_readlane_b32 s17, v253, 62
	v_readlane_b32 s18, v253, 63
	v_readlane_b32 s19, v254, 0
	v_writelane_b32 v255, s8, 11
	s_addc_u32 s55, s25, s55
	s_add_u32 s56, s6, 0x1c00000
	v_writelane_b32 v255, s9, 12
	v_readlane_b32 s8, v253, 45
	s_mul_hi_i32 s3, s2, 0x3618000
	s_mul_i32 s2, s2, 0x3618000
	s_addc_u32 s57, s7, 0
	v_readlane_b32 s16, v253, 53
	v_readlane_b32 s17, v253, 54
	s_add_u32 s58, s16, s2
	s_addc_u32 s59, s17, s3
	v_readlane_b32 s62, v254, 19
	v_readlane_b32 s63, v254, 20
	v_readlane_b32 s66, v254, 23
	v_readlane_b32 s67, v254, 24
	v_readlane_b32 s68, v254, 25
	v_readlane_b32 s69, v254, 26
	v_readlane_b32 s9, v253, 46
	v_readlane_b32 s10, v253, 47
	v_readlane_b32 s11, v253, 48
	v_readlane_b32 s12, v253, 49
	v_readlane_b32 s13, v253, 50
	v_readlane_b32 s14, v253, 51
	v_readlane_b32 s15, v253, 52
	v_readlane_b32 s18, v253, 55
	v_readlane_b32 s19, v253, 56
	v_readlane_b32 s20, v253, 57
	v_readlane_b32 s21, v253, 58
	v_readlane_b32 s22, v253, 59
	v_readlane_b32 s23, v253, 60
	s_and_saveexec_b64 s[2:3], s[4:5]
	s_cbranch_execz .Ltk_pre_done
	v_mov_b32_e32 v249, 1
	global_atomic_add v249, v1, v249, s[0:1] sc0
.Ltk_pre_done:
	s_or_b64 exec, exec, s[2:3]
	s_branch .LBB0_221

; DI void phase_l6(const P& p, int layer, float* ldsf) {
;     ...
;     int* tk = (int*)ldsf + 20000;
;     while (true) {
;       if (tid_ == 0) *tk = (int)atomicAdd(cnt, 1u);
;       __syncthreads();
;       const int t = *tk;
;       __syncthreads();
;       if (t >= 3648) break;
;       wconv_task(p, layer + 1, t, ldsf);
.LBB0_221:
	s_and_saveexec_b64 s[2:3], s[4:5]
	s_cbranch_execz .LBB0_225
	s_mov_b64 s[60:61], exec
	v_mbcnt_lo_u32_b32 v0, s60, 0
	v_mbcnt_hi_u32_b32 v0, s61, v0
	v_cmp_eq_u32_e32 vcc, 0, v0
	s_and_saveexec_b64 s[40:41], vcc
	s_cbranch_execz .LBB0_224
	s_bcnt1_i32_b64 s36, s[60:61]
	s_waitcnt vmcnt(0)
	v_mov_b32_e32 v2, v249
	v_mov_b32_e32 v249, s36
	global_atomic_add v249, v1, v249, s[0:1] sc0
.LBB0_224:
	s_or_b64 exec, exec, s[40:41]
	v_readfirstlane_b32 s36, v2
	s_nop 1
	v_add_u32_e32 v0, s36, v0
	v_readlane_b32 s36, v253, 35
	s_nop 1
	v_mov_b32_e32 v2, s36
	ds_write_b32 v2, v0

; DI void phase_prep(const P& p, int layer, float* ldsf) {
;     ...
;   for (int c = bid_; c < 256; c += gridDim.x) {
;     const int t0 = c * 32;
;     for (int idx = tid; idx < 2048; idx += 512) {
;       int n = idx >> 6, i = idx & 63;
;       float inv = exp2f(-(float)i * (13.287712379549449f / 64.f));
;       double ang = (double)p.pos[t0 + n] * (double)inv;
;       double kq = rint(ang * 0.15915494309189535);
;       float rr = (float)(ang - kq * 6.283185307179586);
;       cosT[idx] = __cosf(rr); sinT[idx] = __sinf(rr);
;     }
.LBB0_286:
	s_waitcnt vmcnt(0)
	v_readlane_b32 s30, v254, 31
	v_readlane_b32 s64, v254, 35
	s_mov_b32 s50, 0x6dc9c883
	s_mov_b32 s52, 0x54442d18
	v_readlane_b32 s60, v255, 17
	v_readlane_b32 s62, v255, 9
	s_mov_b64 s[0:1], 0
	v_readlane_b32 s31, v254, 32
	v_readlane_b32 s65, v254, 36
	s_mov_b32 s51, 0x3fc45f30
	s_mov_b32 s53, 0xc01921fb
	s_mov_b64 s[54:55], 0x4000
	v_readlane_b32 s61, v255, 18
	v_readlane_b32 s63, v255, 10

; DI float bf2f(bf16_t b) { return __uint_as_float(((unsigned)b) << 16); }
; DI float sigmoidf_(float x) { return 1.f / (1.f + __expf(-x)); }
; DI void phase_prep(const P& p, int layer, float* ldsf) {
;     ...
;       for (int n16 = 0; n16 < 2; ++n16) {
;         bf16_t f_[16];
; #pragma unroll
;         for (int j = 0; j < 16; ++j) f_[j] = proj[(long)(t0 + n16 * 16 + j) * NPJ + 4096 + tid];
; #pragma unroll
;         for (int j = 0; j < 16; ++j) { float f = lbv + (1.f - lbv) * sigmoidf_(bf2f(f_[j])); G31 += __logf(fmaxf(f, 1e-6f)); }
;       }
.LBB0_358:
	s_or_b32 s0, s2, s14
	s_mul_i32 s3, s0, 0x3800
	s_mul_hi_i32 s1, s0, 0x3800
	s_add_u32 s4, s92, s3
	s_addc_u32 s5, s93, s1
	s_or_b32 s1, s0, 1
	s_mul_hi_i32 s3, s1, 0x3800
	s_mulk_i32 s1, 0x3800
	v_lshl_add_u64 v[8:9], s[4:5], 0, v[88:89]
	s_add_u32 s4, s92, s1
	v_add_co_u32_e32 v8, vcc, s39, v8
	s_addc_u32 s5, s93, s3
	s_nop 0
	v_addc_co_u32_e32 v9, vcc, 0, v9, vcc
	s_or_b32 s1, s0, 2
	global_load_ushort v5, v[8:9], off
	v_lshl_add_u64 v[8:9], s[4:5], 0, v[88:89]
	s_mul_hi_i32 s3, s1, 0x3800
	s_mulk_i32 s1, 0x3800
	v_add_co_u32_e32 v8, vcc, s39, v8
	s_add_u32 s4, s92, s1
	s_nop 0
	v_addc_co_u32_e32 v9, vcc, 0, v9, vcc
	s_addc_u32 s5, s93, s3
	s_or_b32 s1, s0, 3
	global_load_ushort v7, v[8:9], off
	s_mul_hi_i32 s3, s1, 0x3800
	s_mulk_i32 s1, 0x3800
	v_lshl_add_u64 v[8:9], s[4:5], 0, v[88:89]
	s_add_u32 s4, s92, s1
	v_add_co_u32_e32 v8, vcc, s39, v8
	s_addc_u32 s5, s93, s3
	s_nop 0
	v_addc_co_u32_e32 v9, vcc, 0, v9, vcc
	s_or_b32 s1, s0, 4
	global_load_ushort v10, v[8:9], off
	s_mul_hi_i32 s3, s1, 0x3800
	s_mulk_i32 s1, 0x3800
	v_lshl_add_u64 v[8:9], s[4:5], 0, v[88:89]
	s_add_u32 s4, s92, s1
	v_add_co_u32_e32 v8, vcc, s39, v8
	s_addc_u32 s5, s93, s3
	s_nop 0
	v_addc_co_u32_e32 v9, vcc, 0, v9, vcc
	s_or_b32 s1, s0, 5
	global_load_ushort v11, v[8:9], off
	s_mul_hi_i32 s3, s1, 0x3800
	s_mulk_i32 s1, 0x3800
	v_lshl_add_u64 v[8:9], s[4:5], 0, v[88:89]
	s_add_u32 s4, s92, s1
	v_add_co_u32_e32 v8, vcc, s39, v8
	s_addc_u32 s5, s93, s3
	s_nop 0
	v_addc_co_u32_e32 v9, vcc, 0, v9, vcc
	s_or_b32 s1, s0, 6
	global_load_ushort v12, v[8:9], off
	s_mul_hi_i32 s3, s1, 0x3800
	s_mulk_i32 s1, 0x3800
	v_lshl_add_u64 v[8:9], s[4:5], 0, v[88:89]
	s_add_u32 s4, s92, s1
	v_add_co_u32_e32 v8, vcc, s39, v8
	s_addc_u32 s5, s93, s3
	s_nop 0
	v_addc_co_u32_e32 v9, vcc, 0, v9, vcc
	s_or_b32 s1, s0, 7
	global_load_ushort v13, v[8:9], off
	v_lshl_add_u64 v[8:9], s[4:5], 0, v[88:89]
	s_mul_hi_i32 s3, s1, 0x3800
	s_mulk_i32 s1, 0x3800
	v_add_co_u32_e32 v8, vcc, s39, v8
	s_add_u32 s4, s92, s1
	s_nop 0
	v_addc_co_u32_e32 v9, vcc, 0, v9, vcc
	s_addc_u32 s5, s93, s3
	s_or_b32 s1, s0, 8
	global_load_ushort v14, v[8:9], off
	s_mul_hi_i32 s3, s1, 0x3800
	s_mulk_i32 s1, 0x3800
	v_lshl_add_u64 v[8:9], s[4:5], 0, v[88:89]
	s_add_u32 s4, s92, s1
	v_add_co_u32_e32 v8, vcc, s39, v8
	s_addc_u32 s5, s93, s3
	s_nop 0
	v_addc_co_u32_e32 v9, vcc, 0, v9, vcc
	s_or_b32 s1, s0, 9
	global_load_ushort v15, v[8:9], off
	v_lshl_add_u64 v[8:9], s[4:5], 0, v[88:89]
	s_mul_hi_i32 s3, s1, 0x3800
	s_mulk_i32 s1, 0x3800
	v_add_co_u32_e32 v8, vcc, s39, v8
	s_add_u32 s4, s92, s1
	s_nop 0
	v_addc_co_u32_e32 v9, vcc, 0, v9, vcc
	s_addc_u32 s5, s93, s3
	s_or_b32 s1, s0, 10
	global_load_ushort v16, v[8:9], off
	s_mul_hi_i32 s3, s1, 0x3800
	s_mulk_i32 s1, 0x3800
	v_lshl_add_u64 v[8:9], s[4:5], 0, v[88:89]
	s_add_u32 s4, s92, s1
	v_add_co_u32_e32 v8, vcc, s39, v8
	s_addc_u32 s5, s93, s3
	s_nop 0
	v_addc_co_u32_e32 v9, vcc, 0, v9, vcc
	s_or_b32 s1, s0, 11
	global_load_ushort v17, v[8:9], off
	s_mul_hi_i32 s3, s1, 0x3800
	s_mulk_i32 s1, 0x3800
	v_lshl_add_u64 v[8:9], s[4:5], 0, v[88:89]
	s_add_u32 s4, s92, s1
	v_add_co_u32_e32 v8, vcc, s39, v8
	s_addc_u32 s5, s93, s3
	s_nop 0
	v_addc_co_u32_e32 v9, vcc, 0, v9, vcc
	s_or_b32 s1, s0, 12
	global_load_ushort v18, v[8:9], off
	v_lshl_add_u64 v[8:9], s[4:5], 0, v[88:89]
	s_mul_hi_i32 s3, s1, 0x3800
	s_mulk_i32 s1, 0x3800
	v_add_co_u32_e32 v8, vcc, s39, v8
	s_add_u32 s4, s92, s1
	s_nop 0
	v_addc_co_u32_e32 v9, vcc, 0, v9, vcc
	s_addc_u32 s5, s93, s3
	s_or_b32 s1, s0, 13
	global_load_ushort v19, v[8:9], off
	s_mul_hi_i32 s3, s1, 0x3800
	s_mulk_i32 s1, 0x3800
	v_lshl_add_u64 v[8:9], s[4:5], 0, v[88:89]
	s_add_u32 s4, s92, s1
	v_add_co_u32_e32 v8, vcc, s39, v8
	s_addc_u32 s5, s93, s3
	s_nop 0
	v_addc_co_u32_e32 v9, vcc, 0, v9, vcc
	s_or_b32 s1, s0, 14
	global_load_ushort v20, v[8:9], off
	v_lshl_add_u64 v[8:9], s[4:5], 0, v[88:89]
	s_mul_hi_i32 s3, s1, 0x3800
	s_mulk_i32 s1, 0x3800
	v_add_co_u32_e32 v8, vcc, s39, v8
	s_add_u32 s4, s92, s1
	s_nop 0
	v_addc_co_u32_e32 v9, vcc, 0, v9, vcc
	s_addc_u32 s5, s93, s3
	s_or_b32 s0, s0, 15
	global_load_ushort v21, v[8:9], off
	s_mul_hi_i32 s1, s0, 0x3800
	s_mulk_i32 s0, 0x3800
	v_lshl_add_u64 v[8:9], s[4:5], 0, v[88:89]
	s_add_u32 s0, s92, s0
	v_add_co_u32_e32 v8, vcc, s39, v8
	s_addc_u32 s1, s93, s1
	s_nop 0
	v_addc_co_u32_e32 v9, vcc, 0, v9, vcc
	global_load_ushort v22, v[8:9], off
	v_lshl_add_u64 v[8:9], s[0:1], 0, v[88:89]
	v_add_co_u32_e32 v8, vcc, s39, v8
	v_cndmask_b32_e64 v3, 0, 1, s[48:49]
	s_nop 0
	v_addc_co_u32_e32 v9, vcc, 0, v9, vcc
	v_cmp_ne_u32_e64 s[18:19], 1, v3
	global_load_ushort v3, v[8:9], off
	s_waitcnt vmcnt(15)
	v_lshlrev_b32_e32 v5, 16, v5
	v_mul_f32_e32 v5, 0xbfb8aa3b, v5
	v_exp_f32_e32 v5, v5
	s_waitcnt vmcnt(14)
	v_lshlrev_b32_e32 v7, 16, v7
	v_mul_f32_e32 v7, 0xbfb8aa3b, v7
	v_exp_f32_e32 v7, v7
	v_add_f32_e32 v5, 1.0, v5
	s_waitcnt vmcnt(13)
	v_lshlrev_b32_e32 v8, 16, v10
	v_mul_f32_e32 v8, 0xbfb8aa3b, v8
	v_exp_f32_e32 v8, v8
	v_add_f32_e32 v7, 1.0, v7
	s_waitcnt vmcnt(12)
	v_lshlrev_b32_e32 v11, 16, v11
	v_mul_f32_e32 v11, 0xbfb8aa3b, v11
	v_exp_f32_e32 v11, v11
	v_add_f32_e32 v8, 1.0, v8
	s_waitcnt vmcnt(11)
	v_lshlrev_b32_e32 v12, 16, v12
	v_mul_f32_e32 v12, 0xbfb8aa3b, v12
	v_exp_f32_e32 v12, v12
	v_add_f32_e32 v11, 1.0, v11
	s_waitcnt vmcnt(10)
	v_lshlrev_b32_e32 v13, 16, v13
	v_mul_f32_e32 v13, 0xbfb8aa3b, v13
	v_exp_f32_e32 v13, v13
	v_add_f32_e32 v12, 1.0, v12
	s_waitcnt vmcnt(9)
	v_lshlrev_b32_e32 v14, 16, v14
	v_rcp_f32_e32 v9, v5
	s_nop 0
	v_mul_f32_e32 v5, 1.0, v9
	v_mul_f32_e32 v14, 0xbfb8aa3b, v14
	v_fma_f32 v5, v6, v5, v4
	s_mov_b64 vcc, s[0:1]
	v_exp_f32_e32 v14, v14
	v_max_f32_e32 v5, 0x358637bd, v5
	v_add_f32_e32 v13, 1.0, v13
	v_cmp_gt_f32_e32 vcc, s33, v5
	v_rcp_f32_e32 v10, v7
	s_nop 0
	v_mul_f32_e32 v7, 1.0, v10
	s_waitcnt vmcnt(8)
; DI float bf2f(bf16_t b) { return __uint_as_float(((unsigned)b) << 16); }
; DI float sigmoidf_(float x) { return 1.f / (1.f + __expf(-x)); }
; DI void phase_prep(const P& p, int layer, float* ldsf) {
;     ...
;       for (int n16 = 0; n16 < 2; ++n16) {
;         bf16_t f_[16];
; #pragma unroll
;         for (int j = 0; j < 16; ++j) f_[j] = proj[(long)(t0 + n16 * 16 + j) * NPJ + 4096 + tid];
; #pragma unroll
;         for (int j = 0; j < 16; ++j) { float f = lbv + (1.f - lbv) * sigmoidf_(bf2f(f_[j])); G31 += __logf(fmaxf(f, 1e-6f)); }
;       }
	v_lshlrev_b32_e32 v15, 16, v15
	v_cndmask_b32_e64 v34, 0, 32, vcc
	v_fma_f32 v7, v6, v7, v4
	v_mul_f32_e32 v15, 0xbfb8aa3b, v15
	v_ldexp_f32 v5, v5, v34
	v_cndmask_b32_e32 v26, 0, v211, vcc
	v_max_f32_e32 v7, 0x358637bd, v7
	s_mov_b64 vcc, s[20:21]
	v_exp_f32_e32 v15, v15
	v_log_f32_e32 v5, v5
	v_add_f32_e32 v14, 1.0, v14
	v_cmp_gt_f32_e32 vcc, s33, v7
	s_waitcnt vmcnt(7)
	v_lshlrev_b32_e32 v16, 16, v16
	v_cndmask_b32_e64 v35, 0, 32, vcc
	v_rcp_f32_e32 v25, v8
	s_nop 0
	v_mul_f32_e32 v8, 1.0, v25
	v_mul_f32_e32 v16, 0xbfb8aa3b, v16
	v_ldexp_f32 v7, v7, v35
	v_cndmask_b32_e32 v30, 0, v211, vcc
	v_fma_f32 v8, v6, v8, v4
	s_mov_b64 vcc, s[22:23]
	v_exp_f32_e32 v16, v16
	v_max_f32_e32 v8, 0x358637bd, v8
	v_log_f32_e32 v7, v7
	v_add_f32_e32 v15, 1.0, v15
	v_mul_f32_e32 v36, 0x3f317217, v5
	v_cmp_gt_f32_e32 vcc, s33, v8
	v_rcp_f32_e32 v28, v11
	s_nop 0
	v_mul_f32_e32 v11, 1.0, v28
	s_waitcnt vmcnt(6)
	v_lshlrev_b32_e32 v17, 16, v17
	v_cndmask_b32_e64 v37, 0, 32, vcc
	v_fma_f32 v33, v5, s79, -v36
	v_cndmask_b32_e32 v36, 0, v211, vcc
	v_fma_f32 v11, v6, v11, v4
	s_mov_b64 vcc, s[26:27]
	v_mul_f32_e32 v17, 0xbfb8aa3b, v17
	v_ldexp_f32 v8, v8, v37
	v_fmac_f32_e32 v33, 0x3377d1cf, v5
	v_max_f32_e32 v11, 0x358637bd, v11
	v_exp_f32_e32 v17, v17
	v_log_f32_e32 v8, v8
	v_add_f32_e32 v16, 1.0, v16
	v_fmac_f32_e32 v33, 0x3f317217, v5
	v_cmp_gt_f32_e32 vcc, s33, v11
	v_rcp_f32_e32 v9, v12
	s_nop 0
	v_mul_f32_e32 v9, 1.0, v9
	v_cmp_lt_f32_e64 s[26:27], |v5|, s73
	s_waitcnt vmcnt(5)
	v_lshlrev_b32_e32 v18, 16, v18
	v_mul_f32_e32 v38, 0x3f317217, v7
	v_cndmask_b32_e64 v39, 0, 32, vcc
	v_cndmask_b32_e64 v5, v5, v33, s[26:27]
	v_cndmask_b32_e32 v33, 0, v211, vcc
	v_fma_f32 v9, v6, v9, v4
	s_mov_b64 vcc, s[0:1]
	v_mul_f32_e32 v18, 0xbfb8aa3b, v18
	v_fma_f32 v32, v7, s79, -v38
	v_ldexp_f32 v11, v11, v39
	v_max_f32_e32 v9, 0x358637bd, v9
	v_exp_f32_e32 v18, v18
	v_sub_f32_e32 v5, v5, v26
	v_fmac_f32_e32 v32, 0x3377d1cf, v7
	v_log_f32_e32 v11, v11
	v_cmp_gt_f32_e32 vcc, s33, v9
	v_rcp_f32_e32 v10, v13
	s_nop 0
	v_mul_f32_e32 v10, 1.0, v10
	v_add_f32_e32 v17, 1.0, v17
	s_waitcnt vmcnt(4)
	v_lshlrev_b32_e32 v19, 16, v19
	v_add_f32_e32 v0, v0, v5
	v_fmac_f32_e32 v32, 0x3f317217, v7
	v_mul_f32_e32 v5, 0x3f317217, v8
	v_cndmask_b32_e64 v34, 0, 32, vcc
	v_cmp_lt_f32_e64 s[26:27], |v7|, s73
	v_cndmask_b32_e32 v26, 0, v211, vcc
	v_fma_f32 v10, v6, v10, v4
	s_mov_b64 vcc, s[20:21]
	v_mul_f32_e32 v19, 0xbfb8aa3b, v19
	v_cndmask_b32_e64 v7, v7, v32, s[26:27]
	v_fma_f32 v5, v8, s79, -v5
	v_max_f32_e32 v10, 0x358637bd, v10
	v_ldexp_f32 v9, v9, v34
	v_exp_f32_e32 v19, v19
	v_sub_f32_e32 v7, v7, v30
	v_fmac_f32_e32 v5, 0x3377d1cf, v8
	v_cmp_gt_f32_e32 vcc, s33, v10
	v_rcp_f32_e32 v24, v14
	s_nop 0
	v_mul_f32_e32 v14, 1.0, v24
	v_log_f32_e32 v9, v9
	v_add_f32_e32 v18, 1.0, v18
	v_add_f32_e32 v0, v0, v7
	v_fmac_f32_e32 v5, 0x3f317217, v8
	v_mul_f32_e32 v7, 0x3f317217, v11
	v_cndmask_b32_e64 v34, 0, 32, vcc
	v_cmp_lt_f32_e64 s[26:27], |v8|, s73
	v_fma_f32 v14, v6, v14, v4
	s_waitcnt vmcnt(3)
	v_lshlrev_b32_e32 v20, 16, v20
	v_cndmask_b32_e64 v5, v8, v5, s[26:27]
	v_fma_f32 v7, v11, s79, -v7
	v_ldexp_f32 v8, v10, v34
	v_cndmask_b32_e32 v10, 0, v211, vcc
	v_max_f32_e32 v14, 0x358637bd, v14
	s_mov_b64 vcc, s[24:25]
	v_mul_f32_e32 v20, 0xbfb8aa3b, v20
	v_fmac_f32_e32 v7, 0x3377d1cf, v11
	v_cmp_gt_f32_e32 vcc, s33, v14
	v_exp_f32_e32 v20, v20
	v_sub_f32_e32 v5, v5, v36
	v_log_f32_e32 v8, v8
	v_add_f32_e32 v19, 1.0, v19
	v_fmac_f32_e32 v7, 0x3f317217, v11
	v_cndmask_b32_e64 v35, 0, 32, vcc
	v_rcp_f32_e32 v27, v15
	s_nop 0
	v_mul_f32_e32 v15, 1.0, v27
	v_cmp_lt_f32_e64 s[26:27], |v11|, s73
	s_waitcnt vmcnt(2)
	v_lshlrev_b32_e32 v21, 16, v21
	v_add_f32_e32 v0, v0, v5
	v_mul_f32_e32 v5, 0x3f317217, v9
	v_cndmask_b32_e64 v7, v11, v7, s[26:27]
	v_ldexp_f32 v11, v14, v35
	v_cndmask_b32_e32 v14, 0, v211, vcc
	v_fma_f32 v15, v6, v15, v4
	s_mov_b64 vcc, s[22:23]
	v_mul_f32_e32 v21, 0xbfb8aa3b, v21
	v_fma_f32 v5, v9, s79, -v5
	v_max_f32_e32 v15, 0x358637bd, v15
	v_exp_f32_e32 v21, v21
	v_sub_f32_e32 v7, v7, v33
	v_fmac_f32_e32 v5, 0x3377d1cf, v9
	v_log_f32_e32 v11, v11
	v_cmp_gt_f32_e32 vcc, s33, v15
	v_rcp_f32_e32 v12, v16
	s_nop 0
	v_mul_f32_e32 v12, 1.0, v12
	v_add_f32_e32 v20, 1.0, v20
	v_add_f32_e32 v0, v0, v7
	v_fmac_f32_e32 v5, 0x3f317217, v9
	v_mul_f32_e32 v7, 0x3f317217, v8
	v_cndmask_b32_e64 v35, 0, 32, vcc
	v_cmp_lt_f32_e64 s[26:27], |v9|, s73
	v_fma_f32 v12, v6, v12, v4
	s_waitcnt vmcnt(1)
	v_lshlrev_b32_e32 v22, 16, v22
	v_cndmask_b32_e64 v5, v9, v5, s[26:27]
	v_fma_f32 v7, v8, s79, -v7
	v_ldexp_f32 v9, v15, v35
	v_cndmask_b32_e32 v15, 0, v211, vcc
	v_max_f32_e32 v12, 0x358637bd, v12
	s_mov_b64 vcc, s[0:1]
	v_mul_f32_e32 v22, 0xbfb8aa3b, v22
	v_sub_f32_e32 v5, v5, v26
	v_fmac_f32_e32 v7, 0x3377d1cf, v8
	v_cmp_gt_f32_e32 vcc, s33, v12
	v_exp_f32_e32 v22, v22
	v_log_f32_e32 v9, v9
	v_add_f32_e32 v21, 1.0, v21
	v_add_f32_e32 v0, v0, v5
	v_fmac_f32_e32 v7, 0x3f317217, v8
	v_mul_f32_e32 v5, 0x3f317217, v11
	v_cndmask_b32_e64 v32, 0, 32, vcc
	v_rcp_f32_e32 v13, v17
	s_nop 0
	v_mul_f32_e32 v13, 1.0, v13
	v_cmp_lt_f32_e64 s[26:27], |v8|, s73
	s_waitcnt vmcnt(0)
; DI float bf2f(bf16_t b) { return __uint_as_float(((unsigned)b) << 16); }
; DI float sigmoidf_(float x) { return 1.f / (1.f + __expf(-x)); }
; DI void phase_prep(const P& p, int layer, float* ldsf) {
;     ...
;       for (int n16 = 0; n16 < 2; ++n16) {
;         bf16_t f_[16];
; #pragma unroll
;         for (int j = 0; j < 16; ++j) f_[j] = proj[(long)(t0 + n16 * 16 + j) * NPJ + 4096 + tid];
; #pragma unroll
;         for (int j = 0; j < 16; ++j) { float f = lbv + (1.f - lbv) * sigmoidf_(bf2f(f_[j])); G31 += __logf(fmaxf(f, 1e-6f)); }
;       }
	v_lshlrev_b32_e32 v3, 16, v3
	v_cndmask_b32_e64 v7, v8, v7, s[26:27]
	v_fma_f32 v5, v11, s79, -v5
	v_ldexp_f32 v8, v12, v32
	v_cndmask_b32_e32 v12, 0, v211, vcc
	v_fma_f32 v13, v6, v13, v4
	s_mov_b64 vcc, s[20:21]
	v_mul_f32_e32 v3, 0xbfb8aa3b, v3
	v_sub_f32_e32 v7, v7, v10
	v_fmac_f32_e32 v5, 0x3377d1cf, v11
	v_max_f32_e32 v10, 0x358637bd, v13
	v_exp_f32_e32 v3, v3
	v_log_f32_e32 v8, v8
	v_fmac_f32_e32 v5, 0x3f317217, v11
	v_cmp_gt_f32_e32 vcc, s33, v10
	v_rcp_f32_e32 v13, v18
	s_nop 0
	v_mul_f32_e32 v13, 1.0, v13
	v_cmp_lt_f32_e64 s[26:27], |v11|, s73
	v_add_f32_e32 v22, 1.0, v22
	v_add_f32_e32 v0, v0, v7
	v_mul_f32_e32 v7, 0x3f317217, v9
	v_cndmask_b32_e64 v31, 0, 32, vcc
	v_cndmask_b32_e64 v5, v11, v5, s[26:27]
	v_cndmask_b32_e32 v11, 0, v211, vcc
	v_fma_f32 v13, v6, v13, v4
	s_mov_b64 vcc, s[24:25]
	v_fma_f32 v7, v9, s79, -v7
	v_ldexp_f32 v10, v10, v31
	v_sub_f32_e32 v5, v5, v14
	v_max_f32_e32 v13, 0x358637bd, v13
	v_fmac_f32_e32 v7, 0x3377d1cf, v9
	v_log_f32_e32 v10, v10
	v_cmp_gt_f32_e32 vcc, s33, v13
	v_rcp_f32_e32 v14, v19
	s_nop 0
	v_mul_f32_e32 v14, 1.0, v14
	v_add_f32_e32 v3, 1.0, v3
	v_add_f32_e32 v0, v0, v5
	v_fmac_f32_e32 v7, 0x3f317217, v9
	v_mul_f32_e32 v5, 0x3f317217, v8
	v_cndmask_b32_e64 v31, 0, 32, vcc
	v_cmp_lt_f32_e64 s[26:27], |v9|, s73
	v_fma_f32 v14, v6, v14, v4
	s_nop 3
	v_cndmask_b32_e64 v7, v9, v7, s[26:27]
	v_fma_f32 v5, v8, s79, -v5
	v_ldexp_f32 v9, v13, v31
	v_cndmask_b32_e32 v13, 0, v211, vcc
	v_max_f32_e32 v14, 0x358637bd, v14
	s_mov_b64 vcc, s[22:23]
	v_sub_f32_e32 v7, v7, v15
	v_fmac_f32_e32 v5, 0x3377d1cf, v8
	v_cmp_gt_f32_e32 vcc, s33, v14
	v_log_f32_e32 v9, v9
	v_add_f32_e32 v0, v0, v7
	v_fmac_f32_e32 v5, 0x3f317217, v8
	v_mul_f32_e32 v7, 0x3f317217, v10
	v_cndmask_b32_e64 v31, 0, 32, vcc
	v_rcp_f32_e32 v15, v20
	s_nop 0
	v_mul_f32_e32 v15, 1.0, v15
	v_cmp_lt_f32_e64 s[22:23], |v8|, s73
	s_nop 3
	v_cndmask_b32_e64 v5, v8, v5, s[22:23]
	v_fma_f32 v7, v10, s79, -v7
	v_ldexp_f32 v8, v14, v31
	v_cndmask_b32_e32 v14, 0, v211, vcc
	v_fma_f32 v15, v6, v15, v4
	s_mov_b64 vcc, s[0:1]
	v_sub_f32_e32 v5, v5, v12
	v_fmac_f32_e32 v7, 0x3377d1cf, v10
	v_max_f32_e32 v12, 0x358637bd, v15
	v_fmac_f32_e32 v7, 0x3f317217, v10
	v_cmp_gt_f32_e32 vcc, s33, v12
	v_rcp_f32_e32 v15, v21
	s_nop 0
	v_mul_f32_e32 v15, 1.0, v15
	v_cmp_lt_f32_e64 s[0:1], |v10|, s73
	v_log_f32_e32 v8, v8
	v_add_f32_e32 v0, v0, v5
	v_mul_f32_e32 v5, 0x3f317217, v9
	v_cndmask_b32_e64 v25, 0, 32, vcc
	v_cndmask_b32_e64 v7, v10, v7, s[0:1]
	v_fma_f32 v15, v6, v15, v4
	v_fma_f32 v5, v9, s79, -v5
	v_ldexp_f32 v10, v12, v25
	v_cndmask_b32_e32 v12, 0, v211, vcc
	v_sub_f32_e32 v7, v7, v11
	v_max_f32_e32 v11, 0x358637bd, v15
	s_mov_b64 vcc, s[20:21]
	v_fmac_f32_e32 v5, 0x3377d1cf, v9
	v_cmp_gt_f32_e32 vcc, s33, v11
	v_fmac_f32_e32 v5, 0x3f317217, v9
	v_rcp_f32_e32 v15, v22
	s_nop 0
	v_mul_f32_e32 v15, 1.0, v15
	v_cndmask_b32_e64 v17, 0, 32, vcc
	v_cmp_lt_f32_e64 s[0:1], |v9|, s73
	v_add_f32_e32 v0, v0, v7
	v_mul_f32_e32 v7, 0x3f317217, v8
	v_cndmask_b32_e64 v5, v9, v5, s[0:1]
	v_ldexp_f32 v9, v11, v17
	v_cndmask_b32_e32 v11, 0, v211, vcc
	v_fma_f32 v15, v6, v15, v4
	s_mov_b64 vcc, s[24:25]
	v_log_f32_e32 v10, v10
	v_fma_f32 v7, v8, s79, -v7
	v_sub_f32_e32 v5, v5, v13
	v_max_f32_e32 v13, 0x358637bd, v15
	v_fmac_f32_e32 v7, 0x3377d1cf, v8
	v_log_f32_e32 v9, v9
	v_rcp_f32_e32 v15, v3
	s_nop 0
	v_mul_f32_e32 v3, 1.0, v15
	s_and_b64 vcc, exec, s[18:19]
	v_fmac_f32_e32 v7, 0x3f317217, v8
	v_cmp_gt_f32_e64 s[0:1], s33, v13
	v_cmp_lt_f32_e64 s[18:19], |v8|, s73
	v_fma_f32 v3, v6, v3, v4
	v_cndmask_b32_e64 v16, 0, 32, s[0:1]
	v_cndmask_b32_e64 v7, v8, v7, s[18:19]
	v_max_f32_e32 v3, 0x358637bd, v3
	v_add_f32_e32 v0, v0, v5
	v_mul_f32_e32 v5, 0x3f317217, v10
	v_ldexp_f32 v8, v13, v16
	v_cndmask_b32_e64 v13, 0, v211, s[0:1]
	v_sub_f32_e32 v7, v7, v14
	v_cmp_gt_f32_e64 s[0:1], s33, v3
	v_fma_f32 v5, v10, s79, -v5
	v_add_f32_e32 v0, v0, v7
	v_mul_f32_e32 v7, 0x3f317217, v9
	v_cndmask_b32_e64 v14, 0, 32, s[0:1]
	v_fmac_f32_e32 v5, 0x3377d1cf, v10
	v_log_f32_e32 v8, v8
	v_fma_f32 v7, v9, s79, -v7
	v_ldexp_f32 v3, v3, v14
	v_fmac_f32_e32 v5, 0x3f317217, v10
	v_cmp_lt_f32_e64 s[18:19], |v10|, s73
	v_fmac_f32_e32 v7, 0x3377d1cf, v9
	v_log_f32_e32 v3, v3
	v_cndmask_b32_e64 v5, v10, v5, s[18:19]
	v_cndmask_b32_e64 v10, 0, v211, s[0:1]
	v_fmac_f32_e32 v7, 0x3f317217, v9
	v_cmp_lt_f32_e64 s[0:1], |v9|, s73
	v_sub_f32_e32 v5, v5, v12
	v_add_f32_e32 v0, v0, v5
	v_cndmask_b32_e64 v7, v9, v7, s[0:1]
	v_mul_f32_e32 v5, 0x3f317217, v8
	v_sub_f32_e32 v7, v7, v11
	v_fma_f32 v5, v8, s79, -v5
	v_add_f32_e32 v0, v0, v7
	v_mul_f32_e32 v7, 0x3f317217, v3
	v_fmac_f32_e32 v5, 0x3377d1cf, v8
	v_fma_f32 v7, v3, s79, -v7
	v_fmac_f32_e32 v5, 0x3f317217, v8
	v_cmp_lt_f32_e64 s[0:1], |v8|, s73
	v_fmac_f32_e32 v7, 0x3377d1cf, v3
	v_fmac_f32_e32 v7, 0x3f317217, v3
	v_cndmask_b32_e64 v5, v8, v5, s[0:1]
	v_cmp_lt_f32_e64 s[0:1], |v3|, s73
	v_sub_f32_e32 v5, v5, v13
	v_add_f32_e32 v0, v0, v5
	v_cndmask_b32_e64 v3, v3, v7, s[0:1]
	v_sub_f32_e32 v3, v3, v10
	s_mov_b32 s2, 16
	s_mov_b64 s[48:49], 0
	v_add_f32_e32 v0, v0, v3
	s_cbranch_vccz .LBB0_358
; DI bf16_t f2bf(float x) { unsigned u = __float_as_uint(x); u += 0x7fffu + ((u >> 16) & 1u); return (bf16_t)(u >> 16); }
; DI float bf2f(bf16_t b) { return __uint_as_float(((unsigned)b) << 16); }
; DI float sigmoidf_(float x) { return 1.f / (1.f + __expf(-x)); }
; DI void phase_prep(const P& p, int layer, float* ldsf) {
;     ...
;       for (int n8 = 0; n8 < 4; ++n8) {
;         float kq8[8];
;         bf16_t fl_[8], gq_[8];
; #pragma unroll
;         for (int j = 0; j < 8; ++j) { const bf16_t* row = proj + (long)(t0 + n8 * 8 + j) * NPJ; fl_[j] = row[4096 + tid]; gq_[j] = row[3584 + tid]; }
; #pragma unroll
;         for (int j = 0; j < 8; ++j) {
;           const int n = n8 * 8 + j;
;           float fl = bf2f(fl_[j]);
;           float f = lbv + (1.f - lbv) * sigmoidf_(fl);
;           G += __logf(fmaxf(f, 1e-6f));
;           float kk = 1.f - f;
;           qp[(long)(t0 + n) * 1024 + 512 + tid] = f2bf(bf2f(gq_[j]) * SCALE * __expf(G));
;           kp[(long)(t0 + n) * 1024 + 512 + tid] = f2bf(kk * __expf(fminf(-G, 80.f)));
;           kq8[j] = kk * __expf(G31 - G);
	s_ashr_i32 s31, s30, 31
	v_mad_i64_i32 v[8:9], s[0:1], s30, v228, v[88:89]
	v_mad_i64_i32 v[10:11], s[0:1], s34, v228, v[88:89]
	v_mad_i64_i32 v[12:13], s[0:1], s40, v228, v[88:89]
	v_mad_i64_i32 v[14:15], s[0:1], s42, v228, v[88:89]
	v_mad_i64_i32 v[16:17], s[0:1], s80, v228, v[88:89]
	v_mad_i64_i32 v[18:19], s[0:1], s82, v228, v[88:89]
	v_mad_i64_i32 v[20:21], s[0:1], s16, v228, v[88:89]
	v_mad_i64_i32 v[22:23], s[0:1], s28, v228, v[88:89]
	s_ashr_i32 s35, s34, 31
	s_lshl_b64 s[0:1], s[30:31], 11
	s_ashr_i32 s41, s40, 31
	v_lshl_add_u64 v[26:27], v[88:89], 0, s[0:1]
	s_lshl_b64 s[0:1], s[34:35], 11
	s_ashr_i32 s43, s42, 31
	v_lshl_add_u64 v[28:29], v[88:89], 0, s[0:1]
	s_lshl_b64 s[0:1], s[40:41], 11
	s_ashr_i32 s81, s80, 31
	v_lshl_add_u64 v[30:31], v[88:89], 0, s[0:1]
	s_lshl_b64 s[0:1], s[42:43], 11
	s_ashr_i32 s83, s82, 31
	v_lshl_add_u64 v[32:33], v[88:89], 0, s[0:1]
	s_lshl_b64 s[0:1], s[80:81], 11
	s_ashr_i32 s17, s16, 31
	v_lshl_add_u64 v[34:35], v[88:89], 0, s[0:1]
	s_lshl_b64 s[0:1], s[82:83], 11
	s_ashr_i32 s29, s28, 31
	v_ashrrev_i32_e32 v159, 31, v158
	v_lshl_add_u64 v[36:37], v[88:89], 0, s[0:1]
	s_lshl_b64 s[0:1], s[16:17], 11
	v_lshlrev_b64 v[24:25], 13, v[158:159]
	v_lshl_add_u64 v[38:39], v[88:89], 0, s[0:1]
	s_lshl_b64 s[0:1], s[28:29], 11
	s_mul_hi_i32 s65, s30, 0x3800
	s_mul_i32 s64, s30, 0x3800
	s_mul_hi_i32 s21, s34, 0x3800
	s_mul_i32 s20, s34, 0x3800
	s_mul_hi_i32 s23, s40, 0x3800
	s_mul_i32 s22, s40, 0x3800
	s_mul_hi_i32 s25, s42, 0x3800
	s_mul_i32 s24, s42, 0x3800
	s_mul_hi_i32 s27, s80, 0x3800
	s_mul_i32 s26, s80, 0x3800
	s_mul_hi_i32 s49, s82, 0x3800
	s_mul_i32 s48, s82, 0x3800
	s_mul_hi_i32 s51, s16, 0x3800
	s_mul_i32 s50, s16, 0x3800
	s_mul_hi_i32 s53, s28, 0x3800
	s_mul_i32 s52, s28, 0x3800
	v_lshl_add_u64 v[24:25], v[156:157], 0, v[24:25]
	v_lshl_add_u64 v[40:41], v[88:89], 0, s[0:1]
	v_mov_b32_e32 v5, v4
	v_mov_b32_e32 v7, v6
	v_mov_b32_e32 v3, 0
	s_mov_b32 s2, 4
	v_mov_b64_e32 v[42:43], v[22:23]
	v_mov_b64_e32 v[44:45], v[20:21]
	v_mov_b64_e32 v[46:47], v[18:19]
	v_mov_b64_e32 v[48:49], v[16:17]
	v_mov_b64_e32 v[50:51], v[14:15]
	v_mov_b64_e32 v[52:53], v[12:13]
	v_mov_b64_e32 v[54:55], v[10:11]
	v_mov_b64_e32 v[56:57], v[8:9]
	s_mov_b32 s3, 0x6002000
	s_mov_b32 s4, 0x6001000
	s_mov_b32 s5, 0x20e00000
	s_mov_b32 s12, 0x42a00000
	s_mov_b32 s13, 0x21e00000
.LBB0_360:
	s_nop 0
	v_lshl_add_u64 v[58:59], s[46:47], 0, v[42:43]
	v_add_co_u32_e32 v60, vcc, s3, v58
	v_lshl_add_u64 v[62:63], s[46:47], 0, v[44:45]
	s_nop 0
	v_addc_co_u32_e32 v61, vcc, 0, v59, vcc
	v_add_co_u32_e32 v58, vcc, s4, v58
	v_lshl_add_u64 v[68:69], s[46:47], 0, v[46:47]
	s_nop 0
	v_addc_co_u32_e32 v59, vcc, 0, v59, vcc
	v_add_co_u32_e32 v64, vcc, s3, v62
	global_load_ushort v60, v[60:61], off
	s_nop 0
	v_addc_co_u32_e32 v65, vcc, 0, v63, vcc
	v_add_co_u32_e32 v62, vcc, s4, v62
	v_lshl_add_u64 v[72:73], s[46:47], 0, v[48:49]
	s_nop 0
	v_addc_co_u32_e32 v63, vcc, 0, v63, vcc
	global_load_ushort v62, v[62:63], off offset:3072
	v_lshl_add_u64 v[80:81], s[46:47], 0, v[50:51]
	v_lshl_add_u64 v[78:79], s[46:47], 0, v[52:53]
	v_lshl_add_u64 v[76:77], s[46:47], 0, v[54:55]
	v_lshl_add_u64 v[70:71], s[46:47], 0, v[56:57]
	s_add_i32 s2, s2, -1
	v_lshl_add_u64 v[56:57], v[56:57], 0, s[86:87]
	v_lshl_add_u64 v[54:55], v[54:55], 0, s[86:87]
	v_lshl_add_u64 v[52:53], v[52:53], 0, s[86:87]
	v_lshl_add_u64 v[50:51], v[50:51], 0, s[86:87]
	v_lshl_add_u64 v[48:49], v[48:49], 0, s[86:87]
	v_lshl_add_u64 v[46:47], v[46:47], 0, s[86:87]
	v_lshl_add_u64 v[44:45], v[44:45], 0, s[86:87]
	v_lshl_add_u64 v[42:43], v[42:43], 0, s[86:87]
	s_cmp_eq_u32 s2, 0
	s_waitcnt vmcnt(0)
	v_lshlrev_b32_e32 v62, 16, v62
	v_mul_f32_e32 v129, 0x3db504f3, v62
	v_add_co_u32_e32 v62, vcc, s3, v68
	s_nop 1
	v_addc_co_u32_e32 v63, vcc, 0, v69, vcc
	global_load_ushort v62, v[62:63], off
	s_waitcnt vmcnt(0)
	v_lshlrev_b32_e32 v62, 16, v62
	v_mul_f32_e32 v62, 0xbfb8aa3b, v62
	v_exp_f32_e32 v66, v62
	v_add_co_u32_e32 v62, vcc, s4, v68
	global_load_ushort v58, v[58:59], off offset:3072
	s_nop 0
	v_addc_co_u32_e32 v63, vcc, 0, v69, vcc
	v_add_co_u32_e32 v68, vcc, s3, v72
	global_load_ushort v61, v[64:65], off
	s_nop 0
	v_addc_co_u32_e32 v69, vcc, 0, v73, vcc
	global_load_ushort v67, v[68:69], off
	v_add_co_u32_e32 v68, vcc, s4, v72
	v_lshlrev_b32_e32 v60, 16, v60
	s_nop 0
	v_addc_co_u32_e32 v69, vcc, 0, v73, vcc
	global_load_ushort v68, v[68:69], off offset:3072
	v_mul_f32_e32 v60, 0xbfb8aa3b, v60
	global_load_ushort v62, v[62:63], off offset:3072
	v_exp_f32_e32 v60, v60
	v_lshl_add_u64 v[64:65], s[46:47], 0, v[38:39]
	v_lshl_add_u64 v[72:73], s[46:47], 0, v[34:35]
	v_lshl_add_u64 v[34:35], v[34:35], 0, s[54:55]
	v_lshl_add_u64 v[38:39], v[38:39], 0, s[54:55]
	s_waitcnt vmcnt(4)
	v_lshlrev_b32_e32 v58, 16, v58
	v_mul_f32_e32 v127, 0x3db504f3, v58
	v_lshl_add_u64 v[58:59], s[46:47], 0, v[40:41]
	v_lshl_add_u64 v[40:41], v[40:41], 0, s[54:55]
	s_waitcnt vmcnt(3)
	v_lshlrev_b32_e32 v61, 16, v61
	v_mul_f32_e32 v61, 0xbfb8aa3b, v61
	v_exp_f32_e32 v61, v61
	s_waitcnt vmcnt(2)
	v_lshlrev_b32_e32 v67, 16, v67
	v_mul_f32_e32 v67, 0xbfb8aa3b, v67
	v_exp_f32_e32 v67, v67
	v_pk_add_f32 v[60:61], v[60:61], 1.0 op_sel_hi:[1,0]
	s_waitcnt vmcnt(1)
	v_lshlrev_b32_e32 v68, 16, v68
	v_mul_f32_e32 v133, 0x3db504f3, v68
	v_add_co_u32_e32 v68, vcc, s3, v80
	s_nop 0
	s_nop 3
	v_addc_co_u32_e32 v69, vcc, 0, v81, vcc
	global_load_ushort v68, v[68:69], off
	s_waitcnt vmcnt(1)
	v_lshlrev_b32_e32 v62, 16, v62
	v_mul_f32_e32 v131, 0x3db504f3, v62
	v_lshl_add_u64 v[62:63], s[46:47], 0, v[36:37]
	v_lshl_add_u64 v[36:37], v[36:37], 0, s[54:55]
	s_waitcnt vmcnt(0)
; DI bf16_t f2bf(float x) { unsigned u = __float_as_uint(x); u += 0x7fffu + ((u >> 16) & 1u); return (bf16_t)(u >> 16); }
; DI float bf2f(bf16_t b) { return __uint_as_float(((unsigned)b) << 16); }
; DI float sigmoidf_(float x) { return 1.f / (1.f + __expf(-x)); }
; DI void phase_prep(const P& p, int layer, float* ldsf) {
;     ...
;         for (int j = 0; j < 8; ++j) { const bf16_t* row = proj + (long)(t0 + n8 * 8 + j) * NPJ; fl_[j] = row[4096 + tid]; gq_[j] = row[3584 + tid]; }
; #pragma unroll
;         for (int j = 0; j < 8; ++j) {
;           const int n = n8 * 8 + j;
;           float fl = bf2f(fl_[j]);
;           float f = lbv + (1.f - lbv) * sigmoidf_(fl);
;           G += __logf(fmaxf(f, 1e-6f));
;           float kk = 1.f - f;
;           qp[(long)(t0 + n) * 1024 + 512 + tid] = f2bf(bf2f(gq_[j]) * SCALE * __expf(G));
;           kp[(long)(t0 + n) * 1024 + 512 + tid] = f2bf(kk * __expf(fminf(-G, 80.f)));
;           kq8[j] = kk * __expf(G31 - G);
	v_lshlrev_b32_e32 v68, 16, v68
	v_mul_f32_e32 v68, 0xbfb8aa3b, v68
	v_exp_f32_e32 v74, v68
	v_add_co_u32_e32 v68, vcc, s4, v80
	s_nop 1
	v_addc_co_u32_e32 v69, vcc, 0, v81, vcc
	v_add_co_u32_e32 v80, vcc, s3, v78
	global_load_ushort v68, v[68:69], off offset:3072
	s_nop 0
	v_addc_co_u32_e32 v81, vcc, 0, v79, vcc
	v_add_co_u32_e32 v78, vcc, s4, v78
	global_load_ushort v75, v[80:81], off
	s_nop 0
	v_addc_co_u32_e32 v79, vcc, 0, v79, vcc
	global_load_ushort v78, v[78:79], off offset:3072
	v_add_co_u32_e32 v80, vcc, s3, v76
	s_waitcnt vmcnt(1)
	v_lshlrev_b32_e32 v75, 16, v75
	v_addc_co_u32_e32 v81, vcc, 0, v77, vcc
	v_add_co_u32_e32 v76, vcc, s4, v76
	global_load_ushort v80, v[80:81], off
	s_nop 0
	v_addc_co_u32_e32 v77, vcc, 0, v77, vcc
	v_add_co_u32_e32 v170, vcc, s3, v70
	global_load_ushort v76, v[76:77], off offset:3072
	s_nop 0
	v_addc_co_u32_e32 v171, vcc, 0, v71, vcc
	v_add_co_u32_e32 v70, vcc, s4, v70
	global_load_ushort v81, v[170:171], off
	s_nop 0
	v_addc_co_u32_e32 v71, vcc, 0, v71, vcc
	v_rcp_f32_e32 v143, v61
	s_nop 0
	v_mul_f32_e32 v61, 1.0, v143
	global_load_ushort v70, v[70:71], off offset:3072
	v_mul_f32_e32 v75, 0xbfb8aa3b, v75
	v_exp_f32_e32 v75, v75
	v_rcp_f32_e32 v143, v60
	s_nop 0
	v_mul_f32_e32 v60, 1.0, v143
	v_pk_fma_f32 v[60:61], v[6:7], v[60:61], v[4:5]
	v_lshlrev_b32_e32 v68, 16, v68
	v_max_f32_e32 v143, 0x358637bd, v60
	v_cmp_gt_f32_e32 vcc, s33, v143
	v_mul_f32_e32 v135, 0x3db504f3, v68
	v_lshl_add_u64 v[68:69], s[46:47], 0, v[32:33]
	v_cndmask_b32_e64 v145, 0, 32, vcc
	v_ldexp_f32 v143, v143, v145
	v_log_f32_e32 v143, v143
	s_waitcnt vmcnt(4)
	v_lshlrev_b32_e32 v78, 16, v78
	v_mul_f32_e32 v137, 0x3db504f3, v78
	v_lshl_add_u64 v[78:79], s[46:47], 0, v[30:31]
	v_mul_f32_e32 v145, 0x3f317217, v143
	v_fma_f32 v145, v143, s79, -v145
	v_fmac_f32_e32 v145, 0x3377d1cf, v143
	v_fmac_f32_e32 v145, 0x3f317217, v143
	v_cmp_lt_f32_e64 s[0:1], |v143|, s73
	v_lshl_add_u64 v[170:171], s[46:47], 0, v[26:27]
	v_lshl_add_u64 v[26:27], v[26:27], 0, s[54:55]
	v_cndmask_b32_e64 v143, v143, v145, s[0:1]
	v_cndmask_b32_e32 v145, 0, v211, vcc
	v_sub_f32_e32 v143, v143, v145
	v_add_f32_e32 v3, v3, v143
	v_mul_f32_e32 v143, 0x3fb8aa3b, v3
	v_exp_f32_e32 v143, v143
	v_add_co_u32_e32 v172, vcc, s5, v58
	v_lshl_add_u64 v[30:31], v[30:31], 0, s[54:55]
	v_mul_f32_e32 v127, v127, v143
	v_bfe_u32 v143, v127, 16, 1
	v_add3_u32 v127, v127, v143, s75
	v_addc_co_u32_e32 v173, vcc, 0, v59, vcc
	global_store_short_d16_hi v[172:173], v127, off offset:1024
	v_min_f32_e64 v127, -v3, s12
	v_mul_f32_e32 v127, 0x3fb8aa3b, v127
	v_exp_f32_e32 v127, v127
	v_pk_add_f32 v[172:173], v[60:61], 1.0 op_sel_hi:[1,0] neg_lo:[1,0] neg_hi:[1,0]
	v_add_co_u32_e32 v58, vcc, s13, v58
	v_mul_f32_e32 v60, v172, v127
	v_bfe_u32 v127, v60, 16, 1
	v_add3_u32 v60, v60, v127, s75
	v_addc_co_u32_e32 v59, vcc, 0, v59, vcc
	global_store_short_d16_hi v[58:59], v60, off offset:1024
	v_max_f32_e32 v59, 0x358637bd, v61
	v_cmp_gt_f32_e32 vcc, s33, v59
	v_sub_f32_e32 v58, v0, v3
	s_waitcnt vmcnt(5)
	v_lshlrev_b32_e32 v80, 16, v80
	v_cndmask_b32_e64 v60, 0, 32, vcc
	v_ldexp_f32 v59, v59, v60
	v_log_f32_e32 v59, v59
	s_waitcnt vmcnt(3)
	v_lshlrev_b32_e32 v81, 16, v81
	v_mul_f32_e32 v80, 0xbfb8aa3b, v80
	v_mul_f32_e32 v81, 0xbfb8aa3b, v81
	v_mul_f32_e32 v60, 0x3f317217, v59
	v_fma_f32 v60, v59, s79, -v60
	v_fmac_f32_e32 v60, 0x3377d1cf, v59
	v_fmac_f32_e32 v60, 0x3f317217, v59
	v_cmp_lt_f32_e64 s[0:1], |v59|, s73
	v_exp_f32_e32 v80, v80
	v_exp_f32_e32 v81, v81
	v_cndmask_b32_e64 v59, v59, v60, s[0:1]
	v_cndmask_b32_e32 v60, 0, v211, vcc
	v_sub_f32_e32 v59, v59, v60
	v_add_f32_e32 v3, v3, v59
	v_mul_f32_e32 v59, 0x3fb8aa3b, v3
	v_exp_f32_e32 v59, v59
	v_lshlrev_b32_e32 v76, 16, v76
	v_mul_f32_e32 v139, 0x3db504f3, v76
	v_lshl_add_u64 v[76:77], s[46:47], 0, v[28:29]
	v_mul_f32_e32 v59, v129, v59
	v_bfe_u32 v60, v59, 16, 1
	v_add3_u32 v59, v59, v60, s75
	v_add_co_u32_e32 v60, vcc, s5, v64
	s_waitcnt vmcnt(2)
	v_lshlrev_b32_e32 v70, 16, v70
	v_addc_co_u32_e32 v61, vcc, 0, v65, vcc
	global_store_short_d16_hi v[60:61], v59, off offset:1024
	v_min_f32_e64 v59, -v3, s12
	v_mul_f32_e32 v59, 0x3fb8aa3b, v59
	v_exp_f32_e32 v59, v59
	v_mul_f32_e32 v141, 0x3db504f3, v70
	v_mul_f32_e32 v58, 0x3fb8aa3b, v58
	v_exp_f32_e32 v58, v58
	v_mul_f32_e32 v59, v173, v59
	v_bfe_u32 v60, v59, 16, 1
	v_add3_u32 v59, v59, v60, s75
	v_add_co_u32_e32 v60, vcc, s13, v64
	v_lshl_add_u64 v[70:71], s[46:47], 0, v[24:25]
	s_nop 0
	v_addc_co_u32_e32 v61, vcc, 0, v65, vcc
	global_store_short_d16_hi v[60:61], v59, off offset:1024
	v_pk_add_f32 v[60:61], v[66:67], 1.0 op_sel_hi:[1,0]
	v_sub_f32_e32 v59, v0, v3
	v_mul_f32_e32 v59, 0x3fb8aa3b, v59
	v_exp_f32_e32 v59, v59
	v_lshl_add_u64 v[24:25], v[24:25], 0, 16
	v_rcp_f32_e32 v64, v61
	s_nop 0
	v_mul_f32_e32 v61, 1.0, v64
	v_pk_mul_f32 v[58:59], v[172:173], v[58:59]
	v_lshl_add_u64 v[28:29], v[28:29], 0, s[54:55]
	v_lshl_add_u64 v[32:33], v[32:33], 0, s[54:55]
	v_rcp_f32_e32 v64, v60
	s_nop 0
	v_mul_f32_e32 v60, 1.0, v64
	v_pk_fma_f32 v[60:61], v[6:7], v[60:61], v[4:5]
	s_nop 0
	v_max_f32_e32 v64, 0x358637bd, v60
	v_cmp_gt_f32_e32 vcc, s33, v64
	s_nop 1
	v_cndmask_b32_e64 v65, 0, 32, vcc
	v_ldexp_f32 v64, v64, v65
	v_log_f32_e32 v64, v64
	s_nop 0
	v_mul_f32_e32 v65, 0x3f317217, v64
	v_fma_f32 v65, v64, s79, -v65
	v_fmac_f32_e32 v65, 0x3377d1cf, v64
	v_fmac_f32_e32 v65, 0x3f317217, v64
	v_cmp_lt_f32_e64 s[0:1], |v64|, s73
	s_nop 1
	v_cndmask_b32_e64 v64, v64, v65, s[0:1]
	v_cndmask_b32_e32 v65, 0, v211, vcc
	v_sub_f32_e32 v64, v64, v65
	v_max_f32_e32 v65, 0x358637bd, v61
	v_cmp_gt_f32_e32 vcc, s33, v65
	v_add_f32_e32 v3, v3, v64
	v_mul_f32_e32 v64, 0x3fb8aa3b, v3
; DI bf16_t f2bf(float x) { unsigned u = __float_as_uint(x); u += 0x7fffu + ((u >> 16) & 1u); return (bf16_t)(u >> 16); }
; DI float bf2f(bf16_t b) { return __uint_as_float(((unsigned)b) << 16); }
; DI float sigmoidf_(float x) { return 1.f / (1.f + __expf(-x)); }
; DI void phase_prep(const P& p, int layer, float* ldsf) {
;     ...
;         for (int j = 0; j < 8; ++j) { const bf16_t* row = proj + (long)(t0 + n8 * 8 + j) * NPJ; fl_[j] = row[4096 + tid]; gq_[j] = row[3584 + tid]; }
; #pragma unroll
;         for (int j = 0; j < 8; ++j) {
;           const int n = n8 * 8 + j;
;           float fl = bf2f(fl_[j]);
;           float f = lbv + (1.f - lbv) * sigmoidf_(fl);
;           G += __logf(fmaxf(f, 1e-6f));
;           float kk = 1.f - f;
;           qp[(long)(t0 + n) * 1024 + 512 + tid] = f2bf(bf2f(gq_[j]) * SCALE * __expf(G));
;           kp[(long)(t0 + n) * 1024 + 512 + tid] = f2bf(kk * __expf(fminf(-G, 80.f)));
;           kq8[j] = kk * __expf(G31 - G);
	v_cndmask_b32_e64 v66, 0, 32, vcc
	v_ldexp_f32 v65, v65, v66
	v_log_f32_e32 v65, v65
	v_exp_f32_e32 v64, v64
	v_pk_add_f32 v[60:61], v[60:61], 1.0 op_sel_hi:[1,0] neg_lo:[1,0] neg_hi:[1,0]
	v_mul_f32_e32 v66, 0x3f317217, v65
	v_fma_f32 v66, v65, s79, -v66
	v_fmac_f32_e32 v66, 0x3377d1cf, v65
	v_fmac_f32_e32 v66, 0x3f317217, v65
	v_cmp_lt_f32_e64 s[0:1], |v65|, s73
	v_mul_f32_e32 v64, v131, v64
	s_nop 0
	v_cndmask_b32_e64 v65, v65, v66, s[0:1]
	v_cndmask_b32_e32 v66, 0, v211, vcc
	v_sub_f32_e32 v66, v65, v66
	v_bfe_u32 v65, v64, 16, 1
	v_add3_u32 v67, v64, v65, s75
	v_add_co_u32_e32 v64, vcc, s5, v62
	s_nop 1
	v_addc_co_u32_e32 v65, vcc, 0, v63, vcc
	global_store_short_d16_hi v[64:65], v67, off offset:1024
	v_min_f32_e64 v64, -v3, s12
	v_mul_f32_e32 v64, 0x3fb8aa3b, v64
	v_exp_f32_e32 v64, v64
	v_add_co_u32_e32 v62, vcc, s13, v62
	v_mul_f32_e32 v64, v60, v64
	v_bfe_u32 v65, v64, 16, 1
	v_add3_u32 v64, v64, v65, s75
	v_addc_co_u32_e32 v63, vcc, 0, v63, vcc
	global_store_short_d16_hi v[62:63], v64, off offset:1024
	v_sub_f32_e32 v62, v0, v3
	v_add_f32_e32 v3, v3, v66
	v_mul_f32_e32 v63, 0x3fb8aa3b, v3
	v_exp_f32_e32 v63, v63
	v_mul_f32_e32 v62, 0x3fb8aa3b, v62
	v_exp_f32_e32 v62, v62
	v_mul_f32_e32 v63, v133, v63
	v_bfe_u32 v64, v63, 16, 1
	v_add3_u32 v63, v63, v64, s75
	v_add_co_u32_e32 v64, vcc, s5, v72
	s_nop 1
	v_addc_co_u32_e32 v65, vcc, 0, v73, vcc
	global_store_short_d16_hi v[64:65], v63, off offset:1024
	v_min_f32_e64 v63, -v3, s12
	v_mul_f32_e32 v63, 0x3fb8aa3b, v63
	v_exp_f32_e32 v63, v63
	s_nop 0
	v_mul_f32_e32 v63, v61, v63
	v_bfe_u32 v64, v63, 16, 1
	v_add3_u32 v63, v63, v64, s75
	v_add_co_u32_e32 v64, vcc, s13, v72
	s_nop 1
	v_addc_co_u32_e32 v65, vcc, 0, v73, vcc
	global_store_short_d16_hi v[64:65], v63, off offset:1024
	v_sub_f32_e32 v63, v0, v3
	v_mul_f32_e32 v63, 0x3fb8aa3b, v63
	v_exp_f32_e32 v63, v63
	s_nop 0
	v_pk_mul_f32 v[60:61], v[60:61], v[62:63]
	v_pk_add_f32 v[62:63], v[74:75], 1.0 op_sel_hi:[1,0]
	v_bfe_u32 v74, v59, 16, 1
	v_bfe_u32 v75, v58, 16, 1
	v_add3_u32 v58, v58, v75, s75
	v_rcp_f32_e32 v64, v63
	s_nop 0
	v_mul_f32_e32 v63, 1.0, v64
	s_nop 0
	v_rcp_f32_e32 v64, v62
	s_nop 0
	v_mul_f32_e32 v62, 1.0, v64
	v_pk_fma_f32 v[62:63], v[6:7], v[62:63], v[4:5]
	s_nop 0
	v_max_f32_e32 v64, 0x358637bd, v62
	v_cmp_gt_f32_e32 vcc, s33, v64
	s_nop 1
	v_cndmask_b32_e64 v65, 0, 32, vcc
	v_ldexp_f32 v64, v64, v65
	v_log_f32_e32 v64, v64
	s_nop 0
	v_mul_f32_e32 v65, 0x3f317217, v64
	v_fma_f32 v65, v64, s79, -v65
	v_fmac_f32_e32 v65, 0x3377d1cf, v64
	v_fmac_f32_e32 v65, 0x3f317217, v64
	v_cmp_lt_f32_e64 s[0:1], |v64|, s73
	s_nop 1
	v_cndmask_b32_e64 v64, v64, v65, s[0:1]
	v_cndmask_b32_e32 v65, 0, v211, vcc
	v_sub_f32_e32 v64, v64, v65
	v_max_f32_e32 v65, 0x358637bd, v63
	v_cmp_gt_f32_e32 vcc, s33, v65
	v_add_f32_e32 v3, v3, v64
	v_mul_f32_e32 v64, 0x3fb8aa3b, v3
	v_cndmask_b32_e64 v66, 0, 32, vcc
	v_ldexp_f32 v65, v65, v66
	v_log_f32_e32 v65, v65
	v_exp_f32_e32 v64, v64
	v_pk_add_f32 v[62:63], v[62:63], 1.0 op_sel_hi:[1,0] neg_lo:[1,0] neg_hi:[1,0]
	v_mul_f32_e32 v66, 0x3f317217, v65
	v_fma_f32 v66, v65, s79, -v66
	v_fmac_f32_e32 v66, 0x3377d1cf, v65
	v_fmac_f32_e32 v66, 0x3f317217, v65
	v_cmp_lt_f32_e64 s[0:1], |v65|, s73
	v_mul_f32_e32 v64, v135, v64
	s_nop 0
	v_cndmask_b32_e64 v65, v65, v66, s[0:1]
	v_cndmask_b32_e32 v66, 0, v211, vcc
	v_sub_f32_e32 v66, v65, v66
	v_bfe_u32 v65, v64, 16, 1
	v_add3_u32 v67, v64, v65, s75
	v_add_co_u32_e32 v64, vcc, s5, v68
	s_nop 1
	v_addc_co_u32_e32 v65, vcc, 0, v69, vcc
	global_store_short_d16_hi v[64:65], v67, off offset:1024
	v_min_f32_e64 v64, -v3, s12
	v_mul_f32_e32 v64, 0x3fb8aa3b, v64
	v_exp_f32_e32 v64, v64
	s_nop 0
	v_mul_f32_e32 v64, v62, v64
	v_bfe_u32 v65, v64, 16, 1
	v_add3_u32 v67, v64, v65, s75
	v_add_co_u32_e32 v64, vcc, s13, v68
	s_nop 1
	v_addc_co_u32_e32 v65, vcc, 0, v69, vcc
	global_store_short_d16_hi v[64:65], v67, off offset:1024
	v_sub_f32_e32 v64, v0, v3
	v_add_f32_e32 v3, v3, v66
	v_mul_f32_e32 v65, 0x3fb8aa3b, v3
	v_exp_f32_e32 v65, v65
	v_mul_f32_e32 v64, 0x3fb8aa3b, v64
	v_exp_f32_e32 v64, v64
	v_mul_f32_e32 v65, v137, v65
	v_bfe_u32 v66, v65, 16, 1
	v_add3_u32 v65, v65, v66, s75
	v_add_co_u32_e32 v66, vcc, s5, v78
	s_nop 1
	v_addc_co_u32_e32 v67, vcc, 0, v79, vcc
	global_store_short_d16_hi v[66:67], v65, off offset:1024
; DI bf16_t f2bf(float x) { unsigned u = __float_as_uint(x); u += 0x7fffu + ((u >> 16) & 1u); return (bf16_t)(u >> 16); }
; DI float bf2f(bf16_t b) { return __uint_as_float(((unsigned)b) << 16); }
; DI float sigmoidf_(float x) { return 1.f / (1.f + __expf(-x)); }
; DI void phase_prep(const P& p, int layer, float* ldsf) {
;     ...
;         for (int j = 0; j < 8; ++j) {
;           const int n = n8 * 8 + j;
;           float fl = bf2f(fl_[j]);
;           float f = lbv + (1.f - lbv) * sigmoidf_(fl);
;           G += __logf(fmaxf(f, 1e-6f));
;           float kk = 1.f - f;
;           qp[(long)(t0 + n) * 1024 + 512 + tid] = f2bf(bf2f(gq_[j]) * SCALE * __expf(G));
;           kp[(long)(t0 + n) * 1024 + 512 + tid] = f2bf(kk * __expf(fminf(-G, 80.f)));
;           kq8[j] = kk * __expf(G31 - G);
;         }
;         store_t32(kppT + ((long)(c * 8 + 4 + hd) * 128 + d) * 32 + n8 * 8, kq8);
;       }
;       adec[(c * 8 + 4 + hd) * 128 + d] = __expf(G31);
	v_min_f32_e64 v65, -v3, s12
	v_mul_f32_e32 v65, 0x3fb8aa3b, v65
	v_exp_f32_e32 v65, v65
	s_nop 0
	v_mul_f32_e32 v65, v63, v65
	v_bfe_u32 v66, v65, 16, 1
	v_add3_u32 v65, v65, v66, s75
	v_add_co_u32_e32 v66, vcc, s13, v78
	s_nop 1
	v_addc_co_u32_e32 v67, vcc, 0, v79, vcc
	global_store_short_d16_hi v[66:67], v65, off offset:1024
	v_sub_f32_e32 v65, v0, v3
	v_mul_f32_e32 v65, 0x3fb8aa3b, v65
	v_exp_f32_e32 v65, v65
	s_nop 0
	v_pk_mul_f32 v[62:63], v[62:63], v[64:65]
	v_pk_add_f32 v[64:65], v[80:81], 1.0 op_sel_hi:[1,0]
	s_nop 0
	s_nop 0
	v_rcp_f32_e32 v66, v65
	s_nop 0
	v_mul_f32_e32 v65, 1.0, v66
	s_nop 0
	v_rcp_f32_e32 v66, v64
	s_nop 0
	v_mul_f32_e32 v64, 1.0, v66
	v_pk_fma_f32 v[64:65], v[6:7], v[64:65], v[4:5]
	s_nop 0
	v_max_f32_e32 v66, 0x358637bd, v64
	v_cmp_gt_f32_e32 vcc, s33, v66
	s_nop 1
	v_cndmask_b32_e64 v67, 0, 32, vcc
	v_ldexp_f32 v66, v66, v67
	v_log_f32_e32 v66, v66
	s_nop 0
	v_mul_f32_e32 v67, 0x3f317217, v66
	v_fma_f32 v67, v66, s79, -v67
	v_fmac_f32_e32 v67, 0x3377d1cf, v66
	v_fmac_f32_e32 v67, 0x3f317217, v66
	v_cmp_lt_f32_e64 s[0:1], |v66|, s73
	s_nop 1
	v_cndmask_b32_e64 v66, v66, v67, s[0:1]
	v_cndmask_b32_e32 v67, 0, v211, vcc
	v_sub_f32_e32 v66, v66, v67
	v_max_f32_e32 v67, 0x358637bd, v65
	v_cmp_gt_f32_e32 vcc, s33, v67
	v_add_f32_e32 v3, v3, v66
	v_mul_f32_e32 v66, 0x3fb8aa3b, v3
	v_cndmask_b32_e64 v68, 0, 32, vcc
	v_ldexp_f32 v67, v67, v68
	v_log_f32_e32 v67, v67
	v_exp_f32_e32 v66, v66
	v_pk_add_f32 v[64:65], v[64:65], 1.0 op_sel_hi:[1,0] neg_lo:[1,0] neg_hi:[1,0]
	v_mul_f32_e32 v68, 0x3f317217, v67
	v_fma_f32 v68, v67, s79, -v68
	v_fmac_f32_e32 v68, 0x3377d1cf, v67
	v_fmac_f32_e32 v68, 0x3f317217, v67
	v_cmp_lt_f32_e64 s[0:1], |v67|, s73
	v_mul_f32_e32 v66, v139, v66
	s_nop 0
	v_cndmask_b32_e64 v67, v67, v68, s[0:1]
	v_cndmask_b32_e32 v68, 0, v211, vcc
	v_sub_f32_e32 v68, v67, v68
	v_bfe_u32 v67, v66, 16, 1
	v_add3_u32 v69, v66, v67, s75
	v_add_co_u32_e32 v66, vcc, s5, v76
	s_nop 1
	v_addc_co_u32_e32 v67, vcc, 0, v77, vcc
	global_store_short_d16_hi v[66:67], v69, off offset:1024
	v_min_f32_e64 v66, -v3, s12
	v_mul_f32_e32 v66, 0x3fb8aa3b, v66
	v_exp_f32_e32 v66, v66
	s_nop 0
	v_mul_f32_e32 v66, v64, v66
	v_bfe_u32 v67, v66, 16, 1
	v_add3_u32 v69, v66, v67, s75
	v_add_co_u32_e32 v66, vcc, s13, v76
	s_nop 1
	v_addc_co_u32_e32 v67, vcc, 0, v77, vcc
	global_store_short_d16_hi v[66:67], v69, off offset:1024
	v_sub_f32_e32 v66, v0, v3
	v_add_f32_e32 v3, v3, v68
	v_mul_f32_e32 v67, 0x3fb8aa3b, v3
	v_exp_f32_e32 v67, v67
	v_mul_f32_e32 v66, 0x3fb8aa3b, v66
	v_exp_f32_e32 v66, v66
	v_mul_f32_e32 v67, v141, v67
	v_bfe_u32 v68, v67, 16, 1
	v_add3_u32 v67, v67, v68, s75
	v_add_co_u32_e32 v68, vcc, s5, v170
	s_nop 1
	v_addc_co_u32_e32 v69, vcc, 0, v171, vcc
	global_store_short_d16_hi v[68:69], v67, off offset:1024
	v_min_f32_e64 v67, -v3, s12
	v_mul_f32_e32 v67, 0x3fb8aa3b, v67
	v_exp_f32_e32 v67, v67
	s_nop 0
	v_mul_f32_e32 v67, v65, v67
	v_bfe_u32 v68, v67, 16, 1
	v_add3_u32 v67, v67, v68, s75
	v_add_co_u32_e32 v68, vcc, s13, v170
	s_nop 1
	v_addc_co_u32_e32 v69, vcc, 0, v171, vcc
	global_store_short_d16_hi v[68:69], v67, off offset:1024
	v_sub_f32_e32 v67, v0, v3
	v_mul_f32_e32 v67, 0x3fb8aa3b, v67
	v_exp_f32_e32 v67, v67
	v_bfe_u32 v68, v63, 16, 1
	v_bfe_u32 v69, v62, 16, 1
	v_add3_u32 v62, v62, v69, s75
	v_pk_mul_f32 v[64:65], v[64:65], v[66:67]
	v_bfe_u32 v66, v61, 16, 1
	v_bfe_u32 v67, v60, 16, 1
	v_bfe_u32 v72, v65, 16, 1
	v_bfe_u32 v73, v64, 16, 1
	v_add3_u32 v64, v64, v73, s75
	v_add3_u32 v65, v65, v72, s75
	v_add3_u32 v63, v63, v68, s75
	v_add3_u32 v60, v60, v67, s75
	v_add3_u32 v61, v61, v66, s75
	v_add3_u32 v66, v59, v74, s75
	v_perm_b32 v59, v61, v60, s76
	v_perm_b32 v60, v63, v62, s76
	v_perm_b32 v61, v65, v64, s76
	v_perm_b32 v58, v66, v58, s76
	global_store_dwordx4 v[70:71], v[58:61], off
	s_cbranch_scc0 .LBB0_360
	v_mul_f32_e32 v0, 0x3fb8aa3b, v0
	v_exp_f32_e32 v0, v0
	v_add_u32_e32 v2, 0x200, v2
	v_readlane_b32 s2, v252, 59
	s_lshl_b64 s[0:1], s[28:29], 1
	v_ashrrev_i32_e32 v3, 31, v2
	v_readlane_b32 s3, v252, 60
	v_lshl_add_u64 v[4:5], v[160:161], 0, s[0:1]
	v_lshl_add_u64 v[6:7], v[162:163], 0, s[0:1]
	v_lshl_add_u64 v[2:3], v[2:3], 2, s[2:3]
	s_mov_b32 s2, 4
	s_mov_b32 s4, 0x6000000
	global_store_dword v[2:3], v0, off

; DI unsigned pk2(float a, float b) { f32x2 v; v[0] = a; v[1] = b; return __builtin_bit_cast(unsigned, __builtin_convertvector(v, bf16v2)); }
; DI float siluf_(float x) { return x / (1.f + __expf(-x)); }
; DI void gemm_tile(const GD& g, int pm, int pn, bf16_t* shm) {
;     ...
; #pragma unroll
;         for (int rr = 0; rr < 8; ++rr) {
;           const int row_l = r0 + rr;
;           const float4 gc = *reinterpret_cast<const float4*>(stgw + row_l * 68 + cgp * 4);
;           const float4 vc = *reinterpret_cast<const float4*>(stgw + row_l * 68 + 32 + cgp * 4);
;           const int grow = brow + ai * HALF + wr * 64 + row_l;
;           if (!(first && rr < 2)) {
;             const float a0 = siluf_(bg.x + wg0.x * g2.x + wg1.x * g1.x + wg2.x * gc.x) * (bv.x + wv0.x * v2.x + wv1.x * v1.x + wv2.x * vc.x);
;             const float a1 = siluf_(bg.y + wg0.y * g2.y + wg1.y * g1.y + wg2.y * gc.y) * (bv.y + wv0.y * v2.y + wv1.y * v1.y + wv2.y * vc.y);
;             const float a2 = siluf_(bg.z + wg0.z * g2.z + wg1.z * g1.z + wg2.z * gc.z) * (bv.z + wv0.z * v2.z + wv1.z * v1.z + wv2.z * vc.z);
;             const float a3 = siluf_(bg.w + wg0.w * g2.w + wg1.w * g1.w + wg2.w * gc.w) * (bv.w + wv0.w * v2.w + wv1.w * v1.w + wv2.w * vc.w);
;             u32x2 o2; o2[0] = pk2(a0, a1); o2[1] = pk2(a2, a3);
;             *reinterpret_cast<u32x2*>((bf16_t*)g.C + (long)grow * DFF + fcol) = o2;
;           }
;           if (first && rr < 2) {
;             *reinterpret_cast<float4*>(halo + (size_t)rr * NUP + fcol) = gc; *reinterpret_cast<float4*>(halo + (size_t)rr * NUP + DFF + fcol) = vc;
;           }
.LBB0_534:
	s_or_b64 exec, exec, s[0:1]
	v_mul_u32_u24_e32 v124, 0x110, v142
	v_lshlrev_b32_e32 v126, 2, v146
	v_add3_u32 v98, v141, v124, v126
	ds_read_b128 v[110:113], v98
	ds_read_b128 v[98:101], v98 offset:128
	s_lshl_b64 s[0:1], s[56:57], 2
	v_readlane_b32 s2, v255, 5
	v_readlane_b32 s3, v255, 6
	s_add_u32 s0, s2, s0
	s_addc_u32 s1, s3, s1
	s_and_saveexec_b64 s[2:3], s[52:53]
	s_xor_b64 s[12:13], exec, s[2:3]
	s_cbranch_execz .LBB0_536
	s_waitcnt vmcnt(1) lgkmcnt(5)
	v_pk_fma_f32 v[114:115], v[82:83], v[114:115], v[94:95]
	s_waitcnt vmcnt(0) lgkmcnt(4)
	v_pk_fma_f32 v[102:103], v[2:3], v[102:103], v[14:15]
	s_waitcnt lgkmcnt(3)
	v_pk_fma_f32 v[114:115], v[86:87], v[118:119], v[114:115]
	s_waitcnt lgkmcnt(2)
	v_pk_fma_f32 v[102:103], v[6:7], v[106:107], v[102:103]
	s_waitcnt lgkmcnt(1)
	v_pk_fma_f32 v[114:115], v[90:91], v[110:111], v[114:115]
	s_waitcnt lgkmcnt(0)
	v_pk_fma_f32 v[102:103], v[10:11], v[98:99], v[102:103]
	v_mul_f32_e32 v122, 0xbfb8aa3b, v114
	v_mul_f32_e32 v123, 0xbfb8aa3b, v115
	v_exp_f32_e32 v122, v122
	v_exp_f32_e32 v123, v123
	v_pk_fma_f32 v[104:105], v[4:5], v[104:105], v[16:17]
	v_or_b32_e32 v125, v140, v142
	v_pk_fma_f32 v[104:105], v[8:9], v[108:109], v[104:105]
	v_pk_add_f32 v[122:123], v[122:123], 1.0 op_sel_hi:[1,0]
	v_pk_fma_f32 v[104:105], v[12:13], v[100:101], v[104:105]
	s_nop 0
	v_rcp_f32_e32 v127, v123
	s_nop 0
	v_mul_f32_e32 v115, v115, v127
	s_nop 0
	v_rcp_f32_e32 v123, v122
	s_nop 0
	v_mul_f32_e32 v114, v114, v123
	v_pk_mul_f32 v[102:103], v[114:115], v[102:103]
	v_pk_fma_f32 v[114:115], v[84:85], v[116:117], v[96:97]
	v_cvt_pk_bf16_f32 v102, v102, v103
	v_pk_fma_f32 v[114:115], v[88:89], v[120:121], v[114:115]
	s_nop 0
	v_pk_fma_f32 v[114:115], v[92:93], v[112:113], v[114:115]
	s_nop 0
	v_mul_f32_e32 v116, 0xbfb8aa3b, v114
	v_mul_f32_e32 v117, 0xbfb8aa3b, v115
	v_exp_f32_e32 v116, v116
	v_exp_f32_e32 v117, v117
	s_nop 0
	v_pk_add_f32 v[116:117], v[116:117], 1.0 op_sel_hi:[1,0]
	s_nop 0
	s_nop 0
	v_rcp_f32_e32 v122, v117
	s_nop 0
	v_mul_f32_e32 v115, v115, v122
	s_movk_i32 s2, 0x2c00
	v_rcp_f32_e32 v117, v116
	s_nop 0
	v_mul_f32_e32 v114, v114, v117
	v_pk_mul_f32 v[104:105], v[114:115], v[104:105]
	s_nop 0
	v_cvt_pk_bf16_f32 v103, v104, v105
	v_mov_b64_e32 v[104:105], s[34:35]
	v_mad_i64_i32 v[104:105], s[2:3], v125, s2, v[104:105]
	v_lshl_add_u64 v[104:105], v[130:131], 1, v[104:105]
	global_store_dwordx2 v[104:105], v[102:103], off

; DI unsigned pk2(float a, float b) { f32x2 v; v[0] = a; v[1] = b; return __builtin_bit_cast(unsigned, __builtin_convertvector(v, bf16v2)); }
; DI float siluf_(float x) { return x / (1.f + __expf(-x)); }
; DI void gemm_tile(const GD& g, int pm, int pn, bf16_t* shm) {
;     ...
; #pragma unroll
;         for (int rr = 0; rr < 8; ++rr) {
;           const int row_l = r0 + rr;
;           const float4 gc = *reinterpret_cast<const float4*>(stgw + row_l * 68 + cgp * 4);
;           const float4 vc = *reinterpret_cast<const float4*>(stgw + row_l * 68 + 32 + cgp * 4);
;           const int grow = brow + ai * HALF + wr * 64 + row_l;
;           if (!(first && rr < 2)) {
;             const float a0 = siluf_(bg.x + wg0.x * g2.x + wg1.x * g1.x + wg2.x * gc.x) * (bv.x + wv0.x * v2.x + wv1.x * v1.x + wv2.x * vc.x);
;             const float a1 = siluf_(bg.y + wg0.y * g2.y + wg1.y * g1.y + wg2.y * gc.y) * (bv.y + wv0.y * v2.y + wv1.y * v1.y + wv2.y * vc.y);
;             const float a2 = siluf_(bg.z + wg0.z * g2.z + wg1.z * g1.z + wg2.z * gc.z) * (bv.z + wv0.z * v2.z + wv1.z * v1.z + wv2.z * vc.z);
;             const float a3 = siluf_(bg.w + wg0.w * g2.w + wg1.w * g1.w + wg2.w * gc.w) * (bv.w + wv0.w * v2.w + wv1.w * v1.w + wv2.w * vc.w);
;             u32x2 o2; o2[0] = pk2(a0, a1); o2[1] = pk2(a2, a3);
;             *reinterpret_cast<u32x2*>((bf16_t*)g.C + (long)grow * DFF + fcol) = o2;
;           }
;           if (first && rr < 2) {
;             *reinterpret_cast<float4*>(halo + (size_t)rr * NUP + fcol) = gc; *reinterpret_cast<float4*>(halo + (size_t)rr * NUP + DFF + fcol) = vc;
;           }
.LBB0_538:
	s_or_b64 exec, exec, s[2:3]
	v_add_u32_e32 v128, 0x110, v124
	v_add3_u32 v127, v141, v128, v126
	s_waitcnt lgkmcnt(5)
	ds_read_b128 v[114:117], v127
	s_waitcnt lgkmcnt(5)
	ds_read_b128 v[102:105], v127 offset:128
	s_and_saveexec_b64 s[0:1], s[52:53]
	s_xor_b64 s[0:1], exec, s[0:1]
	s_cbranch_execz .LBB0_540
	s_waitcnt vmcnt(1) lgkmcnt(5)
	v_pk_fma_f32 v[118:119], v[82:83], v[118:119], v[94:95]
	s_waitcnt vmcnt(0) lgkmcnt(4)
	v_pk_fma_f32 v[106:107], v[2:3], v[106:107], v[14:15]
	s_waitcnt lgkmcnt(3)
	v_pk_fma_f32 v[118:119], v[86:87], v[110:111], v[118:119]
	s_waitcnt lgkmcnt(2)
	v_pk_fma_f32 v[106:107], v[6:7], v[98:99], v[106:107]
	s_waitcnt lgkmcnt(1)
	v_pk_fma_f32 v[118:119], v[90:91], v[114:115], v[118:119]
	s_waitcnt lgkmcnt(0)
	v_pk_fma_f32 v[106:107], v[10:11], v[102:103], v[106:107]
	v_mul_f32_e32 v122, 0xbfb8aa3b, v118
	v_mul_f32_e32 v123, 0xbfb8aa3b, v119
	v_exp_f32_e32 v122, v122
	v_exp_f32_e32 v123, v123
	v_pk_fma_f32 v[108:109], v[4:5], v[108:109], v[16:17]
	v_or3_b32 v124, v142, v140, 1
	v_pk_fma_f32 v[108:109], v[8:9], v[100:101], v[108:109]
	v_pk_add_f32 v[122:123], v[122:123], 1.0 op_sel_hi:[1,0]
	v_pk_fma_f32 v[108:109], v[12:13], v[104:105], v[108:109]
	s_nop 0
	v_rcp_f32_e32 v125, v123
	s_nop 0
	v_mul_f32_e32 v119, v119, v125
	s_nop 0
	v_rcp_f32_e32 v123, v122
	s_nop 0
	v_mul_f32_e32 v118, v118, v123
	v_pk_mul_f32 v[106:107], v[118:119], v[106:107]
	v_pk_fma_f32 v[118:119], v[84:85], v[120:121], v[96:97]
	v_cvt_pk_bf16_f32 v106, v106, v107
	v_pk_fma_f32 v[118:119], v[88:89], v[112:113], v[118:119]
	s_nop 0
	v_pk_fma_f32 v[118:119], v[92:93], v[116:117], v[118:119]
	s_nop 0
	v_mul_f32_e32 v120, 0xbfb8aa3b, v118
	v_mul_f32_e32 v121, 0xbfb8aa3b, v119
	v_exp_f32_e32 v120, v120
	v_exp_f32_e32 v121, v121
	s_nop 0
	v_pk_add_f32 v[120:121], v[120:121], 1.0 op_sel_hi:[1,0]
	s_nop 0
	s_nop 0
	v_rcp_f32_e32 v122, v121
	s_nop 0
	v_mul_f32_e32 v119, v119, v122
	s_movk_i32 s2, 0x2c00
	v_rcp_f32_e32 v121, v120
	s_nop 0
	v_mul_f32_e32 v118, v118, v121
	v_pk_mul_f32 v[108:109], v[118:119], v[108:109]
	s_nop 0
	v_cvt_pk_bf16_f32 v107, v108, v109
	v_mov_b64_e32 v[108:109], s[34:35]
	v_mad_i64_i32 v[108:109], s[2:3], v124, s2, v[108:109]
	v_lshl_add_u64 v[108:109], v[130:131], 1, v[108:109]
	global_store_dwordx2 v[108:109], v[106:107], off

; DI unsigned pk2(float a, float b) { f32x2 v; v[0] = a; v[1] = b; return __builtin_bit_cast(unsigned, __builtin_convertvector(v, bf16v2)); }
; DI float siluf_(float x) { return x / (1.f + __expf(-x)); }
; DI void gemm_tile(const GD& g, int pm, int pn, bf16_t* shm) {
;     ...
;         for (int rr = 0; rr < 8; ++rr) {
;           const int row_l = r0 + rr;
;           const float4 gc = *reinterpret_cast<const float4*>(stgw + row_l * 68 + cgp * 4);
;           const float4 vc = *reinterpret_cast<const float4*>(stgw + row_l * 68 + 32 + cgp * 4);
;           const int grow = brow + ai * HALF + wr * 64 + row_l;
;           if (!(first && rr < 2)) {
;             const float a0 = siluf_(bg.x + wg0.x * g2.x + wg1.x * g1.x + wg2.x * gc.x) * (bv.x + wv0.x * v2.x + wv1.x * v1.x + wv2.x * vc.x);
;             const float a1 = siluf_(bg.y + wg0.y * g2.y + wg1.y * g1.y + wg2.y * gc.y) * (bv.y + wv0.y * v2.y + wv1.y * v1.y + wv2.y * vc.y);
;             const float a2 = siluf_(bg.z + wg0.z * g2.z + wg1.z * g1.z + wg2.z * gc.z) * (bv.z + wv0.z * v2.z + wv1.z * v1.z + wv2.z * vc.z);
;             const float a3 = siluf_(bg.w + wg0.w * g2.w + wg1.w * g1.w + wg2.w * gc.w) * (bv.w + wv0.w * v2.w + wv1.w * v1.w + wv2.w * vc.w);
;             u32x2 o2; o2[0] = pk2(a0, a1); o2[1] = pk2(a2, a3);
;             *reinterpret_cast<u32x2*>((bf16_t*)g.C + (long)grow * DFF + fcol) = o2;
;           }
;           if (first && rr < 2) {
;             *reinterpret_cast<float4*>(halo + (size_t)rr * NUP + fcol) = gc; *reinterpret_cast<float4*>(halo + (size_t)rr * NUP + DFF + fcol) = vc;
;           }
.LBB0_542:
	s_or_b64 exec, exec, s[0:1]
	s_waitcnt lgkmcnt(5)
	ds_read_b128 v[118:121], v127 offset:272
	s_waitcnt lgkmcnt(5)
	ds_read_b128 v[106:109], v127 offset:400
	s_waitcnt vmcnt(1) lgkmcnt(5)
	v_pk_fma_f32 v[110:111], v[82:83], v[110:111], v[94:95]
	s_waitcnt vmcnt(0) lgkmcnt(4)
	v_pk_fma_f32 v[98:99], v[2:3], v[98:99], v[14:15]
	s_waitcnt lgkmcnt(3)
	v_pk_fma_f32 v[110:111], v[86:87], v[114:115], v[110:111]
	s_waitcnt lgkmcnt(2)
	v_pk_fma_f32 v[98:99], v[6:7], v[102:103], v[98:99]
	s_waitcnt lgkmcnt(1)
	v_pk_fma_f32 v[110:111], v[90:91], v[118:119], v[110:111]
	s_waitcnt lgkmcnt(0)
	v_pk_fma_f32 v[98:99], v[10:11], v[106:107], v[98:99]
	v_mul_f32_e32 v122, 0xbfb8aa3b, v110
	v_mul_f32_e32 v123, 0xbfb8aa3b, v111
	v_exp_f32_e32 v122, v122
	v_exp_f32_e32 v123, v123
	v_pk_fma_f32 v[100:101], v[4:5], v[100:101], v[16:17]
	v_or_b32_e32 v156, v142, v140
	v_pk_fma_f32 v[100:101], v[8:9], v[104:105], v[100:101]
	v_pk_add_f32 v[122:123], v[122:123], 1.0 op_sel_hi:[1,0]
	v_pk_fma_f32 v[100:101], v[12:13], v[108:109], v[100:101]
	v_or_b32_e32 v124, 2, v156
	s_movk_i32 s2, 0x2c00
	v_rcp_f32_e32 v125, v123
	s_nop 0
	v_mul_f32_e32 v111, v111, v125
	v_lshlrev_b64 v[134:135], 1, v[130:131]
	v_rcp_f32_e32 v123, v122
	s_nop 0
	v_mul_f32_e32 v110, v110, v123
	v_pk_mul_f32 v[98:99], v[110:111], v[98:99]
	v_pk_fma_f32 v[110:111], v[84:85], v[112:113], v[96:97]
	v_cvt_pk_bf16_f32 v98, v98, v99
	v_pk_fma_f32 v[110:111], v[88:89], v[116:117], v[110:111]
	s_nop 0
	v_pk_fma_f32 v[110:111], v[92:93], v[120:121], v[110:111]
	s_nop 0
	v_mul_f32_e32 v112, 0xbfb8aa3b, v110
	v_mul_f32_e32 v113, 0xbfb8aa3b, v111
	v_exp_f32_e32 v112, v112
	v_exp_f32_e32 v113, v113
	s_nop 0
	v_pk_add_f32 v[112:113], v[112:113], 1.0 op_sel_hi:[1,0]
	s_nop 0
	s_nop 0
	v_rcp_f32_e32 v122, v113
	s_nop 0
	v_mul_f32_e32 v111, v111, v122
	v_mov_b64_e32 v[132:133], s[34:35]
	v_rcp_f32_e32 v113, v112
	s_nop 0
	v_mul_f32_e32 v110, v110, v113
	v_pk_mul_f32 v[100:101], v[110:111], v[100:101]
	v_or_b32_e32 v129, 3, v156
	v_cvt_pk_bf16_f32 v99, v100, v101
	v_mad_i64_i32 v[100:101], s[0:1], v124, s2, v[132:133]
	v_lshl_add_u64 v[100:101], v[100:101], 0, v[134:135]
	global_store_dwordx2 v[100:101], v[98:99], off
	ds_read_b128 v[110:113], v127 offset:544
	ds_read_b128 v[122:125], v127 offset:672
	v_pk_fma_f32 v[98:99], v[82:83], v[114:115], v[94:95]
	s_nop 0
	v_pk_fma_f32 v[98:99], v[86:87], v[118:119], v[98:99]
	s_waitcnt lgkmcnt(1)
	v_pk_fma_f32 v[98:99], v[90:91], v[110:111], v[98:99]
	s_nop 0
	v_mul_f32_e32 v100, 0xbfb8aa3b, v98
	v_mul_f32_e32 v101, 0xbfb8aa3b, v99
	v_exp_f32_e32 v100, v100
	v_exp_f32_e32 v101, v101
	s_nop 0
	v_pk_add_f32 v[100:101], v[100:101], 1.0 op_sel_hi:[1,0]
	s_nop 0
	s_nop 0
	v_rcp_f32_e32 v114, v101
	s_nop 0
	v_mul_f32_e32 v99, v99, v114
	s_nop 0
	v_rcp_f32_e32 v101, v100
	s_nop 0
	v_mul_f32_e32 v98, v98, v101
	v_pk_fma_f32 v[100:101], v[2:3], v[102:103], v[14:15]
	s_nop 0
	v_pk_fma_f32 v[100:101], v[6:7], v[106:107], v[100:101]
	s_waitcnt lgkmcnt(0)
	v_pk_fma_f32 v[100:101], v[10:11], v[122:123], v[100:101]
	s_nop 0
	v_pk_mul_f32 v[98:99], v[98:99], v[100:101]
	v_pk_fma_f32 v[100:101], v[84:85], v[116:117], v[96:97]
	v_cvt_pk_bf16_f32 v98, v98, v99
	v_pk_fma_f32 v[100:101], v[88:89], v[120:121], v[100:101]
	s_nop 0
	v_pk_fma_f32 v[100:101], v[92:93], v[112:113], v[100:101]
	s_nop 0
	v_mul_f32_e32 v102, 0xbfb8aa3b, v100
	v_mul_f32_e32 v103, 0xbfb8aa3b, v101
	v_exp_f32_e32 v102, v102
	v_exp_f32_e32 v103, v103
	s_nop 0
	v_pk_add_f32 v[102:103], v[102:103], 1.0 op_sel_hi:[1,0]
	s_nop 0
	s_nop 0
	v_rcp_f32_e32 v114, v103
	s_nop 0
	v_mul_f32_e32 v101, v101, v114
	s_nop 0
	v_rcp_f32_e32 v103, v102
	s_nop 0
	v_mul_f32_e32 v100, v100, v103
	v_pk_fma_f32 v[102:103], v[4:5], v[104:105], v[16:17]
	s_nop 0
	v_pk_fma_f32 v[102:103], v[8:9], v[108:109], v[102:103]
	s_nop 0
	v_pk_fma_f32 v[102:103], v[12:13], v[124:125], v[102:103]
	s_nop 0
	v_pk_mul_f32 v[100:101], v[100:101], v[102:103]
	s_nop 0
	v_cvt_pk_bf16_f32 v99, v100, v101
	v_mad_i64_i32 v[100:101], s[0:1], v129, s2, v[132:133]
	v_lshl_add_u64 v[100:101], v[100:101], 0, v[134:135]
	global_store_dwordx2 v[100:101], v[98:99], off
	ds_read_b128 v[114:117], v127 offset:816
	ds_read_b128 v[102:105], v127 offset:944
	v_pk_fma_f32 v[98:99], v[82:83], v[118:119], v[94:95]
	v_or_b32_e32 v129, 4, v156
	v_pk_fma_f32 v[98:99], v[86:87], v[110:111], v[98:99]
	v_pk_fma_f32 v[110:111], v[82:83], v[110:111], v[94:95]
	s_waitcnt lgkmcnt(1)
	v_pk_fma_f32 v[98:99], v[90:91], v[114:115], v[98:99]
	v_pk_fma_f32 v[110:111], v[86:87], v[114:115], v[110:111]
	v_mul_f32_e32 v100, 0xbfb8aa3b, v98
	v_mul_f32_e32 v101, 0xbfb8aa3b, v99
	v_exp_f32_e32 v100, v100
	v_exp_f32_e32 v101, v101
	s_nop 0
	v_pk_add_f32 v[100:101], v[100:101], 1.0 op_sel_hi:[1,0]
	s_nop 0
	s_nop 0
	v_rcp_f32_e32 v118, v101
	s_nop 0
	v_mul_f32_e32 v99, v99, v118
	s_nop 0
	v_rcp_f32_e32 v101, v100
	s_nop 0
	v_mul_f32_e32 v98, v98, v101
	v_pk_fma_f32 v[100:101], v[2:3], v[106:107], v[14:15]
	s_nop 0
	v_pk_fma_f32 v[100:101], v[6:7], v[122:123], v[100:101]
	s_waitcnt lgkmcnt(0)
; DI unsigned pk2(float a, float b) { f32x2 v; v[0] = a; v[1] = b; return __builtin_bit_cast(unsigned, __builtin_convertvector(v, bf16v2)); }
; DI float siluf_(float x) { return x / (1.f + __expf(-x)); }
; DI void gemm_tile(const GD& g, int pm, int pn, bf16_t* shm) {
;     ...
;         for (int rr = 0; rr < 8; ++rr) {
;           const int row_l = r0 + rr;
;           const float4 gc = *reinterpret_cast<const float4*>(stgw + row_l * 68 + cgp * 4);
;           const float4 vc = *reinterpret_cast<const float4*>(stgw + row_l * 68 + 32 + cgp * 4);
;           const int grow = brow + ai * HALF + wr * 64 + row_l;
;           if (!(first && rr < 2)) {
;             const float a0 = siluf_(bg.x + wg0.x * g2.x + wg1.x * g1.x + wg2.x * gc.x) * (bv.x + wv0.x * v2.x + wv1.x * v1.x + wv2.x * vc.x);
;             const float a1 = siluf_(bg.y + wg0.y * g2.y + wg1.y * g1.y + wg2.y * gc.y) * (bv.y + wv0.y * v2.y + wv1.y * v1.y + wv2.y * vc.y);
;             const float a2 = siluf_(bg.z + wg0.z * g2.z + wg1.z * g1.z + wg2.z * gc.z) * (bv.z + wv0.z * v2.z + wv1.z * v1.z + wv2.z * vc.z);
;             const float a3 = siluf_(bg.w + wg0.w * g2.w + wg1.w * g1.w + wg2.w * gc.w) * (bv.w + wv0.w * v2.w + wv1.w * v1.w + wv2.w * vc.w);
;             u32x2 o2; o2[0] = pk2(a0, a1); o2[1] = pk2(a2, a3);
;             *reinterpret_cast<u32x2*>((bf16_t*)g.C + (long)grow * DFF + fcol) = o2;
;           }
;           if (first && rr < 2) {
;             *reinterpret_cast<float4*>(halo + (size_t)rr * NUP + fcol) = gc; *reinterpret_cast<float4*>(halo + (size_t)rr * NUP + DFF + fcol) = vc;
;           }
;           if (ai == 1 && wr == 1 && rs == 7 && rr >= 6) {
;             *reinterpret_cast<float4*>(halo + (size_t)(rr - 4) * NUP + fcol) = gc; *reinterpret_cast<float4*>(halo + (size_t)(rr - 4) * NUP + DFF + fcol) = vc;
;           }
;           if (ai == 0 && wr == 1 && rs == 7 && rr >= 6) {
;             *reinterpret_cast<float4*>(carry + wc * 128 + (rr - 6) * 64 + cgp * 4) = gc; *reinterpret_cast<float4*>(carry + wc * 128 + (rr - 6) * 64 + 32 + cgp * 4) = vc;
;           }
	v_pk_fma_f32 v[100:101], v[10:11], v[102:103], v[100:101]
	s_nop 0
	v_pk_mul_f32 v[98:99], v[98:99], v[100:101]
	v_pk_fma_f32 v[100:101], v[84:85], v[120:121], v[96:97]
	v_cvt_pk_bf16_f32 v98, v98, v99
	v_pk_fma_f32 v[100:101], v[88:89], v[112:113], v[100:101]
	v_pk_fma_f32 v[112:113], v[84:85], v[112:113], v[96:97]
	v_pk_fma_f32 v[100:101], v[92:93], v[116:117], v[100:101]
	v_pk_fma_f32 v[112:113], v[88:89], v[116:117], v[112:113]
	v_mul_f32_e32 v106, 0xbfb8aa3b, v100
	v_mul_f32_e32 v107, 0xbfb8aa3b, v101
	v_exp_f32_e32 v106, v106
	v_exp_f32_e32 v107, v107
	s_nop 0
	v_pk_add_f32 v[106:107], v[106:107], 1.0 op_sel_hi:[1,0]
	s_nop 0
	s_nop 0
	v_rcp_f32_e32 v118, v107
	s_nop 0
	v_mul_f32_e32 v101, v101, v118
	s_nop 0
	v_rcp_f32_e32 v107, v106
	s_nop 0
	v_mul_f32_e32 v100, v100, v107
	v_pk_fma_f32 v[106:107], v[4:5], v[108:109], v[16:17]
	v_pk_fma_f32 v[118:119], v[2:3], v[122:123], v[14:15]
	v_pk_fma_f32 v[106:107], v[8:9], v[124:125], v[106:107]
	v_pk_fma_f32 v[118:119], v[6:7], v[102:103], v[118:119]
	v_pk_fma_f32 v[106:107], v[12:13], v[104:105], v[106:107]
	v_pk_fma_f32 v[102:103], v[2:3], v[102:103], v[14:15]
	v_pk_mul_f32 v[100:101], v[100:101], v[106:107]
	s_nop 0
	v_cvt_pk_bf16_f32 v99, v100, v101
	v_mad_i64_i32 v[100:101], s[0:1], v129, s2, v[132:133]
	v_lshl_add_u64 v[100:101], v[100:101], 0, v[134:135]
	global_store_dwordx2 v[100:101], v[98:99], off
	v_or_b32_e32 v98, 5, v156
	v_mad_i64_i32 v[98:99], s[0:1], v98, s2, v[132:133]
	v_lshl_add_u64 v[136:137], v[98:99], 0, v[134:135]
	v_add_u32_e32 v98, 0x550, v128
	v_add3_u32 v157, v141, v98, v126
	ds_read_b128 v[106:109], v127 offset:1088
	ds_read_b128 v[98:101], v127 offset:1216
	s_waitcnt lgkmcnt(1)
	v_pk_fma_f32 v[110:111], v[90:91], v[106:107], v[110:111]
	s_nop 0
	v_mul_f32_e32 v120, 0xbfb8aa3b, v110
	v_mul_f32_e32 v121, 0xbfb8aa3b, v111
	v_exp_f32_e32 v120, v120
	v_exp_f32_e32 v121, v121
	s_waitcnt lgkmcnt(0)
	v_pk_fma_f32 v[118:119], v[10:11], v[98:99], v[118:119]
	v_pk_fma_f32 v[112:113], v[92:93], v[108:109], v[112:113]
	v_pk_fma_f32 v[102:103], v[6:7], v[98:99], v[102:103]
	v_pk_add_f32 v[120:121], v[120:121], 1.0 op_sel_hi:[1,0]
	s_nop 0
	s_nop 0
	v_rcp_f32_e32 v122, v121
	s_nop 0
	v_mul_f32_e32 v111, v111, v122
	s_nop 0
	v_rcp_f32_e32 v121, v120
	s_nop 0
	v_mul_f32_e32 v110, v110, v121
	v_pk_mul_f32 v[110:111], v[110:111], v[118:119]
	v_pk_fma_f32 v[122:123], v[4:5], v[124:125], v[16:17]
	v_cvt_pk_bf16_f32 v110, v110, v111
	v_mul_f32_e32 v111, 0xbfb8aa3b, v112
	v_exp_f32_e32 v124, v111
	v_mul_f32_e32 v111, 0xbfb8aa3b, v113
	v_exp_f32_e32 v125, v111
	v_pk_fma_f32 v[122:123], v[8:9], v[104:105], v[122:123]
	ds_read_b128 v[126:129], v157
	ds_read_b128 v[118:121], v157 offset:128
	v_pk_fma_f32 v[122:123], v[12:13], v[100:101], v[122:123]
	v_pk_add_f32 v[124:125], v[124:125], 1.0 op_sel_hi:[1,0]
	v_pk_fma_f32 v[104:105], v[4:5], v[104:105], v[16:17]
	s_waitcnt lgkmcnt(0)
	v_pk_fma_f32 v[102:103], v[10:11], v[118:119], v[102:103]
	v_pk_fma_f32 v[104:105], v[8:9], v[100:101], v[104:105]
	v_rcp_f32_e32 v111, v125
	s_nop 0
	v_mul_f32_e32 v113, v113, v111
	v_pk_fma_f32 v[104:105], v[12:13], v[120:121], v[104:105]
	v_rcp_f32_e32 v111, v124
	s_nop 0
	v_mul_f32_e32 v112, v112, v111
	v_pk_mul_f32 v[112:113], v[112:113], v[122:123]
	v_or_b32_e32 v122, 6, v156
	v_cvt_pk_bf16_f32 v111, v112, v113
	global_store_dwordx2 v[136:137], v[110:111], off
	v_pk_fma_f32 v[110:111], v[82:83], v[114:115], v[94:95]
	s_nop 0
	v_pk_fma_f32 v[110:111], v[86:87], v[106:107], v[110:111]
	s_nop 0
	v_pk_fma_f32 v[110:111], v[90:91], v[126:127], v[110:111]
	s_nop 0
	v_mul_f32_e32 v112, 0xbfb8aa3b, v110
	v_mul_f32_e32 v113, 0xbfb8aa3b, v111
	v_exp_f32_e32 v112, v112
	v_exp_f32_e32 v113, v113
	s_nop 0
	v_pk_add_f32 v[112:113], v[112:113], 1.0 op_sel_hi:[1,0]
	s_nop 0
	s_nop 0
	v_rcp_f32_e32 v114, v113
	s_nop 0
	v_mul_f32_e32 v111, v111, v114
	s_nop 0
	v_rcp_f32_e32 v113, v112
	s_nop 0
	v_mul_f32_e32 v110, v110, v113
	v_pk_mul_f32 v[102:103], v[110:111], v[102:103]
	v_pk_fma_f32 v[110:111], v[84:85], v[116:117], v[96:97]
	v_cvt_pk_bf16_f32 v102, v102, v103
	v_pk_fma_f32 v[110:111], v[88:89], v[108:109], v[110:111]
	s_nop 0
	v_pk_fma_f32 v[110:111], v[92:93], v[128:129], v[110:111]
	s_nop 0
	v_mul_f32_e32 v112, 0xbfb8aa3b, v110
	v_mul_f32_e32 v113, 0xbfb8aa3b, v111
	v_exp_f32_e32 v112, v112
	v_exp_f32_e32 v113, v113
	s_nop 0
	v_pk_add_f32 v[112:113], v[112:113], 1.0 op_sel_hi:[1,0]
	s_nop 0
	s_nop 0
	v_rcp_f32_e32 v114, v113
	s_nop 0
	v_mul_f32_e32 v111, v111, v114
	s_nop 0
	v_rcp_f32_e32 v113, v112
	s_nop 0
	v_mul_f32_e32 v110, v110, v113
	v_pk_mul_f32 v[104:105], v[110:111], v[104:105]
	v_lshl_add_u32 v114, v146, 2, v149
	v_cvt_pk_bf16_f32 v103, v104, v105
	v_mad_i64_i32 v[104:105], s[0:1], v122, s2, v[132:133]
	v_lshl_add_u64 v[104:105], v[104:105], 0, v[134:135]
	global_store_dwordx2 v[104:105], v[102:103], off
	s_and_saveexec_b64 s[0:1], s[50:51]
	s_cbranch_execz .LBB0_544
	ds_write_b128 v114, v[126:129]
	ds_write_b128 v114, v[118:121] offset:128
.LBB0_544:
	s_or_b64 exec, exec, s[0:1]
	ds_read_b128 v[110:113], v157 offset:272
	ds_read_b128 v[102:105], v157 offset:400
	v_pk_fma_f32 v[82:83], v[82:83], v[106:107], v[94:95]
	v_pk_fma_f32 v[2:3], v[2:3], v[98:99], v[14:15]
	v_pk_fma_f32 v[82:83], v[86:87], v[126:127], v[82:83]
	v_pk_fma_f32 v[2:3], v[6:7], v[118:119], v[2:3]
	s_waitcnt lgkmcnt(1)
	v_pk_fma_f32 v[82:83], v[90:91], v[110:111], v[82:83]
	v_pk_fma_f32 v[6:7], v[84:85], v[108:109], v[96:97]
	v_mul_f32_e32 v86, 0xbfb8aa3b, v82
	v_mul_f32_e32 v87, 0xbfb8aa3b, v83
	v_exp_f32_e32 v86, v86
	v_exp_f32_e32 v87, v87
	v_pk_fma_f32 v[6:7], v[88:89], v[128:129], v[6:7]
	s_waitcnt lgkmcnt(0)
	v_pk_fma_f32 v[2:3], v[10:11], v[102:103], v[2:3]
	v_pk_fma_f32 v[6:7], v[92:93], v[112:113], v[6:7]
	v_pk_add_f32 v[86:87], v[86:87], 1.0 op_sel_hi:[1,0]
	v_mul_f32_e32 v10, 0xbfb8aa3b, v6
	v_mul_f32_e32 v11, 0xbfb8aa3b, v7
	v_exp_f32_e32 v10, v10
	v_exp_f32_e32 v11, v11
	v_rcp_f32_e32 v90, v87
	s_nop 0
	v_mul_f32_e32 v83, v83, v90
	v_pk_add_f32 v[10:11], v[10:11], 1.0 op_sel_hi:[1,0]
	v_pk_fma_f32 v[4:5], v[4:5], v[100:101], v[16:17]
	v_rcp_f32_e32 v87, v86
	s_nop 0
	v_mul_f32_e32 v82, v82, v87
	v_pk_mul_f32 v[2:3], v[82:83], v[2:3]
	v_rcp_f32_e32 v14, v11
	s_nop 0
	v_mul_f32_e32 v7, v7, v14
	v_pk_fma_f32 v[4:5], v[8:9], v[120:121], v[4:5]
	v_or3_b32 v115, v142, v140, 7
	v_pk_fma_f32 v[4:5], v[12:13], v[104:105], v[4:5]
	v_rcp_f32_e32 v11, v10
	s_nop 0
	v_mul_f32_e32 v6, v6, v11
	v_pk_mul_f32 v[4:5], v[6:7], v[4:5]
	v_cvt_pk_bf16_f32 v2, v2, v3
	v_cvt_pk_bf16_f32 v3, v4, v5
	v_mov_b64_e32 v[4:5], s[34:35]
	s_movk_i32 s0, 0x2c00
	v_mad_i64_i32 v[4:5], s[0:1], v115, s0, v[4:5]
	v_lshl_add_u64 v[4:5], v[130:131], 1, v[4:5]
	global_store_dwordx2 v[4:5], v[2:3], off
	s_and_saveexec_b64 s[0:1], s[50:51]
	s_cbranch_execz .LBB0_546
	ds_write_b128 v114, v[110:113] offset:256
	ds_write_b128 v114, v[102:105] offset:384

; DI unsigned pk2(float a, float b) { f32x2 v; v[0] = a; v[1] = b; return __builtin_bit_cast(unsigned, __builtin_convertvector(v, bf16v2)); }
; DI float shx_(float v, int m) { return __int_as_float(__builtin_amdgcn_ds_bpermute((lane_pinned_() ^ m) << 2, __float_as_int(v))); }
; DI int shx_(int v, int m) { return __builtin_amdgcn_ds_bpermute((lane_pinned_() ^ m) << 2, v); }
; DI void gemm_tile(const GD& g, int pm, int pn, bf16_t* shm) {
;     ...
;         for (int q = 0; q < 4; ++q) {
;           const int row_l = (pb8 * 4 + q) * 4 + (lane >> 4);
;           float4 v = *reinterpret_cast<const float4*>(stgw + row_l * 68 + c4);
;           const int grow = brow + ai * HALF + wr * 64 + row_l;
;           if (g.epi == 0) {
;             if (g.rowscale) {
;               const float rr = rsc[ai * HALF + wr * 64 + row_l];
;               v.x *= rr; v.y *= rr; v.z *= rr; v.w *= rr;
;             }
;             u32x2 o2; o2[0] = pk2(v.x, v.y); o2[1] = pk2(v.z, v.w);
;             *reinterpret_cast<u32x2*>((bf16_t*)g.C + (long)grow * ldc + gcol) = o2;
;           } else if (g.epi == 2) {
;             const float rr = rsc[ai * HALF + wr * 64 + row_l];
;             v.x *= rr; v.y *= rr; v.z *= rr; v.w *= rr;
;             *reinterpret_cast<float4*>((float*)g.C + (long)grow * ldc + gcol) = v;
;           } else {
;             float4 x = xs[q];
;             x.x += v.x; x.y += v.y; x.z += v.z; x.w += v.w;
;             *reinterpret_cast<float4*>((float*)g.C + (long)grow * ldc + gcol) = x;
;             if (g.gnext) {
;               u32x2 o2; o2[0] = pk2(x.x * gn.x, x.y * gn.y); o2[1] = pk2(x.z * gn.z, x.w * gn.w);
;               *reinterpret_cast<u32x2*>(g.hbout + (long)grow * DM + gcol) = o2;
;               float sq = (x.x * x.x + x.y * x.y) + (x.z * x.z + x.w * x.w);
;               sq += shx_(sq, 1); sq += shx_(sq, 2); sq += shx_(sq, 4); sq += shx_(sq, 8);
;               if ((lane & 15) == 0) g.ss[(long)grow * 32 + pn * 4 + wc] = sq;
.LBB0_625:
	v_mad_u64_u32 v[104:105], s[2:3], v96, s78, 0
	v_mov_b32_e32 v0, v105
	v_mad_u64_u32 v[106:107], s[2:3], v97, s78, v[0:1]
	v_mov_b32_e32 v105, v106
	v_lshl_add_u64 v[104:105], v[104:105], 2, s[34:35]
	s_waitcnt vmcnt(0) lgkmcnt(0)
	v_pk_add_f32 v[90:91], v[14:15], v[86:87]
	v_pk_add_f32 v[92:93], v[16:17], v[88:89]
	v_lshl_add_u64 v[104:105], v[94:95], 2, v[104:105]
	s_cmp_eq_u64 s[80:81], 0
	global_store_dwordx4 v[104:105], v[90:93], off
	s_cbranch_scc1 .LBB0_629
	v_pk_mul_f32 v[104:105], v[82:83], v[90:91]
	v_pk_mul_f32 v[106:107], v[84:85], v[92:93]
	v_cvt_pk_bf16_f32 v104, v104, v105
	v_cvt_pk_bf16_f32 v105, v106, v107
	v_lshlrev_b64 v[106:107], 12, v[96:97]
	v_pk_mul_f32 v[90:91], v[90:91], v[90:91]
	v_pk_mul_f32 v[92:93], v[92:93], v[92:93]
	v_lshl_add_u64 v[106:107], s[20:21], 0, v[106:107]
	v_add_f32_e32 v0, v92, v93
	v_add_f32_e32 v90, v90, v91
	v_lshl_add_u64 v[106:107], v[94:95], 1, v[106:107]
	v_add_f32_e32 v0, v90, v0
	v_mov_b32_e32 v90, v208
	global_store_dwordx2 v[106:107], v[104:105], off
	s_nop 0
	v_lshlrev_b32_e32 v90, 2, v90
	v_xor_b32_e32 v90, 4, v90
	ds_bpermute_b32 v90, v90, v0
	s_waitcnt lgkmcnt(0)
	v_add_f32_e32 v0, v0, v90
	v_mov_b32_e32 v90, v208
	s_nop 0
	v_lshlrev_b32_e32 v90, 2, v90
	v_xor_b32_e32 v90, 8, v90
	ds_bpermute_b32 v90, v90, v0
	s_waitcnt lgkmcnt(0)
	v_add_f32_e32 v0, v0, v90
	v_mov_b32_e32 v90, v208
	s_nop 0
	v_lshlrev_b32_e32 v90, 2, v90
	v_xor_b32_e32 v90, 16, v90
	ds_bpermute_b32 v90, v90, v0
	s_waitcnt lgkmcnt(0)
	v_add_f32_e32 v90, v0, v90
	v_mov_b32_e32 v0, v208
	s_nop 0
	v_lshlrev_b32_e32 v0, 2, v0
	v_xor_b32_e32 v0, 32, v0
	ds_bpermute_b32 v91, v0, v90
	s_and_saveexec_b64 s[2:3], s[4:5]
	s_cbranch_execz .LBB0_628
	v_lshlrev_b64 v[92:93], 7, v[96:97]
	v_lshl_add_u64 v[92:93], s[42:43], 0, v[92:93]
	v_lshl_add_u64 v[92:93], s[0:1], 2, v[92:93]
	v_lshlrev_b32_e32 v0, 2, v139
	v_lshl_add_u64 v[92:93], v[92:93], 0, v[0:1]
	s_waitcnt lgkmcnt(0)
	v_add_f32_e32 v0, v90, v91
	global_store_dword v[92:93], v0, off

; DI unsigned pk2(float a, float b) { f32x2 v; v[0] = a; v[1] = b; return __builtin_bit_cast(unsigned, __builtin_convertvector(v, bf16v2)); }
; DI float shx_(float v, int m) { return __int_as_float(__builtin_amdgcn_ds_bpermute((lane_pinned_() ^ m) << 2, __float_as_int(v))); }
; DI int shx_(int v, int m) { return __builtin_amdgcn_ds_bpermute((lane_pinned_() ^ m) << 2, v); }
; DI void gemm_tile(const GD& g, int pm, int pn, bf16_t* shm) {
;     ...
;         for (int q = 0; q < 4; ++q) {
;           const int row_l = (pb8 * 4 + q) * 4 + (lane >> 4);
;           float4 v = *reinterpret_cast<const float4*>(stgw + row_l * 68 + c4);
;           const int grow = brow + ai * HALF + wr * 64 + row_l;
;           if (g.epi == 0) {
;             if (g.rowscale) {
;               const float rr = rsc[ai * HALF + wr * 64 + row_l];
;               v.x *= rr; v.y *= rr; v.z *= rr; v.w *= rr;
;             }
;             u32x2 o2; o2[0] = pk2(v.x, v.y); o2[1] = pk2(v.z, v.w);
;             *reinterpret_cast<u32x2*>((bf16_t*)g.C + (long)grow * ldc + gcol) = o2;
;           } else if (g.epi == 2) {
;             const float rr = rsc[ai * HALF + wr * 64 + row_l];
;             v.x *= rr; v.y *= rr; v.z *= rr; v.w *= rr;
;             *reinterpret_cast<float4*>((float*)g.C + (long)grow * ldc + gcol) = v;
;           } else {
;             float4 x = xs[q];
;             x.x += v.x; x.y += v.y; x.z += v.z; x.w += v.w;
;             *reinterpret_cast<float4*>((float*)g.C + (long)grow * ldc + gcol) = x;
;             if (g.gnext) {
;               u32x2 o2; o2[0] = pk2(x.x * gn.x, x.y * gn.y); o2[1] = pk2(x.z * gn.z, x.w * gn.w);
;               *reinterpret_cast<u32x2*>(g.hbout + (long)grow * DM + gcol) = o2;
;               float sq = (x.x * x.x + x.y * x.y) + (x.z * x.z + x.w * x.w);
;               sq += shx_(sq, 1); sq += shx_(sq, 2); sq += shx_(sq, 4); sq += shx_(sq, 8);
;               if ((lane & 15) == 0) g.ss[(long)grow * 32 + pn * 4 + wc] = sq;
.LBB0_641:
	v_mad_u64_u32 v[104:105], s[2:3], v96, s78, 0
	v_mov_b32_e32 v0, v105
	v_mad_u64_u32 v[106:107], s[2:3], v97, s78, v[0:1]
	v_mov_b32_e32 v105, v106
	v_lshl_add_u64 v[104:105], v[104:105], 2, s[34:35]
	s_waitcnt lgkmcnt(0)
	v_pk_add_f32 v[90:91], v[6:7], v[86:87]
	v_pk_add_f32 v[92:93], v[8:9], v[88:89]
	v_lshl_add_u64 v[104:105], v[94:95], 2, v[104:105]
	s_cmp_eq_u64 s[80:81], 0
	global_store_dwordx4 v[104:105], v[90:93], off
	s_cbranch_scc1 .LBB0_645
	v_pk_mul_f32 v[104:105], v[82:83], v[90:91]
	v_pk_mul_f32 v[106:107], v[84:85], v[92:93]
	v_cvt_pk_bf16_f32 v104, v104, v105
	v_cvt_pk_bf16_f32 v105, v106, v107
	v_lshlrev_b64 v[106:107], 12, v[96:97]
	v_pk_mul_f32 v[90:91], v[90:91], v[90:91]
	v_pk_mul_f32 v[92:93], v[92:93], v[92:93]
	v_lshl_add_u64 v[106:107], s[20:21], 0, v[106:107]
	v_add_f32_e32 v0, v92, v93
	v_add_f32_e32 v90, v90, v91
	v_lshl_add_u64 v[106:107], v[94:95], 1, v[106:107]
	v_add_f32_e32 v0, v90, v0
	v_mov_b32_e32 v90, v208
	global_store_dwordx2 v[106:107], v[104:105], off
	s_nop 0
	v_lshlrev_b32_e32 v90, 2, v90
	v_xor_b32_e32 v90, 4, v90
	ds_bpermute_b32 v90, v90, v0
	s_waitcnt lgkmcnt(0)
	v_add_f32_e32 v0, v0, v90
	v_mov_b32_e32 v90, v208
	s_nop 0
	v_lshlrev_b32_e32 v90, 2, v90
	v_xor_b32_e32 v90, 8, v90
	ds_bpermute_b32 v90, v90, v0
	s_waitcnt lgkmcnt(0)
	v_add_f32_e32 v0, v0, v90
	v_mov_b32_e32 v90, v208
	s_nop 0
	v_lshlrev_b32_e32 v90, 2, v90
	v_xor_b32_e32 v90, 16, v90
	ds_bpermute_b32 v90, v90, v0
	s_waitcnt lgkmcnt(0)
	v_add_f32_e32 v90, v0, v90
	v_mov_b32_e32 v0, v208
	s_nop 0
	v_lshlrev_b32_e32 v0, 2, v0
	v_xor_b32_e32 v0, 32, v0
	ds_bpermute_b32 v91, v0, v90
	s_and_saveexec_b64 s[2:3], s[4:5]
	s_cbranch_execz .LBB0_644
	v_lshlrev_b64 v[92:93], 7, v[96:97]
	v_lshl_add_u64 v[92:93], s[42:43], 0, v[92:93]
	v_lshl_add_u64 v[92:93], s[0:1], 2, v[92:93]
	v_lshlrev_b32_e32 v0, 2, v139
	v_lshl_add_u64 v[92:93], v[92:93], 0, v[0:1]
	s_waitcnt lgkmcnt(0)
	v_add_f32_e32 v0, v90, v91
	global_store_dword v[92:93], v0, off

; DI unsigned pk2(float a, float b) { f32x2 v; v[0] = a; v[1] = b; return __builtin_bit_cast(unsigned, __builtin_convertvector(v, bf16v2)); }
; DI float shx_(float v, int m) { return __int_as_float(__builtin_amdgcn_ds_bpermute((lane_pinned_() ^ m) << 2, __float_as_int(v))); }
; DI int shx_(int v, int m) { return __builtin_amdgcn_ds_bpermute((lane_pinned_() ^ m) << 2, v); }
; DI void gemm_tile(const GD& g, int pm, int pn, bf16_t* shm) {
;     ...
;         for (int q = 0; q < 4; ++q) {
;           const int row_l = (pb8 * 4 + q) * 4 + (lane >> 4);
;           float4 v = *reinterpret_cast<const float4*>(stgw + row_l * 68 + c4);
;           const int grow = brow + ai * HALF + wr * 64 + row_l;
;           if (g.epi == 0) {
;             if (g.rowscale) {
;               const float rr = rsc[ai * HALF + wr * 64 + row_l];
;               v.x *= rr; v.y *= rr; v.z *= rr; v.w *= rr;
;             }
;             u32x2 o2; o2[0] = pk2(v.x, v.y); o2[1] = pk2(v.z, v.w);
;             *reinterpret_cast<u32x2*>((bf16_t*)g.C + (long)grow * ldc + gcol) = o2;
;           } else if (g.epi == 2) {
;             const float rr = rsc[ai * HALF + wr * 64 + row_l];
;             v.x *= rr; v.y *= rr; v.z *= rr; v.w *= rr;
;             *reinterpret_cast<float4*>((float*)g.C + (long)grow * ldc + gcol) = v;
;           } else {
;             float4 x = xs[q];
;             x.x += v.x; x.y += v.y; x.z += v.z; x.w += v.w;
;             *reinterpret_cast<float4*>((float*)g.C + (long)grow * ldc + gcol) = x;
;             if (g.gnext) {
;               u32x2 o2; o2[0] = pk2(x.x * gn.x, x.y * gn.y); o2[1] = pk2(x.z * gn.z, x.w * gn.w);
;               *reinterpret_cast<u32x2*>(g.hbout + (long)grow * DM + gcol) = o2;
;               float sq = (x.x * x.x + x.y * x.y) + (x.z * x.z + x.w * x.w);
;               sq += shx_(sq, 1); sq += shx_(sq, 2); sq += shx_(sq, 4); sq += shx_(sq, 8);
;               if ((lane & 15) == 0) g.ss[(long)grow * 32 + pn * 4 + wc] = sq;
.LBB0_657:
	v_mad_u64_u32 v[104:105], s[2:3], v96, s78, 0
	v_mov_b32_e32 v0, v105
	v_mad_u64_u32 v[106:107], s[2:3], v97, s78, v[0:1]
	v_mov_b32_e32 v105, v106
	v_lshl_add_u64 v[104:105], v[104:105], 2, s[34:35]
	s_waitcnt lgkmcnt(0)
	v_pk_add_f32 v[90:91], v[10:11], v[86:87]
	v_pk_add_f32 v[92:93], v[12:13], v[88:89]
	v_lshl_add_u64 v[104:105], v[94:95], 2, v[104:105]
	s_cmp_eq_u64 s[80:81], 0
	global_store_dwordx4 v[104:105], v[90:93], off
	s_cbranch_scc1 .LBB0_661
	v_pk_mul_f32 v[104:105], v[82:83], v[90:91]
	v_pk_mul_f32 v[106:107], v[84:85], v[92:93]
	v_cvt_pk_bf16_f32 v104, v104, v105
	v_cvt_pk_bf16_f32 v105, v106, v107
	v_lshlrev_b64 v[106:107], 12, v[96:97]
	v_pk_mul_f32 v[90:91], v[90:91], v[90:91]
	v_pk_mul_f32 v[92:93], v[92:93], v[92:93]
	v_lshl_add_u64 v[106:107], s[20:21], 0, v[106:107]
	v_add_f32_e32 v0, v92, v93
	v_add_f32_e32 v90, v90, v91
	v_lshl_add_u64 v[106:107], v[94:95], 1, v[106:107]
	v_add_f32_e32 v0, v90, v0
	v_mov_b32_e32 v90, v208
	global_store_dwordx2 v[106:107], v[104:105], off
	s_nop 0
	v_lshlrev_b32_e32 v90, 2, v90
	v_xor_b32_e32 v90, 4, v90
	ds_bpermute_b32 v90, v90, v0
	s_waitcnt lgkmcnt(0)
	v_add_f32_e32 v0, v0, v90
	v_mov_b32_e32 v90, v208
	s_nop 0
	v_lshlrev_b32_e32 v90, 2, v90
	v_xor_b32_e32 v90, 8, v90
	ds_bpermute_b32 v90, v90, v0
	s_waitcnt lgkmcnt(0)
	v_add_f32_e32 v0, v0, v90
	v_mov_b32_e32 v90, v208
	s_nop 0
	v_lshlrev_b32_e32 v90, 2, v90
	v_xor_b32_e32 v90, 16, v90
	ds_bpermute_b32 v90, v90, v0
	s_waitcnt lgkmcnt(0)
	v_add_f32_e32 v90, v0, v90
	v_mov_b32_e32 v0, v208
	s_nop 0
	v_lshlrev_b32_e32 v0, 2, v0
	v_xor_b32_e32 v0, 32, v0
	ds_bpermute_b32 v91, v0, v90
	s_and_saveexec_b64 s[2:3], s[4:5]
	s_cbranch_execz .LBB0_660
	v_lshlrev_b64 v[92:93], 7, v[96:97]
	v_lshl_add_u64 v[92:93], s[42:43], 0, v[92:93]
	v_lshl_add_u64 v[92:93], s[0:1], 2, v[92:93]
	v_lshlrev_b32_e32 v0, 2, v139
	v_lshl_add_u64 v[92:93], v[92:93], 0, v[0:1]
	s_waitcnt lgkmcnt(0)
	v_add_f32_e32 v0, v90, v91
	global_store_dword v[92:93], v0, off

; DI unsigned pk2(float a, float b) { f32x2 v; v[0] = a; v[1] = b; return __builtin_bit_cast(unsigned, __builtin_convertvector(v, bf16v2)); }
; DI float shx_(float v, int m) { return __int_as_float(__builtin_amdgcn_ds_bpermute((lane_pinned_() ^ m) << 2, __float_as_int(v))); }
; DI int shx_(int v, int m) { return __builtin_amdgcn_ds_bpermute((lane_pinned_() ^ m) << 2, v); }
; DI void gemm_tile(const GD& g, int pm, int pn, bf16_t* shm) {
;     ...
;         for (int q = 0; q < 4; ++q) {
;           const int row_l = (pb8 * 4 + q) * 4 + (lane >> 4);
;           float4 v = *reinterpret_cast<const float4*>(stgw + row_l * 68 + c4);
;           const int grow = brow + ai * HALF + wr * 64 + row_l;
;           if (g.epi == 0) {
;             if (g.rowscale) {
;               const float rr = rsc[ai * HALF + wr * 64 + row_l];
;               v.x *= rr; v.y *= rr; v.z *= rr; v.w *= rr;
;             }
;             u32x2 o2; o2[0] = pk2(v.x, v.y); o2[1] = pk2(v.z, v.w);
;             *reinterpret_cast<u32x2*>((bf16_t*)g.C + (long)grow * ldc + gcol) = o2;
;           } else if (g.epi == 2) {
;             const float rr = rsc[ai * HALF + wr * 64 + row_l];
;             v.x *= rr; v.y *= rr; v.z *= rr; v.w *= rr;
;             *reinterpret_cast<float4*>((float*)g.C + (long)grow * ldc + gcol) = v;
;           } else {
;             float4 x = xs[q];
;             x.x += v.x; x.y += v.y; x.z += v.z; x.w += v.w;
;             *reinterpret_cast<float4*>((float*)g.C + (long)grow * ldc + gcol) = x;
;             if (g.gnext) {
;               u32x2 o2; o2[0] = pk2(x.x * gn.x, x.y * gn.y); o2[1] = pk2(x.z * gn.z, x.w * gn.w);
;               *reinterpret_cast<u32x2*>(g.hbout + (long)grow * DM + gcol) = o2;
;               float sq = (x.x * x.x + x.y * x.y) + (x.z * x.z + x.w * x.w);
;               sq += shx_(sq, 1); sq += shx_(sq, 2); sq += shx_(sq, 4); sq += shx_(sq, 8);
;               if ((lane & 15) == 0) g.ss[(long)grow * 32 + pn * 4 + wc] = sq;
.LBB0_673:
	v_mad_u64_u32 v[104:105], s[2:3], v96, s78, 0
	v_mov_b32_e32 v0, v105
	v_mad_u64_u32 v[106:107], s[2:3], v97, s78, v[0:1]
	v_mov_b32_e32 v105, v106
	v_lshl_add_u64 v[104:105], v[104:105], 2, s[34:35]
	s_waitcnt lgkmcnt(0)
	v_pk_add_f32 v[90:91], v[2:3], v[86:87]
	v_pk_add_f32 v[92:93], v[4:5], v[88:89]
	v_lshl_add_u64 v[104:105], v[94:95], 2, v[104:105]
	s_cmp_eq_u64 s[80:81], 0
	global_store_dwordx4 v[104:105], v[90:93], off
	s_cbranch_scc1 .LBB0_677
	v_pk_mul_f32 v[104:105], v[82:83], v[90:91]
	v_pk_mul_f32 v[106:107], v[84:85], v[92:93]
	v_cvt_pk_bf16_f32 v104, v104, v105
	v_cvt_pk_bf16_f32 v105, v106, v107
	v_lshlrev_b64 v[106:107], 12, v[96:97]
	v_pk_mul_f32 v[90:91], v[90:91], v[90:91]
	v_pk_mul_f32 v[92:93], v[92:93], v[92:93]
	v_lshl_add_u64 v[106:107], s[20:21], 0, v[106:107]
	v_add_f32_e32 v0, v92, v93
	v_add_f32_e32 v90, v90, v91
	v_lshl_add_u64 v[106:107], v[94:95], 1, v[106:107]
	v_add_f32_e32 v0, v90, v0
	v_mov_b32_e32 v90, v208
	global_store_dwordx2 v[106:107], v[104:105], off
	s_nop 0
	v_lshlrev_b32_e32 v90, 2, v90
	v_xor_b32_e32 v90, 4, v90
	ds_bpermute_b32 v90, v90, v0
	s_waitcnt lgkmcnt(0)
	v_add_f32_e32 v0, v0, v90
	v_mov_b32_e32 v90, v208
	s_nop 0
	v_lshlrev_b32_e32 v90, 2, v90
	v_xor_b32_e32 v90, 8, v90
	ds_bpermute_b32 v90, v90, v0
	s_waitcnt lgkmcnt(0)
	v_add_f32_e32 v0, v0, v90
	v_mov_b32_e32 v90, v208
	s_nop 0
	v_lshlrev_b32_e32 v90, 2, v90
	v_xor_b32_e32 v90, 16, v90
	ds_bpermute_b32 v90, v90, v0
	s_waitcnt lgkmcnt(0)
	v_add_f32_e32 v90, v0, v90
	v_mov_b32_e32 v0, v208
	s_nop 0
	v_lshlrev_b32_e32 v0, 2, v0
	v_xor_b32_e32 v0, 32, v0
	ds_bpermute_b32 v91, v0, v90
	s_and_saveexec_b64 s[2:3], s[4:5]
	s_cbranch_execz .LBB0_676
	v_lshlrev_b64 v[92:93], 7, v[96:97]
	v_lshl_add_u64 v[92:93], s[42:43], 0, v[92:93]
	v_lshl_add_u64 v[92:93], s[0:1], 2, v[92:93]
	v_lshlrev_b32_e32 v0, 2, v139
	v_lshl_add_u64 v[92:93], v[92:93], 0, v[0:1]
	s_waitcnt lgkmcnt(0)
	v_add_f32_e32 v0, v90, v91
	global_store_dword v[92:93], v0, off

; DI void gemm_tile(const GD& g, int pm, int pn, bf16_t* shm) {
;     ...
;       for (int pb8 = 0; pb8 < 4; ++pb8) {
;         float4 xs[4];
;         if (g.epi == 1) {
; #pragma unroll
;           for (int q = 0; q < 4; ++q) {
;             const int grow = brow + ai * HALF + wr * 64 + (pb8 * 4 + q) * 4 + (lane >> 4);
;             xs[q] = *reinterpret_cast<const float4*>((const float*)g.C + (long)grow * ldc + gcol);
;           }
;         }
.LBB0_679:
	v_or_b32_e32 v0, 16, v99
	v_mad_u64_u32 v[4:5], s[2:3], v0, s78, 0
	v_or_b32_e32 v0, 20, v99
	v_mad_u64_u32 v[6:7], s[2:3], v0, s78, 0
	v_lshl_add_u64 v[2:3], v[94:95], 2, s[34:35]
	v_add_u32_e32 v5, v5, v102
	v_add_u32_e32 v7, v7, v102
	v_lshl_add_u64 v[4:5], v[4:5], 2, v[2:3]
	v_lshl_add_u64 v[6:7], v[6:7], 2, v[2:3]
	v_or_b32_e32 v0, 24, v99
	global_load_dwordx4 v[14:17], v[4:5], off
	s_nop 0
	global_load_dwordx4 v[6:9], v[6:7], off
	v_mad_u64_u32 v[4:5], s[2:3], v0, s78, 0
	v_or_b32_e32 v0, 28, v99
	v_mad_u64_u32 v[10:11], s[2:3], v0, s78, 0
	v_add_u32_e32 v5, v5, v102
	v_add_u32_e32 v11, v11, v102
	v_lshl_add_u64 v[4:5], v[4:5], 2, v[2:3]
	v_lshl_add_u64 v[2:3], v[10:11], 2, v[2:3]
	global_load_dwordx4 v[10:13], v[4:5], off
	s_nop 0
	global_load_dwordx4 v[2:5], v[2:3], off

; DI void gemm_tile(const GD& g, int pm, int pn, bf16_t* shm) {
;     ...
;       for (int pb8 = 0; pb8 < 4; ++pb8) {
;         float4 xs[4];
;         if (g.epi == 1) {
; #pragma unroll
;           for (int q = 0; q < 4; ++q) {
;             const int grow = brow + ai * HALF + wr * 64 + (pb8 * 4 + q) * 4 + (lane >> 4);
;             xs[q] = *reinterpret_cast<const float4*>((const float*)g.C + (long)grow * ldc + gcol);
;           }
;         }
.LBB0_745:
	v_or_b32_e32 v0, 32, v99
	v_mad_u64_u32 v[4:5], s[2:3], v0, s78, 0
	v_or_b32_e32 v0, 36, v99
	v_mad_u64_u32 v[6:7], s[2:3], v0, s78, 0
	v_lshl_add_u64 v[2:3], v[94:95], 2, s[34:35]
	v_add_u32_e32 v5, v5, v102
	v_add_u32_e32 v7, v7, v102
	v_lshl_add_u64 v[4:5], v[4:5], 2, v[2:3]
	v_lshl_add_u64 v[6:7], v[6:7], 2, v[2:3]
	v_or_b32_e32 v0, 40, v99
	global_load_dwordx4 v[14:17], v[4:5], off
	s_nop 0
	global_load_dwordx4 v[6:9], v[6:7], off
	v_mad_u64_u32 v[4:5], s[2:3], v0, s78, 0
	v_or_b32_e32 v0, 44, v99
	v_mad_u64_u32 v[10:11], s[2:3], v0, s78, 0
	v_add_u32_e32 v5, v5, v102
	v_add_u32_e32 v11, v11, v102
	v_lshl_add_u64 v[4:5], v[4:5], 2, v[2:3]
	v_lshl_add_u64 v[2:3], v[10:11], 2, v[2:3]
	global_load_dwordx4 v[10:13], v[4:5], off
	s_nop 0
	global_load_dwordx4 v[2:5], v[2:3], off

; DI void gemm_tile(const GD& g, int pm, int pn, bf16_t* shm) {
;     ...
;       for (int pb8 = 0; pb8 < 4; ++pb8) {
;         float4 xs[4];
;         if (g.epi == 1) {
; #pragma unroll
;           for (int q = 0; q < 4; ++q) {
;             const int grow = brow + ai * HALF + wr * 64 + (pb8 * 4 + q) * 4 + (lane >> 4);
;             xs[q] = *reinterpret_cast<const float4*>((const float*)g.C + (long)grow * ldc + gcol);
;           }
;         }
.LBB0_811:
	v_or_b32_e32 v0, 48, v99
	v_mad_u64_u32 v[4:5], s[2:3], v0, s78, 0
	v_or_b32_e32 v0, 52, v99
	v_mad_u64_u32 v[6:7], s[2:3], v0, s78, 0
	v_lshl_add_u64 v[2:3], v[94:95], 2, s[34:35]
	v_add_u32_e32 v5, v5, v102
	v_add_u32_e32 v7, v7, v102
	v_lshl_add_u64 v[4:5], v[4:5], 2, v[2:3]
	v_lshl_add_u64 v[6:7], v[6:7], 2, v[2:3]
	v_or_b32_e32 v0, 56, v99
	global_load_dwordx4 v[14:17], v[4:5], off
	s_nop 0
	global_load_dwordx4 v[6:9], v[6:7], off
	v_mad_u64_u32 v[4:5], s[2:3], v0, s78, 0
	v_or_b32_e32 v0, 60, v99
	v_mad_u64_u32 v[10:11], s[2:3], v0, s78, 0
	v_add_u32_e32 v5, v5, v102
	v_add_u32_e32 v11, v11, v102
	v_lshl_add_u64 v[4:5], v[4:5], 2, v[2:3]
	v_lshl_add_u64 v[2:3], v[10:11], 2, v[2:3]
	global_load_dwordx4 v[10:13], v[4:5], off
	s_nop 0
	global_load_dwordx4 v[2:5], v[2:3], off

; DI unsigned pk2(float a, float b) { f32x2 v; v[0] = a; v[1] = b; return __builtin_bit_cast(unsigned, __builtin_convertvector(v, bf16v2)); }
; DI float shx_(float v, int m) { return __int_as_float(__builtin_amdgcn_ds_bpermute((lane_pinned_() ^ m) << 2, __float_as_int(v))); }
; DI int shx_(int v, int m) { return __builtin_amdgcn_ds_bpermute((lane_pinned_() ^ m) << 2, v); }
; DI void gemm_tile(const GD& g, int pm, int pn, bf16_t* shm) {
;     ...
;         for (int q = 0; q < 4; ++q) {
;           const int row_l = (pb8 * 4 + q) * 4 + (lane >> 4);
;           float4 v = *reinterpret_cast<const float4*>(stgw + row_l * 68 + c4);
;           const int grow = brow + ai * HALF + wr * 64 + row_l;
;           if (g.epi == 0) {
;             if (g.rowscale) {
;               const float rr = rsc[ai * HALF + wr * 64 + row_l];
;               v.x *= rr; v.y *= rr; v.z *= rr; v.w *= rr;
;             }
;             u32x2 o2; o2[0] = pk2(v.x, v.y); o2[1] = pk2(v.z, v.w);
;             *reinterpret_cast<u32x2*>((bf16_t*)g.C + (long)grow * ldc + gcol) = o2;
;           } else if (g.epi == 2) {
;             const float rr = rsc[ai * HALF + wr * 64 + row_l];
;             v.x *= rr; v.y *= rr; v.z *= rr; v.w *= rr;
;             *reinterpret_cast<float4*>((float*)g.C + (long)grow * ldc + gcol) = v;
;           } else {
;             float4 x = xs[q];
;             x.x += v.x; x.y += v.y; x.z += v.z; x.w += v.w;
;             *reinterpret_cast<float4*>((float*)g.C + (long)grow * ldc + gcol) = x;
;             if (g.gnext) {
;               u32x2 o2; o2[0] = pk2(x.x * gn.x, x.y * gn.y); o2[1] = pk2(x.z * gn.z, x.w * gn.w);
;               *reinterpret_cast<u32x2*>(g.hbout + (long)grow * DM + gcol) = o2;
;               float sq = (x.x * x.x + x.y * x.y) + (x.z * x.z + x.w * x.w);
;               sq += shx_(sq, 1); sq += shx_(sq, 2); sq += shx_(sq, 4); sq += shx_(sq, 8);
;               if ((lane & 15) == 0) g.ss[(long)grow * 32 + pn * 4 + wc] = sq;
.LBB0_817:
	v_mad_u64_u32 v[102:103], s[2:3], v96, s78, 0
	v_mov_b32_e32 v0, v103
	v_mad_u64_u32 v[104:105], s[2:3], v97, s78, v[0:1]
	v_mov_b32_e32 v103, v104
	v_lshl_add_u64 v[102:103], v[102:103], 2, s[34:35]
	s_waitcnt vmcnt(0) lgkmcnt(0)
	v_pk_add_f32 v[90:91], v[14:15], v[86:87]
	v_pk_add_f32 v[92:93], v[16:17], v[88:89]
	v_lshl_add_u64 v[102:103], v[94:95], 2, v[102:103]
	s_cmp_eq_u64 s[80:81], 0
	global_store_dwordx4 v[102:103], v[90:93], off
	s_cbranch_scc1 .LBB0_821
	v_pk_mul_f32 v[102:103], v[82:83], v[90:91]
	v_pk_mul_f32 v[104:105], v[84:85], v[92:93]
	v_cvt_pk_bf16_f32 v102, v102, v103
	v_cvt_pk_bf16_f32 v103, v104, v105
	v_lshlrev_b64 v[104:105], 12, v[96:97]
	v_pk_mul_f32 v[90:91], v[90:91], v[90:91]
	v_pk_mul_f32 v[92:93], v[92:93], v[92:93]
	v_lshl_add_u64 v[104:105], s[20:21], 0, v[104:105]
	v_add_f32_e32 v0, v92, v93
	v_add_f32_e32 v90, v90, v91
	v_lshl_add_u64 v[104:105], v[94:95], 1, v[104:105]
	v_add_f32_e32 v0, v90, v0
	v_mov_b32_e32 v90, v208
	global_store_dwordx2 v[104:105], v[102:103], off
	s_nop 0
	v_lshlrev_b32_e32 v90, 2, v90
	v_xor_b32_e32 v90, 4, v90
	ds_bpermute_b32 v90, v90, v0
	s_waitcnt lgkmcnt(0)
	v_add_f32_e32 v0, v0, v90
	v_mov_b32_e32 v90, v208
	s_nop 0
	v_lshlrev_b32_e32 v90, 2, v90
	v_xor_b32_e32 v90, 8, v90
	ds_bpermute_b32 v90, v90, v0
	s_waitcnt lgkmcnt(0)
	v_add_f32_e32 v0, v0, v90
	v_mov_b32_e32 v90, v208
	s_nop 0
	v_lshlrev_b32_e32 v90, 2, v90
	v_xor_b32_e32 v90, 16, v90
	ds_bpermute_b32 v90, v90, v0
	s_waitcnt lgkmcnt(0)
	v_add_f32_e32 v90, v0, v90
	v_mov_b32_e32 v0, v208
	s_nop 0
	v_lshlrev_b32_e32 v0, 2, v0
	v_xor_b32_e32 v0, 32, v0
	ds_bpermute_b32 v91, v0, v90
	s_and_saveexec_b64 s[2:3], s[4:5]
	s_cbranch_execz .LBB0_820
	v_lshlrev_b64 v[92:93], 7, v[96:97]
	v_lshl_add_u64 v[92:93], s[42:43], 0, v[92:93]
	v_lshl_add_u64 v[92:93], s[0:1], 2, v[92:93]
	v_lshlrev_b32_e32 v0, 2, v139
	v_lshl_add_u64 v[92:93], v[92:93], 0, v[0:1]
	s_waitcnt lgkmcnt(0)
	v_add_f32_e32 v0, v90, v91
	global_store_dword v[92:93], v0, off

; DI unsigned pk2(float a, float b) { f32x2 v; v[0] = a; v[1] = b; return __builtin_bit_cast(unsigned, __builtin_convertvector(v, bf16v2)); }
; DI float shx_(float v, int m) { return __int_as_float(__builtin_amdgcn_ds_bpermute((lane_pinned_() ^ m) << 2, __float_as_int(v))); }
; DI int shx_(int v, int m) { return __builtin_amdgcn_ds_bpermute((lane_pinned_() ^ m) << 2, v); }
; DI void gemm_tile(const GD& g, int pm, int pn, bf16_t* shm) {
;     ...
;         for (int q = 0; q < 4; ++q) {
;           const int row_l = (pb8 * 4 + q) * 4 + (lane >> 4);
;           float4 v = *reinterpret_cast<const float4*>(stgw + row_l * 68 + c4);
;           const int grow = brow + ai * HALF + wr * 64 + row_l;
;           if (g.epi == 0) {
;             if (g.rowscale) {
;               const float rr = rsc[ai * HALF + wr * 64 + row_l];
;               v.x *= rr; v.y *= rr; v.z *= rr; v.w *= rr;
;             }
;             u32x2 o2; o2[0] = pk2(v.x, v.y); o2[1] = pk2(v.z, v.w);
;             *reinterpret_cast<u32x2*>((bf16_t*)g.C + (long)grow * ldc + gcol) = o2;
;           } else if (g.epi == 2) {
;             const float rr = rsc[ai * HALF + wr * 64 + row_l];
;             v.x *= rr; v.y *= rr; v.z *= rr; v.w *= rr;
;             *reinterpret_cast<float4*>((float*)g.C + (long)grow * ldc + gcol) = v;
;           } else {
;             float4 x = xs[q];
;             x.x += v.x; x.y += v.y; x.z += v.z; x.w += v.w;
;             *reinterpret_cast<float4*>((float*)g.C + (long)grow * ldc + gcol) = x;
;             if (g.gnext) {
;               u32x2 o2; o2[0] = pk2(x.x * gn.x, x.y * gn.y); o2[1] = pk2(x.z * gn.z, x.w * gn.w);
;               *reinterpret_cast<u32x2*>(g.hbout + (long)grow * DM + gcol) = o2;
;               float sq = (x.x * x.x + x.y * x.y) + (x.z * x.z + x.w * x.w);
;               sq += shx_(sq, 1); sq += shx_(sq, 2); sq += shx_(sq, 4); sq += shx_(sq, 8);
;               if ((lane & 15) == 0) g.ss[(long)grow * 32 + pn * 4 + wc] = sq;
.LBB0_839:
	v_mad_u64_u32 v[102:103], s[2:3], v96, s78, 0
	v_mov_b32_e32 v0, v103
	v_mad_u64_u32 v[104:105], s[2:3], v97, s78, v[0:1]
	v_mov_b32_e32 v103, v104
	v_lshl_add_u64 v[102:103], v[102:103], 2, s[34:35]
	s_waitcnt lgkmcnt(0)
	v_pk_add_f32 v[90:91], v[6:7], v[86:87]
	v_pk_add_f32 v[92:93], v[8:9], v[88:89]
	v_lshl_add_u64 v[102:103], v[94:95], 2, v[102:103]
	s_cmp_eq_u64 s[80:81], 0
	global_store_dwordx4 v[102:103], v[90:93], off
	s_cbranch_scc1 .LBB0_843
	v_pk_mul_f32 v[102:103], v[82:83], v[90:91]
	v_pk_mul_f32 v[104:105], v[84:85], v[92:93]
	v_cvt_pk_bf16_f32 v102, v102, v103
	v_cvt_pk_bf16_f32 v103, v104, v105
	v_lshlrev_b64 v[104:105], 12, v[96:97]
	v_pk_mul_f32 v[90:91], v[90:91], v[90:91]
	v_pk_mul_f32 v[92:93], v[92:93], v[92:93]
	v_lshl_add_u64 v[104:105], s[20:21], 0, v[104:105]
	v_add_f32_e32 v0, v92, v93
	v_add_f32_e32 v90, v90, v91
	v_lshl_add_u64 v[104:105], v[94:95], 1, v[104:105]
	v_add_f32_e32 v0, v90, v0
	v_mov_b32_e32 v90, v208
	global_store_dwordx2 v[104:105], v[102:103], off
	s_nop 0
	v_lshlrev_b32_e32 v90, 2, v90
	v_xor_b32_e32 v90, 4, v90
	ds_bpermute_b32 v90, v90, v0
	s_waitcnt lgkmcnt(0)
	v_add_f32_e32 v0, v0, v90
	v_mov_b32_e32 v90, v208
	s_nop 0
	v_lshlrev_b32_e32 v90, 2, v90
	v_xor_b32_e32 v90, 8, v90
	ds_bpermute_b32 v90, v90, v0
	s_waitcnt lgkmcnt(0)
	v_add_f32_e32 v0, v0, v90
	v_mov_b32_e32 v90, v208
	s_nop 0
	v_lshlrev_b32_e32 v90, 2, v90
	v_xor_b32_e32 v90, 16, v90
	ds_bpermute_b32 v90, v90, v0
	s_waitcnt lgkmcnt(0)
	v_add_f32_e32 v90, v0, v90
	v_mov_b32_e32 v0, v208
	s_nop 0
	v_lshlrev_b32_e32 v0, 2, v0
	v_xor_b32_e32 v0, 32, v0
	ds_bpermute_b32 v91, v0, v90
	s_and_saveexec_b64 s[2:3], s[4:5]
	s_cbranch_execz .LBB0_842
	v_lshlrev_b64 v[92:93], 7, v[96:97]
	v_lshl_add_u64 v[92:93], s[42:43], 0, v[92:93]
	v_lshl_add_u64 v[92:93], s[0:1], 2, v[92:93]
	v_lshlrev_b32_e32 v0, 2, v139
	v_lshl_add_u64 v[92:93], v[92:93], 0, v[0:1]
	s_waitcnt lgkmcnt(0)
	v_add_f32_e32 v0, v90, v91
	global_store_dword v[92:93], v0, off

; DI unsigned pk2(float a, float b) { f32x2 v; v[0] = a; v[1] = b; return __builtin_bit_cast(unsigned, __builtin_convertvector(v, bf16v2)); }
; DI float shx_(float v, int m) { return __int_as_float(__builtin_amdgcn_ds_bpermute((lane_pinned_() ^ m) << 2, __float_as_int(v))); }
; DI int shx_(int v, int m) { return __builtin_amdgcn_ds_bpermute((lane_pinned_() ^ m) << 2, v); }
; DI void gemm_tile(const GD& g, int pm, int pn, bf16_t* shm) {
;     ...
;         for (int q = 0; q < 4; ++q) {
;           const int row_l = (pb8 * 4 + q) * 4 + (lane >> 4);
;           float4 v = *reinterpret_cast<const float4*>(stgw + row_l * 68 + c4);
;           const int grow = brow + ai * HALF + wr * 64 + row_l;
;           if (g.epi == 0) {
;             if (g.rowscale) {
;               const float rr = rsc[ai * HALF + wr * 64 + row_l];
;               v.x *= rr; v.y *= rr; v.z *= rr; v.w *= rr;
;             }
;             u32x2 o2; o2[0] = pk2(v.x, v.y); o2[1] = pk2(v.z, v.w);
;             *reinterpret_cast<u32x2*>((bf16_t*)g.C + (long)grow * ldc + gcol) = o2;
;           } else if (g.epi == 2) {
;             const float rr = rsc[ai * HALF + wr * 64 + row_l];
;             v.x *= rr; v.y *= rr; v.z *= rr; v.w *= rr;
;             *reinterpret_cast<float4*>((float*)g.C + (long)grow * ldc + gcol) = v;
;           } else {
;             float4 x = xs[q];
;             x.x += v.x; x.y += v.y; x.z += v.z; x.w += v.w;
;             *reinterpret_cast<float4*>((float*)g.C + (long)grow * ldc + gcol) = x;
;             if (g.gnext) {
;               u32x2 o2; o2[0] = pk2(x.x * gn.x, x.y * gn.y); o2[1] = pk2(x.z * gn.z, x.w * gn.w);
;               *reinterpret_cast<u32x2*>(g.hbout + (long)grow * DM + gcol) = o2;
;               float sq = (x.x * x.x + x.y * x.y) + (x.z * x.z + x.w * x.w);
;               sq += shx_(sq, 1); sq += shx_(sq, 2); sq += shx_(sq, 4); sq += shx_(sq, 8);
;               if ((lane & 15) == 0) g.ss[(long)grow * 32 + pn * 4 + wc] = sq;
.LBB0_855:
	v_mad_u64_u32 v[102:103], s[2:3], v96, s78, 0
	v_mov_b32_e32 v0, v103
	v_mad_u64_u32 v[104:105], s[2:3], v97, s78, v[0:1]
	v_mov_b32_e32 v103, v104
	v_lshl_add_u64 v[102:103], v[102:103], 2, s[34:35]
	s_waitcnt lgkmcnt(0)
	v_pk_add_f32 v[90:91], v[10:11], v[86:87]
	v_pk_add_f32 v[92:93], v[12:13], v[88:89]
	v_lshl_add_u64 v[102:103], v[94:95], 2, v[102:103]
	s_cmp_eq_u64 s[80:81], 0
	global_store_dwordx4 v[102:103], v[90:93], off
	s_cbranch_scc1 .LBB0_859
	v_pk_mul_f32 v[102:103], v[82:83], v[90:91]
	v_pk_mul_f32 v[104:105], v[84:85], v[92:93]
	v_cvt_pk_bf16_f32 v102, v102, v103
	v_cvt_pk_bf16_f32 v103, v104, v105
	v_lshlrev_b64 v[104:105], 12, v[96:97]
	v_pk_mul_f32 v[90:91], v[90:91], v[90:91]
	v_pk_mul_f32 v[92:93], v[92:93], v[92:93]
	v_lshl_add_u64 v[104:105], s[20:21], 0, v[104:105]
	v_add_f32_e32 v0, v92, v93
	v_add_f32_e32 v90, v90, v91
	v_lshl_add_u64 v[104:105], v[94:95], 1, v[104:105]
	v_add_f32_e32 v0, v90, v0
	v_mov_b32_e32 v90, v208
	global_store_dwordx2 v[104:105], v[102:103], off
	s_nop 0
	v_lshlrev_b32_e32 v90, 2, v90
	v_xor_b32_e32 v90, 4, v90
	ds_bpermute_b32 v90, v90, v0
	s_waitcnt lgkmcnt(0)
	v_add_f32_e32 v0, v0, v90
	v_mov_b32_e32 v90, v208
	s_nop 0
	v_lshlrev_b32_e32 v90, 2, v90
	v_xor_b32_e32 v90, 8, v90
	ds_bpermute_b32 v90, v90, v0
	s_waitcnt lgkmcnt(0)
	v_add_f32_e32 v0, v0, v90
	v_mov_b32_e32 v90, v208
	s_nop 0
	v_lshlrev_b32_e32 v90, 2, v90
	v_xor_b32_e32 v90, 16, v90
	ds_bpermute_b32 v90, v90, v0
	s_waitcnt lgkmcnt(0)
	v_add_f32_e32 v90, v0, v90
	v_mov_b32_e32 v0, v208
	s_nop 0
	v_lshlrev_b32_e32 v0, 2, v0
	v_xor_b32_e32 v0, 32, v0
	ds_bpermute_b32 v91, v0, v90
	s_and_saveexec_b64 s[2:3], s[4:5]
	s_cbranch_execz .LBB0_858
	v_lshlrev_b64 v[92:93], 7, v[96:97]
	v_lshl_add_u64 v[92:93], s[42:43], 0, v[92:93]
	v_lshl_add_u64 v[92:93], s[0:1], 2, v[92:93]
	v_lshlrev_b32_e32 v0, 2, v139
	v_lshl_add_u64 v[92:93], v[92:93], 0, v[0:1]
	s_waitcnt lgkmcnt(0)
	v_add_f32_e32 v0, v90, v91
	global_store_dword v[92:93], v0, off

; DI unsigned pk2(float a, float b) { f32x2 v; v[0] = a; v[1] = b; return __builtin_bit_cast(unsigned, __builtin_convertvector(v, bf16v2)); }
; DI float shx_(float v, int m) { return __int_as_float(__builtin_amdgcn_ds_bpermute((lane_pinned_() ^ m) << 2, __float_as_int(v))); }
; DI int shx_(int v, int m) { return __builtin_amdgcn_ds_bpermute((lane_pinned_() ^ m) << 2, v); }
; DI void gemm_tile(const GD& g, int pm, int pn, bf16_t* shm) {
;     ...
;         for (int q = 0; q < 4; ++q) {
;           const int row_l = (pb8 * 4 + q) * 4 + (lane >> 4);
;           float4 v = *reinterpret_cast<const float4*>(stgw + row_l * 68 + c4);
;           const int grow = brow + ai * HALF + wr * 64 + row_l;
;           if (g.epi == 0) {
;             if (g.rowscale) {
;               const float rr = rsc[ai * HALF + wr * 64 + row_l];
;               v.x *= rr; v.y *= rr; v.z *= rr; v.w *= rr;
;             }
;             u32x2 o2; o2[0] = pk2(v.x, v.y); o2[1] = pk2(v.z, v.w);
;             *reinterpret_cast<u32x2*>((bf16_t*)g.C + (long)grow * ldc + gcol) = o2;
;           } else if (g.epi == 2) {
;             const float rr = rsc[ai * HALF + wr * 64 + row_l];
;             v.x *= rr; v.y *= rr; v.z *= rr; v.w *= rr;
;             *reinterpret_cast<float4*>((float*)g.C + (long)grow * ldc + gcol) = v;
;           } else {
;             float4 x = xs[q];
;             x.x += v.x; x.y += v.y; x.z += v.z; x.w += v.w;
;             *reinterpret_cast<float4*>((float*)g.C + (long)grow * ldc + gcol) = x;
;             if (g.gnext) {
;               u32x2 o2; o2[0] = pk2(x.x * gn.x, x.y * gn.y); o2[1] = pk2(x.z * gn.z, x.w * gn.w);
;               *reinterpret_cast<u32x2*>(g.hbout + (long)grow * DM + gcol) = o2;
;               float sq = (x.x * x.x + x.y * x.y) + (x.z * x.z + x.w * x.w);
;               sq += shx_(sq, 1); sq += shx_(sq, 2); sq += shx_(sq, 4); sq += shx_(sq, 8);
;               if ((lane & 15) == 0) g.ss[(long)grow * 32 + pn * 4 + wc] = sq;
.LBB0_871:
	v_mad_u64_u32 v[102:103], s[2:3], v96, s78, 0
	v_mov_b32_e32 v0, v103
	v_mad_u64_u32 v[104:105], s[2:3], v97, s78, v[0:1]
	v_mov_b32_e32 v103, v104
	v_lshl_add_u64 v[102:103], v[102:103], 2, s[34:35]
	s_waitcnt lgkmcnt(0)
	v_pk_add_f32 v[90:91], v[2:3], v[86:87]
	v_pk_add_f32 v[92:93], v[4:5], v[88:89]
	v_lshl_add_u64 v[102:103], v[94:95], 2, v[102:103]
	s_cmp_eq_u64 s[80:81], 0
	global_store_dwordx4 v[102:103], v[90:93], off
	s_cbranch_scc1 .LBB0_875
	v_pk_mul_f32 v[82:83], v[82:83], v[90:91]
	v_pk_mul_f32 v[84:85], v[84:85], v[92:93]
	v_cvt_pk_bf16_f32 v82, v82, v83
	v_cvt_pk_bf16_f32 v83, v84, v85
	v_lshlrev_b64 v[84:85], 12, v[96:97]
	v_lshl_add_u64 v[84:85], s[20:21], 0, v[84:85]
	v_lshl_add_u64 v[84:85], v[94:95], 1, v[84:85]
	global_store_dwordx2 v[84:85], v[82:83], off
	v_pk_mul_f32 v[82:83], v[90:91], v[90:91]
	v_pk_mul_f32 v[84:85], v[92:93], v[92:93]
	v_add_f32_e32 v82, v82, v83
	v_add_f32_e32 v0, v84, v85
	v_add_f32_e32 v0, v82, v0
	v_mov_b32_e32 v82, v208
	s_nop 0
	v_lshlrev_b32_e32 v82, 2, v82
	v_xor_b32_e32 v82, 4, v82
	ds_bpermute_b32 v82, v82, v0
	s_waitcnt lgkmcnt(0)
	v_add_f32_e32 v0, v0, v82
	v_mov_b32_e32 v82, v208
	s_nop 0
	v_lshlrev_b32_e32 v82, 2, v82
	v_xor_b32_e32 v82, 8, v82
	ds_bpermute_b32 v82, v82, v0
	s_waitcnt lgkmcnt(0)
	v_add_f32_e32 v0, v0, v82
	v_mov_b32_e32 v82, v208
	s_nop 0
	v_lshlrev_b32_e32 v82, 2, v82
	v_xor_b32_e32 v82, 16, v82
	ds_bpermute_b32 v82, v82, v0
	s_waitcnt lgkmcnt(0)
	v_add_f32_e32 v82, v0, v82
	v_mov_b32_e32 v0, v208
	s_nop 0
	v_lshlrev_b32_e32 v0, 2, v0
	v_xor_b32_e32 v0, 32, v0
	ds_bpermute_b32 v83, v0, v82
	s_and_saveexec_b64 s[2:3], s[4:5]
	s_cbranch_execz .LBB0_874
	v_lshlrev_b64 v[84:85], 7, v[96:97]
	v_lshl_add_u64 v[84:85], s[42:43], 0, v[84:85]
	v_lshl_add_u64 v[84:85], s[0:1], 2, v[84:85]
	v_lshlrev_b32_e32 v0, 2, v139
	v_lshl_add_u64 v[84:85], v[84:85], 0, v[0:1]
	s_waitcnt lgkmcnt(0)
	v_add_f32_e32 v0, v82, v83
	global_store_dword v[84:85], v0, off

; DI void gemm_tile(const GD& g, int pm, int pn, bf16_t* shm) {
;     ...
;       if (g.epi == 3) {
;         const int cgp = lane & 7, rs = lane >> 3, r0 = rs * 8;
;         const int fcol = pn * HALF + wc * 32 + cgp * 4;
;         const float* cw = g.gnext;
;         const float4 wg0 = *reinterpret_cast<const float4*>(cw + fcol), wg1 = *reinterpret_cast<const float4*>(cw + NUP + fcol), wg2 = *reinterpret_cast<const float4*>(cw + 2 * NUP + fcol);
;         const float4 wv0 = *reinterpret_cast<const float4*>(cw + DFF + fcol), wv1 = *reinterpret_cast<const float4*>(cw + NUP + DFF + fcol), wv2 = *reinterpret_cast<const float4*>(cw + 2 * NUP + DFF + fcol);
;         const float4 bg = *reinterpret_cast<const float4*>(g.cbias + fcol), bv = *reinterpret_cast<const float4*>(g.cbias + DFF + fcol);
;         float* carry = (float*)shm + 8 * (64 * 68) + 256;
;         float4 g2, g1, v2, v1;
;         const bool first = (ai == 0 && wr == 0 && rs == 0);
;         {
;           const float* pb;
;           int ra, rb;
;           if (rs > 0) { pb = stgw; ra = r0 - 2; rb = r0 - 1; }
;           else if (wr == 1) { pb = (float*)shm + (wid - 4) * (64 * 68); ra = 62; rb = 63; }
;           else { pb = carry + wc * 128 - 0; ra = 0; rb = 1; }
;           if (rs == 0 && wr == 0) {
;             if (ai == 1) {
;               g2 = *reinterpret_cast<const float4*>(carry + wc * 128 + cgp * 4); v2 = *reinterpret_cast<const float4*>(carry + wc * 128 + 32 + cgp * 4);
;               g1 = *reinterpret_cast<const float4*>(carry + wc * 128 + 64 + cgp * 4); v1 = *reinterpret_cast<const float4*>(carry + wc * 128 + 96 + cgp * 4);
;             } else { g2 = g1 = v2 = v1 = make_float4(0.f, 0.f, 0.f, 0.f); }
;           } else {
;             g2 = *reinterpret_cast<const float4*>(pb + ra * 68 + cgp * 4); v2 = *reinterpret_cast<const float4*>(pb + ra * 68 + 32 + cgp * 4);
;             g1 = *reinterpret_cast<const float4*>(pb + rb * 68 + cgp * 4); v1 = *reinterpret_cast<const float4*>(pb + rb * 68 + 32 + cgp * 4);
;           }
;         }
;         float* halo = g.halo + (size_t)pm * 4 * NUP;
; #pragma unroll
;         for (int rr = 0; rr < 8; ++rr) {
;           const int row_l = r0 + rr;
;           const float4 gc = *reinterpret_cast<const float4*>(stgw + row_l * 68 + cgp * 4);
;           const float4 vc = *reinterpret_cast<const float4*>(stgw + row_l * 68 + 32 + cgp * 4);
.LBB0_1010:
	s_cmp_lt_i32 s48, 3
	ds_write_b32 v145, v21 offset:14064
	s_waitcnt lgkmcnt(0)
	s_barrier
	s_cbranch_scc1 .LBB0_1020
	s_cmp_eq_u32 s48, 3
	s_mov_b64 s[2:3], -1
	s_cbranch_scc0 .LBB0_1019
	v_lshlrev_b64 v[18:19], 2, v[130:131]
	v_readlane_b32 s2, v255, 3
	v_lshl_add_u64 v[26:27], s[80:81], 0, v[18:19]
	v_readlane_b32 s3, v255, 4
	global_load_dwordx4 v[34:37], v[26:27], off
	s_nop 0
	v_lshl_add_u64 v[30:31], s[2:3], 0, v[18:19]
	v_add_co_u32_e32 v18, vcc, 0xb000, v26
	v_readlane_b32 s2, v253, 36
	s_nop 0
	v_addc_co_u32_e32 v19, vcc, 0, v27, vcc
	v_add_co_u32_e32 v20, vcc, 0x16000, v26
	v_lshl_add_u32 v50, v143, 9, s2
	s_nop 0
	v_addc_co_u32_e32 v21, vcc, 0, v27, vcc
	global_load_dwordx4 v[38:41], v[18:19], off
	global_load_dwordx4 v[42:45], v[20:21], off
	v_add_co_u32_e32 v18, vcc, 0x5000, v26
	v_add_u32_e32 v0, 0x100, v50
	s_nop 0
	v_addc_co_u32_e32 v19, vcc, 0, v27, vcc
	v_add_co_u32_e32 v22, vcc, 0x10000, v26
	v_add_u32_e32 v51, 0x180, v50
	s_nop 0
	v_addc_co_u32_e32 v23, vcc, 0, v27, vcc
	v_add_co_u32_e32 v26, vcc, 0x1b000, v26
	global_load_dwordx4 v[18:21], v[18:19], off offset:2048
	s_nop 0
	global_load_dwordx4 v[22:25], v[22:23], off offset:2048
	v_addc_co_u32_e32 v27, vcc, 0, v27, vcc
	global_load_dwordx4 v[26:29], v[26:27], off offset:2048
	s_nop 0
	global_load_dwordx4 v[46:49], v[30:31], off
	v_add_co_u32_e32 v30, vcc, 0x5000, v30
	s_nop 1
	v_addc_co_u32_e32 v31, vcc, 0, v31, vcc
	global_load_dwordx4 v[30:33], v[30:31], off offset:2048
	s_and_saveexec_b64 s[2:3], s[52:53]
	v_cndmask_b32_e64 v0, v231, v232, s[10:11]
	v_cndmask_b32_e64 v51, v149, v150, s[10:11]
	v_cndmask_b32_e64 v0, v148, v0, s[8:9]
	v_cndmask_b32_e64 v50, 0, v233, s[10:11]
	v_cndmask_b32_e64 v51, v141, v51, s[8:9]
	v_cndmask_b32_e64 v50, v147, v50, s[8:9]
	v_lshl_add_u32 v0, v0, 2, v51
	v_lshl_add_u32 v50, v50, 2, v51
	v_add_u32_e32 v51, 0x80, v0
	s_or_b64 exec, exec, s[2:3]
	v_lshlrev_b32_e32 v78, 2, v146
	v_add_u32_e32 v51, v51, v78
	v_add_u32_e32 v52, v0, v78
	v_mul_u32_u24_e32 v53, 0x110, v142
	v_add_u32_e32 v70, v50, v78
	v_add3_u32 v79, v141, v53, v78
	ds_read_b128 v[58:61], v51
	ds_read_b128 v[66:69], v52
	ds_read_b128 v[62:65], v79
	ds_read_b128 v[50:53], v79 offset:128
	ds_read_b128 v[54:57], v70 offset:128
	ds_read_b128 v[70:73], v70
	s_lshl_b64 s[2:3], s[56:57], 2
	v_readlane_b32 s6, v255, 5
	v_readlane_b32 s7, v255, 6
	s_add_u32 s6, s6, s2
	s_waitcnt vmcnt(1) lgkmcnt(0)
	v_pk_fma_f32 v[70:71], v[34:35], v[70:71], v[46:47]
	s_addc_u32 s7, s7, s3
	v_pk_fma_f32 v[70:71], v[38:39], v[66:67], v[70:71]
	s_waitcnt vmcnt(0)
	v_pk_fma_f32 v[54:55], v[18:19], v[54:55], v[30:31]
	v_pk_fma_f32 v[70:71], v[42:43], v[62:63], v[70:71]
	v_pk_fma_f32 v[54:55], v[22:23], v[58:59], v[54:55]
	v_mul_f32_e32 v74, 0xbfb8aa3b, v70
	v_mul_f32_e32 v75, 0xbfb8aa3b, v71
	v_exp_f32_e32 v74, v74
	v_exp_f32_e32 v75, v75
	v_pk_fma_f32 v[54:55], v[26:27], v[50:51], v[54:55]
	v_pk_fma_f32 v[56:57], v[20:21], v[56:57], v[32:33]
	v_add_u32_e32 v0, 0x80, v140
	v_pk_add_f32 v[74:75], v[74:75], 1.0 op_sel_hi:[1,0]
	v_pk_fma_f32 v[56:57], v[24:25], v[60:61], v[56:57]
	v_pk_fma_f32 v[56:57], v[28:29], v[52:53], v[56:57]
	v_or_b32_e32 v88, v0, v142
	s_movk_i32 s8, 0x2c00
	v_rcp_f32_e32 v76, v75
	s_nop 0
	v_mul_f32_e32 v71, v71, v76
	v_mov_b64_e32 v[82:83], s[34:35]
	v_lshlrev_b64 v[84:85], 1, v[130:131]
	v_pk_fma_f32 v[66:67], v[34:35], v[66:67], v[46:47]
	v_rcp_f32_e32 v75, v74
	s_nop 0
	v_mul_f32_e32 v70, v70, v75
	v_pk_mul_f32 v[54:55], v[54:55], v[70:71]
	v_pk_fma_f32 v[70:71], v[36:37], v[72:73], v[48:49]
	v_cvt_pk_bf16_f32 v54, v54, v55
	v_pk_fma_f32 v[70:71], v[40:41], v[68:69], v[70:71]
	v_pk_fma_f32 v[66:67], v[38:39], v[62:63], v[66:67]
	v_pk_fma_f32 v[70:71], v[44:45], v[64:65], v[70:71]
	v_pk_fma_f32 v[58:59], v[18:19], v[58:59], v[30:31]
	v_mul_f32_e32 v72, 0xbfb8aa3b, v70
	v_mul_f32_e32 v73, 0xbfb8aa3b, v71
	v_exp_f32_e32 v72, v72
	v_exp_f32_e32 v73, v73
	v_pk_fma_f32 v[58:59], v[22:23], v[50:51], v[58:59]
	v_pk_fma_f32 v[60:61], v[20:21], v[60:61], v[32:33]
	v_pk_fma_f32 v[62:63], v[34:35], v[62:63], v[46:47]
	v_pk_add_f32 v[72:73], v[72:73], 1.0 op_sel_hi:[1,0]
	v_pk_fma_f32 v[60:61], v[24:25], v[52:53], v[60:61]
	v_pk_fma_f32 v[50:51], v[18:19], v[50:51], v[30:31]
	v_pk_fma_f32 v[52:53], v[20:21], v[52:53], v[32:33]
	v_rcp_f32_e32 v74, v73
	s_nop 0
	v_mul_f32_e32 v71, v71, v74
	s_nop 0
	v_rcp_f32_e32 v73, v72
	s_nop 0
	v_mul_f32_e32 v70, v70, v73
	v_pk_mul_f32 v[56:57], v[56:57], v[70:71]
	v_or_b32_e32 v76, 1, v88
	v_cvt_pk_bf16_f32 v55, v56, v57
	v_mad_i64_i32 v[56:57], s[2:3], v88, s8, v[82:83]
	v_lshl_add_u64 v[56:57], v[56:57], 0, v[84:85]
	global_store_dwordx2 v[56:57], v[54:55], off
	ds_read_b128 v[70:73], v79 offset:272
	ds_read_b128 v[54:57], v79 offset:400
	s_waitcnt lgkmcnt(1)
	v_pk_fma_f32 v[66:67], v[42:43], v[70:71], v[66:67]
	s_nop 0
	v_mul_f32_e32 v74, 0xbfb8aa3b, v66
	v_mul_f32_e32 v75, 0xbfb8aa3b, v67
	v_exp_f32_e32 v74, v74
	v_exp_f32_e32 v75, v75
	s_waitcnt lgkmcnt(0)
; DI unsigned pk2(float a, float b) { f32x2 v; v[0] = a; v[1] = b; return __builtin_bit_cast(unsigned, __builtin_convertvector(v, bf16v2)); }
; DI float siluf_(float x) { return x / (1.f + __expf(-x)); }
; DI void gemm_tile(const GD& g, int pm, int pn, bf16_t* shm) {
;     ...
;         for (int rr = 0; rr < 8; ++rr) {
;           const int row_l = r0 + rr;
;           const float4 gc = *reinterpret_cast<const float4*>(stgw + row_l * 68 + cgp * 4);
;           const float4 vc = *reinterpret_cast<const float4*>(stgw + row_l * 68 + 32 + cgp * 4);
;           const int grow = brow + ai * HALF + wr * 64 + row_l;
;           if (!(first && rr < 2)) {
;             const float a0 = siluf_(bg.x + wg0.x * g2.x + wg1.x * g1.x + wg2.x * gc.x) * (bv.x + wv0.x * v2.x + wv1.x * v1.x + wv2.x * vc.x);
;             const float a1 = siluf_(bg.y + wg0.y * g2.y + wg1.y * g1.y + wg2.y * gc.y) * (bv.y + wv0.y * v2.y + wv1.y * v1.y + wv2.y * vc.y);
;             const float a2 = siluf_(bg.z + wg0.z * g2.z + wg1.z * g1.z + wg2.z * gc.z) * (bv.z + wv0.z * v2.z + wv1.z * v1.z + wv2.z * vc.z);
;             const float a3 = siluf_(bg.w + wg0.w * g2.w + wg1.w * g1.w + wg2.w * gc.w) * (bv.w + wv0.w * v2.w + wv1.w * v1.w + wv2.w * vc.w);
;             u32x2 o2; o2[0] = pk2(a0, a1); o2[1] = pk2(a2, a3);
;             *reinterpret_cast<u32x2*>((bf16_t*)g.C + (long)grow * DFF + fcol) = o2;
;           }
;           if (first && rr < 2) {
;             *reinterpret_cast<float4*>(halo + (size_t)rr * NUP + fcol) = gc; *reinterpret_cast<float4*>(halo + (size_t)rr * NUP + DFF + fcol) = vc;
;           }
	v_pk_fma_f32 v[58:59], v[26:27], v[54:55], v[58:59]
	v_pk_fma_f32 v[60:61], v[28:29], v[56:57], v[60:61]
	v_pk_fma_f32 v[62:63], v[38:39], v[70:71], v[62:63]
	v_pk_add_f32 v[74:75], v[74:75], 1.0 op_sel_hi:[1,0]
	v_pk_fma_f32 v[50:51], v[22:23], v[54:55], v[50:51]
	v_pk_fma_f32 v[52:53], v[24:25], v[56:57], v[52:53]
	v_rcp_f32_e32 v77, v75
	s_nop 0
	v_mul_f32_e32 v67, v67, v77
	s_nop 0
	v_rcp_f32_e32 v75, v74
	s_nop 0
	v_mul_f32_e32 v66, v66, v75
	v_pk_mul_f32 v[58:59], v[66:67], v[58:59]
	v_pk_fma_f32 v[66:67], v[36:37], v[68:69], v[48:49]
	v_cvt_pk_bf16_f32 v58, v58, v59
	v_pk_fma_f32 v[66:67], v[40:41], v[64:65], v[66:67]
	s_nop 0
	v_pk_fma_f32 v[66:67], v[44:45], v[72:73], v[66:67]
	s_nop 0
	v_mul_f32_e32 v68, 0xbfb8aa3b, v66
	v_mul_f32_e32 v69, 0xbfb8aa3b, v67
	v_exp_f32_e32 v68, v68
	v_exp_f32_e32 v69, v69
	s_nop 0
	v_pk_add_f32 v[68:69], v[68:69], 1.0 op_sel_hi:[1,0]
	s_nop 0
	s_nop 0
	v_rcp_f32_e32 v74, v69
	s_nop 0
	v_mul_f32_e32 v67, v67, v74
	s_nop 0
	v_rcp_f32_e32 v69, v68
	s_nop 0
	v_mul_f32_e32 v66, v66, v69
	v_pk_mul_f32 v[60:61], v[66:67], v[60:61]
	v_or_b32_e32 v68, 2, v88
	v_cvt_pk_bf16_f32 v59, v60, v61
	v_mad_i64_i32 v[60:61], s[2:3], v76, s8, v[82:83]
	v_lshl_add_u64 v[60:61], v[60:61], 0, v[84:85]
	global_store_dwordx2 v[60:61], v[58:59], off
	ds_read_b128 v[74:77], v79 offset:544
	ds_read_b128 v[58:61], v79 offset:672
	s_waitcnt lgkmcnt(1)
	v_pk_fma_f32 v[62:63], v[42:43], v[74:75], v[62:63]
	s_nop 0
	v_mul_f32_e32 v66, 0xbfb8aa3b, v62
	v_mul_f32_e32 v67, 0xbfb8aa3b, v63
	v_exp_f32_e32 v66, v66
	v_exp_f32_e32 v67, v67
	s_waitcnt lgkmcnt(0)
	v_pk_fma_f32 v[50:51], v[26:27], v[58:59], v[50:51]
	v_pk_fma_f32 v[52:53], v[28:29], v[60:61], v[52:53]
	v_pk_add_f32 v[66:67], v[66:67], 1.0 op_sel_hi:[1,0]
	s_nop 0
	s_nop 0
	v_rcp_f32_e32 v69, v67
	s_nop 0
	v_mul_f32_e32 v63, v63, v69
	s_nop 0
	v_rcp_f32_e32 v67, v66
	s_nop 0
	v_mul_f32_e32 v62, v62, v67
	v_pk_mul_f32 v[50:51], v[62:63], v[50:51]
	v_pk_fma_f32 v[62:63], v[36:37], v[64:65], v[48:49]
	v_cvt_pk_bf16_f32 v50, v50, v51
	v_pk_fma_f32 v[62:63], v[40:41], v[72:73], v[62:63]
	s_nop 0
	v_pk_fma_f32 v[62:63], v[44:45], v[76:77], v[62:63]
	s_nop 0
	v_mul_f32_e32 v64, 0xbfb8aa3b, v62
	v_mul_f32_e32 v65, 0xbfb8aa3b, v63
	v_exp_f32_e32 v64, v64
	v_exp_f32_e32 v65, v65
	s_nop 0
	v_pk_add_f32 v[64:65], v[64:65], 1.0 op_sel_hi:[1,0]
	s_nop 0
	s_nop 0
	v_rcp_f32_e32 v66, v65
	s_nop 0
	v_mul_f32_e32 v63, v63, v66
	s_nop 0
	v_rcp_f32_e32 v65, v64
	s_nop 0
	v_mul_f32_e32 v62, v62, v65
	v_pk_mul_f32 v[52:53], v[62:63], v[52:53]
	v_or_b32_e32 v80, 3, v88
	v_cvt_pk_bf16_f32 v51, v52, v53
	v_mad_i64_i32 v[52:53], s[2:3], v68, s8, v[82:83]
	v_lshl_add_u64 v[52:53], v[52:53], 0, v[84:85]
	global_store_dwordx2 v[52:53], v[50:51], off
	ds_read_b128 v[62:65], v79 offset:816
	ds_read_b128 v[66:69], v79 offset:944
	v_pk_fma_f32 v[50:51], v[34:35], v[70:71], v[46:47]
	s_nop 0
	v_pk_fma_f32 v[50:51], v[38:39], v[74:75], v[50:51]
	s_waitcnt lgkmcnt(1)
	v_pk_fma_f32 v[50:51], v[42:43], v[62:63], v[50:51]
	s_nop 0
	v_mul_f32_e32 v52, 0xbfb8aa3b, v50
	v_mul_f32_e32 v53, 0xbfb8aa3b, v51
	v_exp_f32_e32 v52, v52
	v_exp_f32_e32 v53, v53
	s_nop 0
	v_pk_add_f32 v[52:53], v[52:53], 1.0 op_sel_hi:[1,0]
	s_nop 0
	s_nop 0
	v_rcp_f32_e32 v70, v53
	s_nop 0
	v_mul_f32_e32 v51, v51, v70
	s_nop 0
	v_rcp_f32_e32 v53, v52
	s_nop 0
	v_mul_f32_e32 v50, v50, v53
	v_pk_fma_f32 v[52:53], v[18:19], v[54:55], v[30:31]
	s_nop 0
	v_pk_fma_f32 v[52:53], v[22:23], v[58:59], v[52:53]
	s_waitcnt lgkmcnt(0)
	v_pk_fma_f32 v[52:53], v[26:27], v[66:67], v[52:53]
	s_nop 0
	v_pk_mul_f32 v[50:51], v[50:51], v[52:53]
	v_pk_fma_f32 v[52:53], v[36:37], v[72:73], v[48:49]
	v_cvt_pk_bf16_f32 v50, v50, v51
	v_pk_fma_f32 v[52:53], v[40:41], v[76:77], v[52:53]
	s_nop 0
	v_pk_fma_f32 v[52:53], v[44:45], v[64:65], v[52:53]
	s_nop 0
	v_mul_f32_e32 v54, 0xbfb8aa3b, v52
	v_mul_f32_e32 v55, 0xbfb8aa3b, v53
	v_exp_f32_e32 v54, v54
	v_exp_f32_e32 v55, v55
	s_nop 0
	v_pk_add_f32 v[54:55], v[54:55], 1.0 op_sel_hi:[1,0]
	s_nop 0
	s_nop 0
	v_rcp_f32_e32 v70, v55
	s_nop 0
	v_mul_f32_e32 v53, v53, v70
	s_nop 0
	v_rcp_f32_e32 v55, v54
	s_nop 0
	v_mul_f32_e32 v52, v52, v55
	v_pk_fma_f32 v[54:55], v[20:21], v[56:57], v[32:33]
	s_nop 0
	v_pk_fma_f32 v[54:55], v[24:25], v[60:61], v[54:55]
	s_nop 0
	v_pk_fma_f32 v[54:55], v[28:29], v[68:69], v[54:55]
	s_nop 0
	v_pk_mul_f32 v[52:53], v[52:53], v[54:55]
	v_pk_fma_f32 v[54:55], v[34:35], v[74:75], v[46:47]
	v_cvt_pk_bf16_f32 v51, v52, v53
	v_mad_i64_i32 v[52:53], s[2:3], v80, s8, v[82:83]
	v_lshl_add_u64 v[52:53], v[52:53], 0, v[84:85]
	global_store_dwordx2 v[52:53], v[50:51], off
	ds_read_b128 v[70:73], v79 offset:1088
	ds_read_b128 v[50:53], v79 offset:1216
	v_pk_fma_f32 v[54:55], v[38:39], v[62:63], v[54:55]
	v_or_b32_e32 v80, 4, v88
	v_pk_fma_f32 v[62:63], v[34:35], v[62:63], v[46:47]
	s_waitcnt lgkmcnt(1)
	v_pk_fma_f32 v[54:55], v[42:43], v[70:71], v[54:55]
	v_pk_fma_f32 v[62:63], v[38:39], v[70:71], v[62:63]
	v_mul_f32_e32 v56, 0xbfb8aa3b, v54
	v_mul_f32_e32 v57, 0xbfb8aa3b, v55
	v_exp_f32_e32 v56, v56
	v_exp_f32_e32 v57, v57
	s_nop 0
	v_pk_add_f32 v[56:57], v[56:57], 1.0 op_sel_hi:[1,0]
	s_nop 0
	s_nop 0
	v_rcp_f32_e32 v74, v57
	s_nop 0
	v_mul_f32_e32 v55, v55, v74
	s_nop 0
	v_rcp_f32_e32 v57, v56
	s_nop 0
	v_mul_f32_e32 v54, v54, v57
	v_pk_fma_f32 v[56:57], v[18:19], v[58:59], v[30:31]
	s_nop 0
	v_pk_fma_f32 v[56:57], v[22:23], v[66:67], v[56:57]
	v_pk_fma_f32 v[66:67], v[18:19], v[66:67], v[30:31]
	s_waitcnt lgkmcnt(0)
; DI unsigned pk2(float a, float b) { f32x2 v; v[0] = a; v[1] = b; return __builtin_bit_cast(unsigned, __builtin_convertvector(v, bf16v2)); }
; DI float siluf_(float x) { return x / (1.f + __expf(-x)); }
; DI void gemm_tile(const GD& g, int pm, int pn, bf16_t* shm) {
;     ...
;         for (int rr = 0; rr < 8; ++rr) {
;           const int row_l = r0 + rr;
;           const float4 gc = *reinterpret_cast<const float4*>(stgw + row_l * 68 + cgp * 4);
;           const float4 vc = *reinterpret_cast<const float4*>(stgw + row_l * 68 + 32 + cgp * 4);
;           const int grow = brow + ai * HALF + wr * 64 + row_l;
;           if (!(first && rr < 2)) {
;             const float a0 = siluf_(bg.x + wg0.x * g2.x + wg1.x * g1.x + wg2.x * gc.x) * (bv.x + wv0.x * v2.x + wv1.x * v1.x + wv2.x * vc.x);
;             const float a1 = siluf_(bg.y + wg0.y * g2.y + wg1.y * g1.y + wg2.y * gc.y) * (bv.y + wv0.y * v2.y + wv1.y * v1.y + wv2.y * vc.y);
;             const float a2 = siluf_(bg.z + wg0.z * g2.z + wg1.z * g1.z + wg2.z * gc.z) * (bv.z + wv0.z * v2.z + wv1.z * v1.z + wv2.z * vc.z);
;             const float a3 = siluf_(bg.w + wg0.w * g2.w + wg1.w * g1.w + wg2.w * gc.w) * (bv.w + wv0.w * v2.w + wv1.w * v1.w + wv2.w * vc.w);
;             u32x2 o2; o2[0] = pk2(a0, a1); o2[1] = pk2(a2, a3);
;             *reinterpret_cast<u32x2*>((bf16_t*)g.C + (long)grow * DFF + fcol) = o2;
;           }
;           if (first && rr < 2) {
;             *reinterpret_cast<float4*>(halo + (size_t)rr * NUP + fcol) = gc; *reinterpret_cast<float4*>(halo + (size_t)rr * NUP + DFF + fcol) = vc;
;           }
;           if (ai == 1 && wr == 1 && rs == 7 && rr >= 6) {
;             *reinterpret_cast<float4*>(halo + (size_t)(rr - 4) * NUP + fcol) = gc; *reinterpret_cast<float4*>(halo + (size_t)(rr - 4) * NUP + DFF + fcol) = vc;
;           }
;           if (ai == 0 && wr == 1 && rs == 7 && rr >= 6) {
;             *reinterpret_cast<float4*>(carry + wc * 128 + (rr - 6) * 64 + cgp * 4) = gc; *reinterpret_cast<float4*>(carry + wc * 128 + (rr - 6) * 64 + 32 + cgp * 4) = vc;
;           }
	v_pk_fma_f32 v[56:57], v[26:27], v[50:51], v[56:57]
	v_pk_fma_f32 v[66:67], v[22:23], v[50:51], v[66:67]
	v_pk_mul_f32 v[54:55], v[54:55], v[56:57]
	v_pk_fma_f32 v[56:57], v[36:37], v[76:77], v[48:49]
	v_cvt_pk_bf16_f32 v54, v54, v55
	v_pk_fma_f32 v[56:57], v[40:41], v[64:65], v[56:57]
	v_pk_fma_f32 v[64:65], v[36:37], v[64:65], v[48:49]
	v_pk_fma_f32 v[56:57], v[44:45], v[72:73], v[56:57]
	v_pk_fma_f32 v[64:65], v[40:41], v[72:73], v[64:65]
	v_mul_f32_e32 v58, 0xbfb8aa3b, v56
	v_mul_f32_e32 v59, 0xbfb8aa3b, v57
	v_exp_f32_e32 v58, v58
	v_exp_f32_e32 v59, v59
	v_pk_fma_f32 v[50:51], v[18:19], v[50:51], v[30:31]
	v_pk_add_f32 v[58:59], v[58:59], 1.0 op_sel_hi:[1,0]
	s_nop 0
	s_nop 0
	v_rcp_f32_e32 v74, v59
	s_nop 0
	v_mul_f32_e32 v57, v57, v74
	s_nop 0
	v_rcp_f32_e32 v59, v58
	s_nop 0
	v_mul_f32_e32 v56, v56, v59
	v_pk_fma_f32 v[58:59], v[20:21], v[60:61], v[32:33]
	s_nop 0
	v_pk_fma_f32 v[58:59], v[24:25], v[68:69], v[58:59]
	s_nop 0
	v_pk_fma_f32 v[58:59], v[28:29], v[52:53], v[58:59]
	s_nop 0
	v_pk_mul_f32 v[56:57], v[56:57], v[58:59]
	s_nop 0
	v_cvt_pk_bf16_f32 v55, v56, v57
	v_mad_i64_i32 v[56:57], s[2:3], v80, s8, v[82:83]
	v_lshl_add_u64 v[56:57], v[56:57], 0, v[84:85]
	global_store_dwordx2 v[56:57], v[54:55], off
	v_or_b32_e32 v54, 5, v88
	v_mad_i64_i32 v[54:55], s[2:3], v54, s8, v[82:83]
	s_movk_i32 s2, 0x110
	v_lshl_add_u64 v[86:87], v[54:55], 0, v[84:85]
	v_mad_u32_u24 v54, v142, s2, v234
	v_add3_u32 v89, v141, v54, v78
	ds_read_b128 v[58:61], v79 offset:1360
	ds_read_b128 v[54:57], v79 offset:1488
	s_waitcnt lgkmcnt(1)
	v_pk_fma_f32 v[62:63], v[42:43], v[58:59], v[62:63]
	s_nop 0
	v_mul_f32_e32 v74, 0xbfb8aa3b, v62
	v_mul_f32_e32 v75, 0xbfb8aa3b, v63
	v_exp_f32_e32 v74, v74
	v_exp_f32_e32 v75, v75
	s_waitcnt lgkmcnt(0)
	v_pk_fma_f32 v[66:67], v[26:27], v[54:55], v[66:67]
	v_pk_fma_f32 v[64:65], v[44:45], v[60:61], v[64:65]
	v_pk_fma_f32 v[50:51], v[22:23], v[54:55], v[50:51]
	v_pk_add_f32 v[74:75], v[74:75], 1.0 op_sel_hi:[1,0]
	s_nop 0
	s_nop 0
	v_rcp_f32_e32 v76, v75
	s_nop 0
	v_mul_f32_e32 v63, v63, v76
	s_nop 0
	v_rcp_f32_e32 v75, v74
	s_nop 0
	v_mul_f32_e32 v62, v62, v75
	v_pk_mul_f32 v[62:63], v[62:63], v[66:67]
	v_pk_fma_f32 v[66:67], v[20:21], v[68:69], v[32:33]
	v_cvt_pk_bf16_f32 v62, v62, v63
	v_mul_f32_e32 v63, 0xbfb8aa3b, v64
	v_exp_f32_e32 v68, v63
	v_mul_f32_e32 v63, 0xbfb8aa3b, v65
	v_exp_f32_e32 v69, v63
	v_pk_fma_f32 v[66:67], v[24:25], v[52:53], v[66:67]
	ds_read_b128 v[78:81], v89
	ds_read_b128 v[74:77], v89 offset:128
	v_pk_fma_f32 v[66:67], v[28:29], v[56:57], v[66:67]
	v_pk_add_f32 v[68:69], v[68:69], 1.0 op_sel_hi:[1,0]
	v_pk_fma_f32 v[52:53], v[20:21], v[52:53], v[32:33]
	s_waitcnt lgkmcnt(0)
	v_pk_fma_f32 v[50:51], v[26:27], v[74:75], v[50:51]
	v_pk_fma_f32 v[52:53], v[24:25], v[56:57], v[52:53]
	v_rcp_f32_e32 v63, v69
	s_nop 0
	v_mul_f32_e32 v65, v65, v63
	v_pk_fma_f32 v[52:53], v[28:29], v[76:77], v[52:53]
	v_rcp_f32_e32 v63, v68
	s_nop 0
	v_mul_f32_e32 v64, v64, v63
	v_pk_mul_f32 v[64:65], v[64:65], v[66:67]
	v_or_b32_e32 v66, 6, v88
	v_cvt_pk_bf16_f32 v63, v64, v65
	global_store_dwordx2 v[86:87], v[62:63], off
	v_pk_fma_f32 v[62:63], v[34:35], v[70:71], v[46:47]
	s_nop 0
	v_pk_fma_f32 v[62:63], v[38:39], v[58:59], v[62:63]
	s_nop 0
	v_pk_fma_f32 v[62:63], v[42:43], v[78:79], v[62:63]
	s_nop 0
	v_mul_f32_e32 v64, 0xbfb8aa3b, v62
	v_mul_f32_e32 v65, 0xbfb8aa3b, v63
	v_exp_f32_e32 v64, v64
	v_exp_f32_e32 v65, v65
	s_nop 0
	v_pk_add_f32 v[64:65], v[64:65], 1.0 op_sel_hi:[1,0]
	s_nop 0
	s_nop 0
	v_rcp_f32_e32 v67, v65
	s_nop 0
	v_mul_f32_e32 v63, v63, v67
	s_nop 0
	v_rcp_f32_e32 v65, v64
	s_nop 0
	v_mul_f32_e32 v62, v62, v65
	v_pk_mul_f32 v[50:51], v[62:63], v[50:51]
	v_pk_fma_f32 v[62:63], v[36:37], v[72:73], v[48:49]
	v_cvt_pk_bf16_f32 v50, v50, v51
	v_pk_fma_f32 v[62:63], v[40:41], v[60:61], v[62:63]
	s_nop 0
	v_pk_fma_f32 v[62:63], v[44:45], v[80:81], v[62:63]
	s_nop 0
	v_mul_f32_e32 v64, 0xbfb8aa3b, v62
	v_mul_f32_e32 v65, 0xbfb8aa3b, v63
	v_exp_f32_e32 v64, v64
	v_exp_f32_e32 v65, v65
	s_nop 0
	v_pk_add_f32 v[64:65], v[64:65], 1.0 op_sel_hi:[1,0]
	s_nop 0
	s_nop 0
	v_rcp_f32_e32 v67, v65
	s_nop 0
	v_mul_f32_e32 v63, v63, v67
	s_nop 0
	v_rcp_f32_e32 v65, v64
	s_nop 0
	v_mul_f32_e32 v62, v62, v65
	v_pk_mul_f32 v[52:53], v[62:63], v[52:53]
	s_nop 0
	v_cvt_pk_bf16_f32 v51, v52, v53
	v_mad_i64_i32 v[52:53], s[2:3], v66, s8, v[82:83]
	v_lshl_add_u64 v[52:53], v[52:53], 0, v[84:85]
	v_lshl_add_u64 v[66:67], v[130:131], 2, s[6:7]
	global_store_dwordx2 v[52:53], v[50:51], off
	s_and_saveexec_b64 s[2:3], s[50:51]
	s_cbranch_execz .LBB0_1016
	v_add_co_u32_e32 v50, vcc, 0x16000, v66
	s_nop 1
	v_addc_co_u32_e32 v51, vcc, 0, v67, vcc
	global_store_dwordx4 v[50:51], v[78:81], off
	v_add_co_u32_e32 v50, vcc, 0x1b000, v66
	s_nop 1
	v_addc_co_u32_e32 v51, vcc, 0, v67, vcc
	global_store_dwordx4 v[50:51], v[74:77], off offset:2048
.LBB0_1016:
	s_or_b64 exec, exec, s[2:3]
	ds_read_b128 v[50:53], v89 offset:272
	ds_read_b128 v[62:65], v89 offset:400
	v_pk_fma_f32 v[34:35], v[34:35], v[58:59], v[46:47]
	v_pk_fma_f32 v[36:37], v[36:37], v[60:61], v[48:49]
	v_pk_fma_f32 v[34:35], v[38:39], v[78:79], v[34:35]
	v_pk_fma_f32 v[36:37], v[40:41], v[80:81], v[36:37]
	s_waitcnt lgkmcnt(1)
	v_pk_fma_f32 v[34:35], v[42:43], v[50:51], v[34:35]
	v_pk_fma_f32 v[36:37], v[44:45], v[52:53], v[36:37]
	v_mul_f32_e32 v38, 0xbfb8aa3b, v34
	v_mul_f32_e32 v39, 0xbfb8aa3b, v35
	v_exp_f32_e32 v38, v38
	v_exp_f32_e32 v39, v39
	v_mul_f32_e32 v40, 0xbfb8aa3b, v36
	v_mul_f32_e32 v41, 0xbfb8aa3b, v37
	v_exp_f32_e32 v40, v40
	v_pk_add_f32 v[38:39], v[38:39], 1.0 op_sel_hi:[1,0]
	v_exp_f32_e32 v41, v41
	v_pk_fma_f32 v[18:19], v[18:19], v[54:55], v[30:31]
	v_rcp_f32_e32 v42, v39
	s_nop 0
	v_mul_f32_e32 v35, v35, v42
	v_pk_add_f32 v[30:31], v[40:41], 1.0 op_sel_hi:[1,0]
	v_rcp_f32_e32 v39, v38
	s_nop 0
	v_mul_f32_e32 v34, v34, v39
	v_pk_fma_f32 v[18:19], v[22:23], v[74:75], v[18:19]
	v_pk_fma_f32 v[20:21], v[20:21], v[56:57], v[32:33]
	s_waitcnt lgkmcnt(0)
	v_pk_fma_f32 v[18:19], v[26:27], v[62:63], v[18:19]
	v_rcp_f32_e32 v22, v31
	s_nop 0
	v_mul_f32_e32 v23, v37, v22
	v_pk_mul_f32 v[18:19], v[34:35], v[18:19]
	v_pk_fma_f32 v[20:21], v[24:25], v[76:77], v[20:21]
	v_rcp_f32_e32 v22, v30
	s_nop 0
	v_mul_f32_e32 v22, v36, v22
	v_pk_fma_f32 v[20:21], v[28:29], v[64:65], v[20:21]
	v_or3_b32 v0, v142, v0, 7
	v_pk_mul_f32 v[20:21], v[22:23], v[20:21]
	v_cvt_pk_bf16_f32 v18, v18, v19
	v_cvt_pk_bf16_f32 v19, v20, v21
	v_mov_b64_e32 v[20:21], s[34:35]
	s_movk_i32 s2, 0x2c00
	v_mad_i64_i32 v[20:21], s[2:3], v0, s2, v[20:21]
	v_lshl_add_u64 v[20:21], v[130:131], 1, v[20:21]
	global_store_dwordx2 v[20:21], v[18:19], off
	s_and_saveexec_b64 s[2:3], s[50:51]
	s_cbranch_execz .LBB0_1018
	v_add_co_u32_e32 v18, vcc, 0x21000, v66
	s_nop 1
	v_addc_co_u32_e32 v19, vcc, 0, v67, vcc
	global_store_dwordx4 v[18:19], v[50:53], off
	v_add_co_u32_e32 v18, vcc, 0x26000, v66
	s_nop 1
	v_addc_co_u32_e32 v19, vcc, 0, v67, vcc
	global_store_dwordx4 v[18:19], v[62:65], off offset:2048

; DI void gemm_tile(const GD& g, int pm, int pn, bf16_t* shm) {
;     ...
;       for (int pb8 = 0; pb8 < 4; ++pb8) {
;         float4 xs[4];
;         if (g.epi == 1) {
; #pragma unroll
;           for (int q = 0; q < 4; ++q) {
;             const int grow = brow + ai * HALF + wr * 64 + (pb8 * 4 + q) * 4 + (lane >> 4);
;             xs[q] = *reinterpret_cast<const float4*>((const float*)g.C + (long)grow * ldc + gcol);
;           }
;         }
.LBB0_1027:
	s_andn2_b64 vcc, exec, s[2:3]
	s_cbranch_vccnz .LBB0_1292
	s_cmp_eq_u32 s48, 1
	s_cselect_b64 s[10:11], -1, 0
	s_cmp_lg_u32 s48, 1
	v_lshl_add_u64 v[30:31], v[94:95], 2, s[34:35]
	s_cbranch_scc1 .LBB0_1030
	v_add_u32_e32 v0, 0x80, v99
	v_mad_u64_u32 v[2:3], s[2:3], v0, s78, 0
	v_ashrrev_i32_e32 v4, 31, v0
	v_mov_b32_e32 v0, v3
	v_mad_u64_u32 v[4:5], s[2:3], v4, s78, v[0:1]
	v_add_u32_e32 v0, 0x84, v99
	v_mov_b32_e32 v3, v4
	v_mad_u64_u32 v[4:5], s[2:3], v0, s78, 0
	v_ashrrev_i32_e32 v6, 31, v0
	v_mov_b32_e32 v0, v5
	v_mad_u64_u32 v[6:7], s[2:3], v6, s78, v[0:1]
	v_lshl_add_u64 v[2:3], v[2:3], 2, v[30:31]
	v_mov_b32_e32 v5, v6
	v_add_u32_e32 v0, 0x88, v99
	v_lshl_add_u64 v[4:5], v[4:5], 2, v[30:31]
	global_load_dwordx4 v[14:17], v[2:3], off
	global_load_dwordx4 v[6:9], v[4:5], off
	v_mad_u64_u32 v[2:3], s[2:3], v0, s78, 0
	v_ashrrev_i32_e32 v4, 31, v0
	v_mov_b32_e32 v0, v3
	v_mad_u64_u32 v[4:5], s[2:3], v4, s78, v[0:1]
	v_add_u32_e32 v0, 0x8c, v99
	v_mov_b32_e32 v3, v4
	v_mad_u64_u32 v[4:5], s[2:3], v0, s78, 0
	v_ashrrev_i32_e32 v10, 31, v0
	v_mov_b32_e32 v0, v5
	v_mad_u64_u32 v[10:11], s[2:3], v10, s78, v[0:1]
	v_mov_b32_e32 v5, v10
	v_lshl_add_u64 v[2:3], v[2:3], 2, v[30:31]
	v_lshl_add_u64 v[4:5], v[4:5], 2, v[30:31]
	global_load_dwordx4 v[10:13], v[2:3], off
	s_nop 0
	global_load_dwordx4 v[2:5], v[4:5], off

; DI unsigned pk2(float a, float b) { f32x2 v; v[0] = a; v[1] = b; return __builtin_bit_cast(unsigned, __builtin_convertvector(v, bf16v2)); }
; DI float shx_(float v, int m) { return __int_as_float(__builtin_amdgcn_ds_bpermute((lane_pinned_() ^ m) << 2, __float_as_int(v))); }
; DI int shx_(int v, int m) { return __builtin_amdgcn_ds_bpermute((lane_pinned_() ^ m) << 2, v); }
; DI void gemm_tile(const GD& g, int pm, int pn, bf16_t* shm) {
;     ...
; #pragma unroll
;         for (int q = 0; q < 4; ++q) {
;           const int row_l = (pb8 * 4 + q) * 4 + (lane >> 4);
;           float4 v = *reinterpret_cast<const float4*>(stgw + row_l * 68 + c4);
;           const int grow = brow + ai * HALF + wr * 64 + row_l;
;           if (g.epi == 0) {
;             if (g.rowscale) {
;               const float rr = rsc[ai * HALF + wr * 64 + row_l];
;               v.x *= rr; v.y *= rr; v.z *= rr; v.w *= rr;
;             }
;             u32x2 o2; o2[0] = pk2(v.x, v.y); o2[1] = pk2(v.z, v.w);
;             *reinterpret_cast<u32x2*>((bf16_t*)g.C + (long)grow * ldc + gcol) = o2;
;           } else if (g.epi == 2) {
;             const float rr = rsc[ai * HALF + wr * 64 + row_l];
;             v.x *= rr; v.y *= rr; v.z *= rr; v.w *= rr;
;             *reinterpret_cast<float4*>((float*)g.C + (long)grow * ldc + gcol) = v;
;           } else {
;             float4 x = xs[q];
;             x.x += v.x; x.y += v.y; x.z += v.z; x.w += v.w;
;             *reinterpret_cast<float4*>((float*)g.C + (long)grow * ldc + gcol) = x;
;             if (g.gnext) {
;               u32x2 o2; o2[0] = pk2(x.x * gn.x, x.y * gn.y); o2[1] = pk2(x.z * gn.z, x.w * gn.w);
;               *reinterpret_cast<u32x2*>(g.hbout + (long)grow * DM + gcol) = o2;
;               float sq = (x.x * x.x + x.y * x.y) + (x.z * x.z + x.w * x.w);
;               sq += shx_(sq, 1); sq += shx_(sq, 2); sq += shx_(sq, 4); sq += shx_(sq, 8);
;               if ((lane & 15) == 0) g.ss[(long)grow * 32 + pn * 4 + wc] = sq;
;             }
.LBB0_1035:
	v_mad_u64_u32 v[36:37], s[2:3], v32, s78, 0
	v_mov_b32_e32 v0, v37
	v_mad_u64_u32 v[38:39], s[2:3], v33, s78, v[0:1]
	v_mov_b32_e32 v37, v38
	v_lshl_add_u64 v[36:37], v[36:37], 2, s[34:35]
	s_waitcnt vmcnt(0) lgkmcnt(0)
	v_pk_add_f32 v[26:27], v[14:15], v[22:23]
	v_pk_add_f32 v[28:29], v[16:17], v[24:25]
	v_lshl_add_u64 v[36:37], v[94:95], 2, v[36:37]
	s_cmp_eq_u64 s[80:81], 0
	global_store_dwordx4 v[36:37], v[26:29], off
	s_cbranch_scc1 .LBB0_1039
	v_pk_mul_f32 v[36:37], v[18:19], v[26:27]
	v_pk_mul_f32 v[38:39], v[20:21], v[28:29]
	v_cvt_pk_bf16_f32 v36, v36, v37
	v_cvt_pk_bf16_f32 v37, v38, v39
	v_lshlrev_b64 v[38:39], 12, v[32:33]
	v_pk_mul_f32 v[26:27], v[26:27], v[26:27]
	v_pk_mul_f32 v[28:29], v[28:29], v[28:29]
	v_lshl_add_u64 v[38:39], s[20:21], 0, v[38:39]
	v_add_f32_e32 v0, v28, v29
	v_add_f32_e32 v26, v26, v27
	v_lshl_add_u64 v[38:39], v[94:95], 1, v[38:39]
	v_add_f32_e32 v0, v26, v0
	v_mov_b32_e32 v26, v208
	global_store_dwordx2 v[38:39], v[36:37], off
	s_nop 0
	v_lshlrev_b32_e32 v26, 2, v26
	v_xor_b32_e32 v26, 4, v26
	ds_bpermute_b32 v26, v26, v0
	s_waitcnt lgkmcnt(0)
	v_add_f32_e32 v0, v0, v26
	v_mov_b32_e32 v26, v208
	s_nop 0
	v_lshlrev_b32_e32 v26, 2, v26
	v_xor_b32_e32 v26, 8, v26
	ds_bpermute_b32 v26, v26, v0
	s_waitcnt lgkmcnt(0)
	v_add_f32_e32 v0, v0, v26
	v_mov_b32_e32 v26, v208
	s_nop 0
	v_lshlrev_b32_e32 v26, 2, v26
	v_xor_b32_e32 v26, 16, v26
	ds_bpermute_b32 v26, v26, v0
	s_waitcnt lgkmcnt(0)
	v_add_f32_e32 v26, v0, v26
	v_mov_b32_e32 v0, v208
	s_nop 0
	v_lshlrev_b32_e32 v0, 2, v0
	v_xor_b32_e32 v0, 32, v0
	ds_bpermute_b32 v27, v0, v26
	s_and_saveexec_b64 s[2:3], s[4:5]
	s_cbranch_execz .LBB0_1038
	v_lshlrev_b64 v[28:29], 7, v[32:33]
	v_lshl_add_u64 v[28:29], s[42:43], 0, v[28:29]
	v_lshl_add_u64 v[28:29], s[0:1], 2, v[28:29]
	v_lshlrev_b32_e32 v0, 2, v139
	v_lshl_add_u64 v[28:29], v[28:29], 0, v[0:1]
	s_waitcnt lgkmcnt(0)
	v_add_f32_e32 v0, v26, v27
	global_store_dword v[28:29], v0, off

; DI unsigned pk2(float a, float b) { f32x2 v; v[0] = a; v[1] = b; return __builtin_bit_cast(unsigned, __builtin_convertvector(v, bf16v2)); }
; DI float shx_(float v, int m) { return __int_as_float(__builtin_amdgcn_ds_bpermute((lane_pinned_() ^ m) << 2, __float_as_int(v))); }
; DI int shx_(int v, int m) { return __builtin_amdgcn_ds_bpermute((lane_pinned_() ^ m) << 2, v); }
; DI void gemm_tile(const GD& g, int pm, int pn, bf16_t* shm) {
;     ...
; #pragma unroll
;         for (int q = 0; q < 4; ++q) {
;           const int row_l = (pb8 * 4 + q) * 4 + (lane >> 4);
;           float4 v = *reinterpret_cast<const float4*>(stgw + row_l * 68 + c4);
;           const int grow = brow + ai * HALF + wr * 64 + row_l;
;           if (g.epi == 0) {
;             if (g.rowscale) {
;               const float rr = rsc[ai * HALF + wr * 64 + row_l];
;               v.x *= rr; v.y *= rr; v.z *= rr; v.w *= rr;
;             }
;             u32x2 o2; o2[0] = pk2(v.x, v.y); o2[1] = pk2(v.z, v.w);
;             *reinterpret_cast<u32x2*>((bf16_t*)g.C + (long)grow * ldc + gcol) = o2;
;           } else if (g.epi == 2) {
;             const float rr = rsc[ai * HALF + wr * 64 + row_l];
;             v.x *= rr; v.y *= rr; v.z *= rr; v.w *= rr;
;             *reinterpret_cast<float4*>((float*)g.C + (long)grow * ldc + gcol) = v;
;           } else {
;             float4 x = xs[q];
;             x.x += v.x; x.y += v.y; x.z += v.z; x.w += v.w;
;             *reinterpret_cast<float4*>((float*)g.C + (long)grow * ldc + gcol) = x;
;             if (g.gnext) {
;               u32x2 o2; o2[0] = pk2(x.x * gn.x, x.y * gn.y); o2[1] = pk2(x.z * gn.z, x.w * gn.w);
;               *reinterpret_cast<u32x2*>(g.hbout + (long)grow * DM + gcol) = o2;
;               float sq = (x.x * x.x + x.y * x.y) + (x.z * x.z + x.w * x.w);
;               sq += shx_(sq, 1); sq += shx_(sq, 2); sq += shx_(sq, 4); sq += shx_(sq, 8);
;               if ((lane & 15) == 0) g.ss[(long)grow * 32 + pn * 4 + wc] = sq;
;             }
.LBB0_1051:
	v_mad_u64_u32 v[36:37], s[2:3], v32, s78, 0
	v_mov_b32_e32 v0, v37
	v_mad_u64_u32 v[38:39], s[2:3], v33, s78, v[0:1]
	v_mov_b32_e32 v37, v38
	v_lshl_add_u64 v[36:37], v[36:37], 2, s[34:35]
	s_waitcnt lgkmcnt(0)
	v_pk_add_f32 v[26:27], v[6:7], v[22:23]
	v_pk_add_f32 v[28:29], v[8:9], v[24:25]
	v_lshl_add_u64 v[36:37], v[94:95], 2, v[36:37]
	s_cmp_eq_u64 s[80:81], 0
	global_store_dwordx4 v[36:37], v[26:29], off
	s_cbranch_scc1 .LBB0_1055
	v_pk_mul_f32 v[36:37], v[18:19], v[26:27]
	v_pk_mul_f32 v[38:39], v[20:21], v[28:29]
	v_cvt_pk_bf16_f32 v36, v36, v37
	v_cvt_pk_bf16_f32 v37, v38, v39
	v_lshlrev_b64 v[38:39], 12, v[32:33]
	v_pk_mul_f32 v[26:27], v[26:27], v[26:27]
	v_pk_mul_f32 v[28:29], v[28:29], v[28:29]
	v_lshl_add_u64 v[38:39], s[20:21], 0, v[38:39]
	v_add_f32_e32 v0, v28, v29
	v_add_f32_e32 v26, v26, v27
	v_lshl_add_u64 v[38:39], v[94:95], 1, v[38:39]
	v_add_f32_e32 v0, v26, v0
	v_mov_b32_e32 v26, v208
	global_store_dwordx2 v[38:39], v[36:37], off
	s_nop 0
	v_lshlrev_b32_e32 v26, 2, v26
	v_xor_b32_e32 v26, 4, v26
	ds_bpermute_b32 v26, v26, v0
	s_waitcnt lgkmcnt(0)
	v_add_f32_e32 v0, v0, v26
	v_mov_b32_e32 v26, v208
	s_nop 0
	v_lshlrev_b32_e32 v26, 2, v26
	v_xor_b32_e32 v26, 8, v26
	ds_bpermute_b32 v26, v26, v0
	s_waitcnt lgkmcnt(0)
	v_add_f32_e32 v0, v0, v26
	v_mov_b32_e32 v26, v208
	s_nop 0
	v_lshlrev_b32_e32 v26, 2, v26
	v_xor_b32_e32 v26, 16, v26
	ds_bpermute_b32 v26, v26, v0
	s_waitcnt lgkmcnt(0)
	v_add_f32_e32 v26, v0, v26
	v_mov_b32_e32 v0, v208
	s_nop 0
	v_lshlrev_b32_e32 v0, 2, v0
	v_xor_b32_e32 v0, 32, v0
	ds_bpermute_b32 v27, v0, v26
	s_and_saveexec_b64 s[2:3], s[4:5]
	s_cbranch_execz .LBB0_1054
	v_lshlrev_b64 v[28:29], 7, v[32:33]
	v_lshl_add_u64 v[28:29], s[42:43], 0, v[28:29]
	v_lshl_add_u64 v[28:29], s[0:1], 2, v[28:29]
	v_lshlrev_b32_e32 v0, 2, v139
	v_lshl_add_u64 v[28:29], v[28:29], 0, v[0:1]
	s_waitcnt lgkmcnt(0)
	v_add_f32_e32 v0, v26, v27
	global_store_dword v[28:29], v0, off

; DI unsigned pk2(float a, float b) { f32x2 v; v[0] = a; v[1] = b; return __builtin_bit_cast(unsigned, __builtin_convertvector(v, bf16v2)); }
; DI float shx_(float v, int m) { return __int_as_float(__builtin_amdgcn_ds_bpermute((lane_pinned_() ^ m) << 2, __float_as_int(v))); }
; DI int shx_(int v, int m) { return __builtin_amdgcn_ds_bpermute((lane_pinned_() ^ m) << 2, v); }
; DI void gemm_tile(const GD& g, int pm, int pn, bf16_t* shm) {
;     ...
; #pragma unroll
;         for (int q = 0; q < 4; ++q) {
;           const int row_l = (pb8 * 4 + q) * 4 + (lane >> 4);
;           float4 v = *reinterpret_cast<const float4*>(stgw + row_l * 68 + c4);
;           const int grow = brow + ai * HALF + wr * 64 + row_l;
;           if (g.epi == 0) {
;             if (g.rowscale) {
;               const float rr = rsc[ai * HALF + wr * 64 + row_l];
;               v.x *= rr; v.y *= rr; v.z *= rr; v.w *= rr;
;             }
;             u32x2 o2; o2[0] = pk2(v.x, v.y); o2[1] = pk2(v.z, v.w);
;             *reinterpret_cast<u32x2*>((bf16_t*)g.C + (long)grow * ldc + gcol) = o2;
;           } else if (g.epi == 2) {
;             const float rr = rsc[ai * HALF + wr * 64 + row_l];
;             v.x *= rr; v.y *= rr; v.z *= rr; v.w *= rr;
;             *reinterpret_cast<float4*>((float*)g.C + (long)grow * ldc + gcol) = v;
;           } else {
;             float4 x = xs[q];
;             x.x += v.x; x.y += v.y; x.z += v.z; x.w += v.w;
;             *reinterpret_cast<float4*>((float*)g.C + (long)grow * ldc + gcol) = x;
;             if (g.gnext) {
;               u32x2 o2; o2[0] = pk2(x.x * gn.x, x.y * gn.y); o2[1] = pk2(x.z * gn.z, x.w * gn.w);
;               *reinterpret_cast<u32x2*>(g.hbout + (long)grow * DM + gcol) = o2;
;               float sq = (x.x * x.x + x.y * x.y) + (x.z * x.z + x.w * x.w);
;               sq += shx_(sq, 1); sq += shx_(sq, 2); sq += shx_(sq, 4); sq += shx_(sq, 8);
;               if ((lane & 15) == 0) g.ss[(long)grow * 32 + pn * 4 + wc] = sq;
;             }
.LBB0_1067:
	v_mad_u64_u32 v[36:37], s[2:3], v32, s78, 0
	v_mov_b32_e32 v0, v37
	v_mad_u64_u32 v[38:39], s[2:3], v33, s78, v[0:1]
	v_mov_b32_e32 v37, v38
	v_lshl_add_u64 v[36:37], v[36:37], 2, s[34:35]
	s_waitcnt lgkmcnt(0)
	v_pk_add_f32 v[26:27], v[10:11], v[22:23]
	v_pk_add_f32 v[28:29], v[12:13], v[24:25]
	v_lshl_add_u64 v[36:37], v[94:95], 2, v[36:37]
	s_cmp_eq_u64 s[80:81], 0
	global_store_dwordx4 v[36:37], v[26:29], off
	s_cbranch_scc1 .LBB0_1071
	v_pk_mul_f32 v[36:37], v[18:19], v[26:27]
	v_pk_mul_f32 v[38:39], v[20:21], v[28:29]
	v_cvt_pk_bf16_f32 v36, v36, v37
	v_cvt_pk_bf16_f32 v37, v38, v39
	v_lshlrev_b64 v[38:39], 12, v[32:33]
	v_pk_mul_f32 v[26:27], v[26:27], v[26:27]
	v_pk_mul_f32 v[28:29], v[28:29], v[28:29]
	v_lshl_add_u64 v[38:39], s[20:21], 0, v[38:39]
	v_add_f32_e32 v0, v28, v29
	v_add_f32_e32 v26, v26, v27
	v_lshl_add_u64 v[38:39], v[94:95], 1, v[38:39]
	v_add_f32_e32 v0, v26, v0
	v_mov_b32_e32 v26, v208
	global_store_dwordx2 v[38:39], v[36:37], off
	s_nop 0
	v_lshlrev_b32_e32 v26, 2, v26
	v_xor_b32_e32 v26, 4, v26
	ds_bpermute_b32 v26, v26, v0
	s_waitcnt lgkmcnt(0)
	v_add_f32_e32 v0, v0, v26
	v_mov_b32_e32 v26, v208
	s_nop 0
	v_lshlrev_b32_e32 v26, 2, v26
	v_xor_b32_e32 v26, 8, v26
	ds_bpermute_b32 v26, v26, v0
	s_waitcnt lgkmcnt(0)
	v_add_f32_e32 v0, v0, v26
	v_mov_b32_e32 v26, v208
	s_nop 0
	v_lshlrev_b32_e32 v26, 2, v26
	v_xor_b32_e32 v26, 16, v26
	ds_bpermute_b32 v26, v26, v0
	s_waitcnt lgkmcnt(0)
	v_add_f32_e32 v26, v0, v26
	v_mov_b32_e32 v0, v208
	s_nop 0
	v_lshlrev_b32_e32 v0, 2, v0
	v_xor_b32_e32 v0, 32, v0
	ds_bpermute_b32 v27, v0, v26
	s_and_saveexec_b64 s[2:3], s[4:5]
	s_cbranch_execz .LBB0_1070
	v_lshlrev_b64 v[28:29], 7, v[32:33]
	v_lshl_add_u64 v[28:29], s[42:43], 0, v[28:29]
	v_lshl_add_u64 v[28:29], s[0:1], 2, v[28:29]
	v_lshlrev_b32_e32 v0, 2, v139
	v_lshl_add_u64 v[28:29], v[28:29], 0, v[0:1]
	s_waitcnt lgkmcnt(0)
	v_add_f32_e32 v0, v26, v27
	global_store_dword v[28:29], v0, off

; DI unsigned pk2(float a, float b) { f32x2 v; v[0] = a; v[1] = b; return __builtin_bit_cast(unsigned, __builtin_convertvector(v, bf16v2)); }
; DI float shx_(float v, int m) { return __int_as_float(__builtin_amdgcn_ds_bpermute((lane_pinned_() ^ m) << 2, __float_as_int(v))); }
; DI int shx_(int v, int m) { return __builtin_amdgcn_ds_bpermute((lane_pinned_() ^ m) << 2, v); }
; DI void gemm_tile(const GD& g, int pm, int pn, bf16_t* shm) {
;     ...
; #pragma unroll
;         for (int q = 0; q < 4; ++q) {
;           const int row_l = (pb8 * 4 + q) * 4 + (lane >> 4);
;           float4 v = *reinterpret_cast<const float4*>(stgw + row_l * 68 + c4);
;           const int grow = brow + ai * HALF + wr * 64 + row_l;
;           if (g.epi == 0) {
;             if (g.rowscale) {
;               const float rr = rsc[ai * HALF + wr * 64 + row_l];
;               v.x *= rr; v.y *= rr; v.z *= rr; v.w *= rr;
;             }
;             u32x2 o2; o2[0] = pk2(v.x, v.y); o2[1] = pk2(v.z, v.w);
;             *reinterpret_cast<u32x2*>((bf16_t*)g.C + (long)grow * ldc + gcol) = o2;
;           } else if (g.epi == 2) {
;             const float rr = rsc[ai * HALF + wr * 64 + row_l];
;             v.x *= rr; v.y *= rr; v.z *= rr; v.w *= rr;
;             *reinterpret_cast<float4*>((float*)g.C + (long)grow * ldc + gcol) = v;
;           } else {
;             float4 x = xs[q];
;             x.x += v.x; x.y += v.y; x.z += v.z; x.w += v.w;
;             *reinterpret_cast<float4*>((float*)g.C + (long)grow * ldc + gcol) = x;
;             if (g.gnext) {
;               u32x2 o2; o2[0] = pk2(x.x * gn.x, x.y * gn.y); o2[1] = pk2(x.z * gn.z, x.w * gn.w);
;               *reinterpret_cast<u32x2*>(g.hbout + (long)grow * DM + gcol) = o2;
;               float sq = (x.x * x.x + x.y * x.y) + (x.z * x.z + x.w * x.w);
;               sq += shx_(sq, 1); sq += shx_(sq, 2); sq += shx_(sq, 4); sq += shx_(sq, 8);
;               if ((lane & 15) == 0) g.ss[(long)grow * 32 + pn * 4 + wc] = sq;
;             }
.LBB0_1083:
	v_mad_u64_u32 v[36:37], s[2:3], v32, s78, 0
	v_mov_b32_e32 v0, v37
	v_mad_u64_u32 v[38:39], s[2:3], v33, s78, v[0:1]
	v_mov_b32_e32 v37, v38
	v_lshl_add_u64 v[36:37], v[36:37], 2, s[34:35]
	s_waitcnt lgkmcnt(0)
	v_pk_add_f32 v[26:27], v[2:3], v[22:23]
	v_pk_add_f32 v[28:29], v[4:5], v[24:25]
	v_lshl_add_u64 v[36:37], v[94:95], 2, v[36:37]
	s_cmp_eq_u64 s[80:81], 0
	global_store_dwordx4 v[36:37], v[26:29], off
	s_cbranch_scc1 .LBB0_1087
	v_pk_mul_f32 v[36:37], v[18:19], v[26:27]
	v_pk_mul_f32 v[38:39], v[20:21], v[28:29]
	v_cvt_pk_bf16_f32 v36, v36, v37
	v_cvt_pk_bf16_f32 v37, v38, v39
	v_lshlrev_b64 v[38:39], 12, v[32:33]
	v_pk_mul_f32 v[26:27], v[26:27], v[26:27]
	v_pk_mul_f32 v[28:29], v[28:29], v[28:29]
	v_lshl_add_u64 v[38:39], s[20:21], 0, v[38:39]
	v_add_f32_e32 v0, v28, v29
	v_add_f32_e32 v26, v26, v27
	v_lshl_add_u64 v[38:39], v[94:95], 1, v[38:39]
	v_add_f32_e32 v0, v26, v0
	v_mov_b32_e32 v26, v208
	global_store_dwordx2 v[38:39], v[36:37], off
	s_nop 0
	v_lshlrev_b32_e32 v26, 2, v26
	v_xor_b32_e32 v26, 4, v26
	ds_bpermute_b32 v26, v26, v0
	s_waitcnt lgkmcnt(0)
	v_add_f32_e32 v0, v0, v26
	v_mov_b32_e32 v26, v208
	s_nop 0
	v_lshlrev_b32_e32 v26, 2, v26
	v_xor_b32_e32 v26, 8, v26
	ds_bpermute_b32 v26, v26, v0
	s_waitcnt lgkmcnt(0)
	v_add_f32_e32 v0, v0, v26
	v_mov_b32_e32 v26, v208
	s_nop 0
	v_lshlrev_b32_e32 v26, 2, v26
	v_xor_b32_e32 v26, 16, v26
	ds_bpermute_b32 v26, v26, v0
	s_waitcnt lgkmcnt(0)
	v_add_f32_e32 v26, v0, v26
	v_mov_b32_e32 v0, v208
	s_nop 0
	v_lshlrev_b32_e32 v0, 2, v0
	v_xor_b32_e32 v0, 32, v0
	ds_bpermute_b32 v27, v0, v26
	s_and_saveexec_b64 s[2:3], s[4:5]
	s_cbranch_execz .LBB0_1086
	v_lshlrev_b64 v[28:29], 7, v[32:33]
	v_lshl_add_u64 v[28:29], s[42:43], 0, v[28:29]
	v_lshl_add_u64 v[28:29], s[0:1], 2, v[28:29]
	v_lshlrev_b32_e32 v0, 2, v139
	v_lshl_add_u64 v[28:29], v[28:29], 0, v[0:1]
	s_waitcnt lgkmcnt(0)
	v_add_f32_e32 v0, v26, v27
	global_store_dword v[28:29], v0, off

; DI void gemm_tile(const GD& g, int pm, int pn, bf16_t* shm) {
;     ...
;       for (int pb8 = 0; pb8 < 4; ++pb8) {
;         float4 xs[4];
;         if (g.epi == 1) {
; #pragma unroll
;           for (int q = 0; q < 4; ++q) {
;             const int grow = brow + ai * HALF + wr * 64 + (pb8 * 4 + q) * 4 + (lane >> 4);
;             xs[q] = *reinterpret_cast<const float4*>((const float*)g.C + (long)grow * ldc + gcol);
;           }
;         }
.LBB0_1089:
	v_add_u32_e32 v0, 0x90, v99
	v_mad_u64_u32 v[2:3], s[2:3], v0, s78, 0
	v_ashrrev_i32_e32 v4, 31, v0
	v_mov_b32_e32 v0, v3
	v_mad_u64_u32 v[4:5], s[2:3], v4, s78, v[0:1]
	v_add_u32_e32 v0, 0x94, v99
	v_mov_b32_e32 v3, v4
	v_mad_u64_u32 v[4:5], s[2:3], v0, s78, 0
	v_ashrrev_i32_e32 v6, 31, v0
	v_mov_b32_e32 v0, v5
	v_mad_u64_u32 v[6:7], s[2:3], v6, s78, v[0:1]
	v_lshl_add_u64 v[2:3], v[2:3], 2, v[30:31]
	v_mov_b32_e32 v5, v6
	v_add_u32_e32 v0, 0x98, v99
	v_lshl_add_u64 v[4:5], v[4:5], 2, v[30:31]
	global_load_dwordx4 v[14:17], v[2:3], off
	global_load_dwordx4 v[6:9], v[4:5], off
	v_mad_u64_u32 v[2:3], s[2:3], v0, s78, 0
	v_ashrrev_i32_e32 v4, 31, v0
	v_mov_b32_e32 v0, v3
	v_mad_u64_u32 v[4:5], s[2:3], v4, s78, v[0:1]
	v_add_u32_e32 v0, 0x9c, v99
	v_mov_b32_e32 v3, v4
	v_mad_u64_u32 v[4:5], s[2:3], v0, s78, 0
	v_ashrrev_i32_e32 v10, 31, v0
	v_mov_b32_e32 v0, v5
	v_mad_u64_u32 v[10:11], s[2:3], v10, s78, v[0:1]
	v_mov_b32_e32 v5, v10
	v_lshl_add_u64 v[2:3], v[2:3], 2, v[30:31]
	v_lshl_add_u64 v[4:5], v[4:5], 2, v[30:31]
	global_load_dwordx4 v[10:13], v[2:3], off
	s_nop 0
	global_load_dwordx4 v[2:5], v[4:5], off

; DI void gemm_tile(const GD& g, int pm, int pn, bf16_t* shm) {
;     ...
;       for (int pb8 = 0; pb8 < 4; ++pb8) {
;         float4 xs[4];
;         if (g.epi == 1) {
; #pragma unroll
;           for (int q = 0; q < 4; ++q) {
;             const int grow = brow + ai * HALF + wr * 64 + (pb8 * 4 + q) * 4 + (lane >> 4);
;             xs[q] = *reinterpret_cast<const float4*>((const float*)g.C + (long)grow * ldc + gcol);
;           }
;         }
.LBB0_1155:
	v_add_u32_e32 v0, 0xa0, v99
	v_mad_u64_u32 v[2:3], s[2:3], v0, s78, 0
	v_ashrrev_i32_e32 v4, 31, v0
	v_mov_b32_e32 v0, v3
	v_mad_u64_u32 v[4:5], s[2:3], v4, s78, v[0:1]
	v_add_u32_e32 v0, 0xa4, v99
	v_mov_b32_e32 v3, v4
	v_mad_u64_u32 v[4:5], s[2:3], v0, s78, 0
	v_ashrrev_i32_e32 v6, 31, v0
	v_mov_b32_e32 v0, v5
	v_mad_u64_u32 v[6:7], s[2:3], v6, s78, v[0:1]
	v_lshl_add_u64 v[2:3], v[2:3], 2, v[30:31]
	v_mov_b32_e32 v5, v6
	v_add_u32_e32 v0, 0xa8, v99
	v_lshl_add_u64 v[4:5], v[4:5], 2, v[30:31]
	global_load_dwordx4 v[14:17], v[2:3], off
	global_load_dwordx4 v[6:9], v[4:5], off
	v_mad_u64_u32 v[2:3], s[2:3], v0, s78, 0
	v_ashrrev_i32_e32 v4, 31, v0
	v_mov_b32_e32 v0, v3
	v_mad_u64_u32 v[4:5], s[2:3], v4, s78, v[0:1]
	v_add_u32_e32 v0, 0xac, v99
	v_mov_b32_e32 v3, v4
	v_mad_u64_u32 v[4:5], s[2:3], v0, s78, 0
	v_ashrrev_i32_e32 v10, 31, v0
	v_mov_b32_e32 v0, v5
	v_mad_u64_u32 v[10:11], s[2:3], v10, s78, v[0:1]
	v_mov_b32_e32 v5, v10
	v_lshl_add_u64 v[2:3], v[2:3], 2, v[30:31]
	v_lshl_add_u64 v[4:5], v[4:5], 2, v[30:31]
	global_load_dwordx4 v[10:13], v[2:3], off
	s_nop 0
	global_load_dwordx4 v[2:5], v[4:5], off

; DI void gemm_tile(const GD& g, int pm, int pn, bf16_t* shm) {
;     ...
;       for (int pb8 = 0; pb8 < 4; ++pb8) {
;         float4 xs[4];
;         if (g.epi == 1) {
; #pragma unroll
;           for (int q = 0; q < 4; ++q) {
;             const int grow = brow + ai * HALF + wr * 64 + (pb8 * 4 + q) * 4 + (lane >> 4);
;             xs[q] = *reinterpret_cast<const float4*>((const float*)g.C + (long)grow * ldc + gcol);
;           }
;         }
.LBB0_1221:
	v_add_u32_e32 v0, 0xb0, v99
	v_mad_u64_u32 v[2:3], s[2:3], v0, s78, 0
	v_ashrrev_i32_e32 v4, 31, v0
	v_mov_b32_e32 v0, v3
	v_mad_u64_u32 v[4:5], s[2:3], v4, s78, v[0:1]
	v_add_u32_e32 v0, 0xb4, v99
	v_mov_b32_e32 v3, v4
	v_mad_u64_u32 v[4:5], s[2:3], v0, s78, 0
	v_ashrrev_i32_e32 v6, 31, v0
	v_mov_b32_e32 v0, v5
	v_mad_u64_u32 v[6:7], s[2:3], v6, s78, v[0:1]
	v_lshl_add_u64 v[2:3], v[2:3], 2, v[30:31]
	v_mov_b32_e32 v5, v6
	v_add_u32_e32 v0, 0xb8, v99
	v_lshl_add_u64 v[4:5], v[4:5], 2, v[30:31]
	global_load_dwordx4 v[14:17], v[2:3], off
	global_load_dwordx4 v[6:9], v[4:5], off
	v_mad_u64_u32 v[2:3], s[2:3], v0, s78, 0
	v_ashrrev_i32_e32 v4, 31, v0
	v_mov_b32_e32 v0, v3
	v_mad_u64_u32 v[4:5], s[2:3], v4, s78, v[0:1]
	v_add_u32_e32 v0, 0xbc, v99
	v_mov_b32_e32 v3, v4
	v_mad_u64_u32 v[4:5], s[2:3], v0, s78, 0
	v_ashrrev_i32_e32 v10, 31, v0
	v_mov_b32_e32 v0, v5
	v_mad_u64_u32 v[10:11], s[2:3], v10, s78, v[0:1]
	v_mov_b32_e32 v5, v10
	v_lshl_add_u64 v[2:3], v[2:3], 2, v[30:31]
	v_lshl_add_u64 v[4:5], v[4:5], 2, v[30:31]
	global_load_dwordx4 v[10:13], v[2:3], off
	s_nop 0
	global_load_dwordx4 v[2:5], v[4:5], off

; DI unsigned pk2(float a, float b) { f32x2 v; v[0] = a; v[1] = b; return __builtin_bit_cast(unsigned, __builtin_convertvector(v, bf16v2)); }
; DI float shx_(float v, int m) { return __int_as_float(__builtin_amdgcn_ds_bpermute((lane_pinned_() ^ m) << 2, __float_as_int(v))); }
; DI int shx_(int v, int m) { return __builtin_amdgcn_ds_bpermute((lane_pinned_() ^ m) << 2, v); }
; DI void gemm_tile(const GD& g, int pm, int pn, bf16_t* shm) {
;     ...
; #pragma unroll
;         for (int q = 0; q < 4; ++q) {
;           const int row_l = (pb8 * 4 + q) * 4 + (lane >> 4);
;           float4 v = *reinterpret_cast<const float4*>(stgw + row_l * 68 + c4);
;           const int grow = brow + ai * HALF + wr * 64 + row_l;
;           if (g.epi == 0) {
;             if (g.rowscale) {
;               const float rr = rsc[ai * HALF + wr * 64 + row_l];
;               v.x *= rr; v.y *= rr; v.z *= rr; v.w *= rr;
;             }
;             u32x2 o2; o2[0] = pk2(v.x, v.y); o2[1] = pk2(v.z, v.w);
;             *reinterpret_cast<u32x2*>((bf16_t*)g.C + (long)grow * ldc + gcol) = o2;
;           } else if (g.epi == 2) {
;             const float rr = rsc[ai * HALF + wr * 64 + row_l];
;             v.x *= rr; v.y *= rr; v.z *= rr; v.w *= rr;
;             *reinterpret_cast<float4*>((float*)g.C + (long)grow * ldc + gcol) = v;
;           } else {
;             float4 x = xs[q];
;             x.x += v.x; x.y += v.y; x.z += v.z; x.w += v.w;
;             *reinterpret_cast<float4*>((float*)g.C + (long)grow * ldc + gcol) = x;
;             if (g.gnext) {
;               u32x2 o2; o2[0] = pk2(x.x * gn.x, x.y * gn.y); o2[1] = pk2(x.z * gn.z, x.w * gn.w);
;               *reinterpret_cast<u32x2*>(g.hbout + (long)grow * DM + gcol) = o2;
;               float sq = (x.x * x.x + x.y * x.y) + (x.z * x.z + x.w * x.w);
;               sq += shx_(sq, 1); sq += shx_(sq, 2); sq += shx_(sq, 4); sq += shx_(sq, 8);
;               if ((lane & 15) == 0) g.ss[(long)grow * 32 + pn * 4 + wc] = sq;
;             }
.LBB0_1227:
	v_mad_u64_u32 v[28:29], s[2:3], v26, s78, 0
	v_mov_b32_e32 v0, v29
	v_mad_u64_u32 v[30:31], s[2:3], v27, s78, v[0:1]
	v_mov_b32_e32 v29, v30
	v_lshl_add_u64 v[28:29], v[28:29], 2, s[34:35]
	s_waitcnt vmcnt(0) lgkmcnt(0)
	v_pk_add_f32 v[14:15], v[14:15], v[22:23]
	v_pk_add_f32 v[16:17], v[16:17], v[24:25]
	v_lshl_add_u64 v[28:29], v[94:95], 2, v[28:29]
	s_cmp_eq_u64 s[80:81], 0
	global_store_dwordx4 v[28:29], v[14:17], off
	s_cbranch_scc1 .LBB0_1231
	v_pk_mul_f32 v[28:29], v[18:19], v[14:15]
	v_pk_mul_f32 v[30:31], v[20:21], v[16:17]
	v_cvt_pk_bf16_f32 v28, v28, v29
	v_cvt_pk_bf16_f32 v29, v30, v31
	v_lshlrev_b64 v[30:31], 12, v[26:27]
	v_pk_mul_f32 v[14:15], v[14:15], v[14:15]
	v_pk_mul_f32 v[16:17], v[16:17], v[16:17]
	v_lshl_add_u64 v[30:31], s[20:21], 0, v[30:31]
	v_add_f32_e32 v0, v16, v17
	v_add_f32_e32 v14, v14, v15
	v_lshl_add_u64 v[30:31], v[94:95], 1, v[30:31]
	v_add_f32_e32 v0, v14, v0
	v_mov_b32_e32 v14, v208
	global_store_dwordx2 v[30:31], v[28:29], off
	s_nop 0
	v_lshlrev_b32_e32 v14, 2, v14
	v_xor_b32_e32 v14, 4, v14
	ds_bpermute_b32 v14, v14, v0
	s_waitcnt lgkmcnt(0)
	v_add_f32_e32 v0, v0, v14
	v_mov_b32_e32 v14, v208
	s_nop 0
	v_lshlrev_b32_e32 v14, 2, v14
	v_xor_b32_e32 v14, 8, v14
	ds_bpermute_b32 v14, v14, v0
	s_waitcnt lgkmcnt(0)
	v_add_f32_e32 v0, v0, v14
	v_mov_b32_e32 v14, v208
	s_nop 0
	v_lshlrev_b32_e32 v14, 2, v14
	v_xor_b32_e32 v14, 16, v14
	ds_bpermute_b32 v14, v14, v0
	s_waitcnt lgkmcnt(0)
	v_add_f32_e32 v14, v0, v14
	v_mov_b32_e32 v0, v208
	s_nop 0
	v_lshlrev_b32_e32 v0, 2, v0
	v_xor_b32_e32 v0, 32, v0
	ds_bpermute_b32 v15, v0, v14
	s_and_saveexec_b64 s[2:3], s[4:5]
	s_cbranch_execz .LBB0_1230
	v_lshlrev_b64 v[16:17], 7, v[26:27]
	v_lshl_add_u64 v[16:17], s[42:43], 0, v[16:17]
	v_lshl_add_u64 v[16:17], s[0:1], 2, v[16:17]
	v_lshlrev_b32_e32 v0, 2, v139
	v_lshl_add_u64 v[16:17], v[16:17], 0, v[0:1]
	s_waitcnt lgkmcnt(0)
	v_add_f32_e32 v0, v14, v15
	global_store_dword v[16:17], v0, off

; DI unsigned pk2(float a, float b) { f32x2 v; v[0] = a; v[1] = b; return __builtin_bit_cast(unsigned, __builtin_convertvector(v, bf16v2)); }
; DI void gemm_tile(const GD& g, int pm, int pn, bf16_t* shm) {
;     ...
;           float4 v = *reinterpret_cast<const float4*>(stgw + row_l * 68 + c4);
;           const int grow = brow + ai * HALF + wr * 64 + row_l;
;           if (g.epi == 0) {
;             if (g.rowscale) {
;               const float rr = rsc[ai * HALF + wr * 64 + row_l];
;               v.x *= rr; v.y *= rr; v.z *= rr; v.w *= rr;
;             }
;             u32x2 o2; o2[0] = pk2(v.x, v.y); o2[1] = pk2(v.z, v.w);
;             *reinterpret_cast<u32x2*>((bf16_t*)g.C + (long)grow * ldc + gcol) = o2;
;           } else if (g.epi == 2) {
;             const float rr = rsc[ai * HALF + wr * 64 + row_l];
;             v.x *= rr; v.y *= rr; v.z *= rr; v.w *= rr;
;             *reinterpret_cast<float4*>((float*)g.C + (long)grow * ldc + gcol) = v;
.LBB0_1243:
	v_mad_u64_u32 v[16:17], s[2:3], v26, s78, 0
	v_mov_b32_e32 v0, v17
	s_waitcnt lgkmcnt(0)
	v_cvt_pk_bf16_f32 v14, v22, v23
	v_mad_u64_u32 v[22:23], s[2:3], v27, s78, v[0:1]
	v_mov_b32_e32 v17, v22
	v_lshl_add_u64 v[16:17], v[16:17], 1, s[34:35]
	v_cvt_pk_bf16_f32 v15, v24, v25
	v_lshl_add_u64 v[16:17], v[94:95], 1, v[16:17]
	global_store_dwordx2 v[16:17], v[14:15], off
.LBB0_1244:
	s_waitcnt lgkmcnt(0)
	ds_read_b128 v[14:17], v35 offset:14144
	v_or3_b32 v22, v138, v34, 52
	s_mov_b64 s[10:11], -1
	s_mov_b64 s[2:3], 0
	s_cmp_lt_i32 s48, 2
	s_mov_b64 s[8:9], 0
	s_cbranch_scc1 .LBB0_1254
	s_cmp_eq_u32 s48, 2
	s_mov_b64 s[8:9], -1
	s_cbranch_scc0 .LBB0_1247
	v_lshl_add_u32 v0, v138, 2, v98
	ds_read_b32 v0, v0 offset:720
	v_mad_u64_u32 v[24:25], s[8:9], v22, s78, 0
	v_ashrrev_i32_e32 v23, 31, v22
	v_mov_b32_e32 v26, v25
	v_mad_u64_u32 v[26:27], s[8:9], v23, s78, v[26:27]
	v_mov_b32_e32 v25, v26
	v_lshl_add_u64 v[24:25], v[24:25], 2, s[34:35]
	v_lshl_add_u64 v[28:29], v[94:95], 2, v[24:25]
	s_waitcnt lgkmcnt(0)
	v_pk_mul_f32 v[24:25], v[14:15], v[0:1] op_sel_hi:[1,0]
	v_pk_mul_f32 v[26:27], v[16:17], v[0:1] op_sel_hi:[1,0]
	global_store_dwordx4 v[28:29], v[24:27], off
	s_mov_b64 s[8:9], 0

; DI unsigned pk2(float a, float b) { f32x2 v; v[0] = a; v[1] = b; return __builtin_bit_cast(unsigned, __builtin_convertvector(v, bf16v2)); }
; DI float shx_(float v, int m) { return __int_as_float(__builtin_amdgcn_ds_bpermute((lane_pinned_() ^ m) << 2, __float_as_int(v))); }
; DI int shx_(int v, int m) { return __builtin_amdgcn_ds_bpermute((lane_pinned_() ^ m) << 2, v); }
; DI void gemm_tile(const GD& g, int pm, int pn, bf16_t* shm) {
;     ...
; #pragma unroll
;         for (int q = 0; q < 4; ++q) {
;           const int row_l = (pb8 * 4 + q) * 4 + (lane >> 4);
;           float4 v = *reinterpret_cast<const float4*>(stgw + row_l * 68 + c4);
;           const int grow = brow + ai * HALF + wr * 64 + row_l;
;           if (g.epi == 0) {
;             if (g.rowscale) {
;               const float rr = rsc[ai * HALF + wr * 64 + row_l];
;               v.x *= rr; v.y *= rr; v.z *= rr; v.w *= rr;
;             }
;             u32x2 o2; o2[0] = pk2(v.x, v.y); o2[1] = pk2(v.z, v.w);
;             *reinterpret_cast<u32x2*>((bf16_t*)g.C + (long)grow * ldc + gcol) = o2;
;           } else if (g.epi == 2) {
;             const float rr = rsc[ai * HALF + wr * 64 + row_l];
;             v.x *= rr; v.y *= rr; v.z *= rr; v.w *= rr;
;             *reinterpret_cast<float4*>((float*)g.C + (long)grow * ldc + gcol) = v;
;           } else {
;             float4 x = xs[q];
;             x.x += v.x; x.y += v.y; x.z += v.z; x.w += v.w;
;             *reinterpret_cast<float4*>((float*)g.C + (long)grow * ldc + gcol) = x;
;             if (g.gnext) {
;               u32x2 o2; o2[0] = pk2(x.x * gn.x, x.y * gn.y); o2[1] = pk2(x.z * gn.z, x.w * gn.w);
;               *reinterpret_cast<u32x2*>(g.hbout + (long)grow * DM + gcol) = o2;
;               float sq = (x.x * x.x + x.y * x.y) + (x.z * x.z + x.w * x.w);
;               sq += shx_(sq, 1); sq += shx_(sq, 2); sq += shx_(sq, 4); sq += shx_(sq, 8);
;               if ((lane & 15) == 0) g.ss[(long)grow * 32 + pn * 4 + wc] = sq;
;             }
.LBB0_1249:
	v_mad_u64_u32 v[24:25], s[2:3], v22, s78, 0
	v_mov_b32_e32 v0, v25
	v_mad_u64_u32 v[26:27], s[2:3], v23, s78, v[0:1]
	v_mov_b32_e32 v25, v26
	v_lshl_add_u64 v[24:25], v[24:25], 2, s[34:35]
	s_waitcnt lgkmcnt(0)
	v_pk_add_f32 v[6:7], v[6:7], v[14:15]
	v_pk_add_f32 v[8:9], v[8:9], v[16:17]
	v_lshl_add_u64 v[24:25], v[94:95], 2, v[24:25]
	s_cmp_eq_u64 s[80:81], 0
	global_store_dwordx4 v[24:25], v[6:9], off
	s_cbranch_scc1 .LBB0_1253
	v_pk_mul_f32 v[24:25], v[18:19], v[6:7]
	v_pk_mul_f32 v[26:27], v[20:21], v[8:9]
	v_cvt_pk_bf16_f32 v24, v24, v25
	v_cvt_pk_bf16_f32 v25, v26, v27
	v_lshlrev_b64 v[26:27], 12, v[22:23]
	v_pk_mul_f32 v[6:7], v[6:7], v[6:7]
	v_pk_mul_f32 v[8:9], v[8:9], v[8:9]
	v_lshl_add_u64 v[26:27], s[20:21], 0, v[26:27]
	v_add_f32_e32 v0, v8, v9
	v_add_f32_e32 v6, v6, v7
	v_lshl_add_u64 v[26:27], v[94:95], 1, v[26:27]
	v_add_f32_e32 v0, v6, v0
	v_mov_b32_e32 v6, v208
	global_store_dwordx2 v[26:27], v[24:25], off
	s_nop 0
	v_lshlrev_b32_e32 v6, 2, v6
	v_xor_b32_e32 v6, 4, v6
	ds_bpermute_b32 v6, v6, v0
	s_waitcnt lgkmcnt(0)
	v_add_f32_e32 v0, v0, v6
	v_mov_b32_e32 v6, v208
	s_nop 0
	v_lshlrev_b32_e32 v6, 2, v6
	v_xor_b32_e32 v6, 8, v6
	ds_bpermute_b32 v6, v6, v0
	s_waitcnt lgkmcnt(0)
	v_add_f32_e32 v0, v0, v6
	v_mov_b32_e32 v6, v208
	s_nop 0
	v_lshlrev_b32_e32 v6, 2, v6
	v_xor_b32_e32 v6, 16, v6
	ds_bpermute_b32 v6, v6, v0
	s_waitcnt lgkmcnt(0)
	v_add_f32_e32 v6, v0, v6
	v_mov_b32_e32 v0, v208
	s_nop 0
	v_lshlrev_b32_e32 v0, 2, v0
	v_xor_b32_e32 v0, 32, v0
	ds_bpermute_b32 v7, v0, v6
	s_and_saveexec_b64 s[2:3], s[4:5]
	s_cbranch_execz .LBB0_1252
	v_lshlrev_b64 v[8:9], 7, v[22:23]
	v_lshl_add_u64 v[8:9], s[42:43], 0, v[8:9]
	v_lshl_add_u64 v[8:9], s[0:1], 2, v[8:9]
	v_lshlrev_b32_e32 v0, 2, v139
	v_lshl_add_u64 v[8:9], v[8:9], 0, v[0:1]
	s_waitcnt lgkmcnt(0)
	v_add_f32_e32 v0, v6, v7
	global_store_dword v[8:9], v0, off

; DI unsigned pk2(float a, float b) { f32x2 v; v[0] = a; v[1] = b; return __builtin_bit_cast(unsigned, __builtin_convertvector(v, bf16v2)); }
; DI void gemm_tile(const GD& g, int pm, int pn, bf16_t* shm) {
;     ...
;           float4 v = *reinterpret_cast<const float4*>(stgw + row_l * 68 + c4);
;           const int grow = brow + ai * HALF + wr * 64 + row_l;
;           if (g.epi == 0) {
;             if (g.rowscale) {
;               const float rr = rsc[ai * HALF + wr * 64 + row_l];
;               v.x *= rr; v.y *= rr; v.z *= rr; v.w *= rr;
;             }
;             u32x2 o2; o2[0] = pk2(v.x, v.y); o2[1] = pk2(v.z, v.w);
;             *reinterpret_cast<u32x2*>((bf16_t*)g.C + (long)grow * ldc + gcol) = o2;
;           } else if (g.epi == 2) {
;             const float rr = rsc[ai * HALF + wr * 64 + row_l];
;             v.x *= rr; v.y *= rr; v.z *= rr; v.w *= rr;
;             *reinterpret_cast<float4*>((float*)g.C + (long)grow * ldc + gcol) = v;
.LBB0_1259:
	v_mad_u64_u32 v[8:9], s[2:3], v22, s78, 0
	v_mov_b32_e32 v0, v9
	s_waitcnt lgkmcnt(0)
	v_cvt_pk_bf16_f32 v6, v14, v15
	v_mad_u64_u32 v[14:15], s[2:3], v23, s78, v[0:1]
	v_mov_b32_e32 v9, v14
	v_lshl_add_u64 v[8:9], v[8:9], 1, s[34:35]
	v_cvt_pk_bf16_f32 v7, v16, v17
	v_lshl_add_u64 v[8:9], v[94:95], 1, v[8:9]
	global_store_dwordx2 v[8:9], v[6:7], off
.LBB0_1260:
	s_waitcnt lgkmcnt(0)
	ds_read_b128 v[6:9], v35 offset:15232
	v_or3_b32 v14, v138, v34, 56
	s_mov_b64 s[10:11], -1
	s_mov_b64 s[2:3], 0
	s_cmp_lt_i32 s48, 2
	s_mov_b64 s[8:9], 0
	s_cbranch_scc1 .LBB0_1270
	s_cmp_eq_u32 s48, 2
	s_mov_b64 s[8:9], -1
	s_cbranch_scc0 .LBB0_1263
	v_lshl_add_u32 v0, v138, 2, v98
	ds_read_b32 v0, v0 offset:736
	v_mad_u64_u32 v[16:17], s[8:9], v14, s78, 0
	v_ashrrev_i32_e32 v15, 31, v14
	v_mov_b32_e32 v22, v17
	v_mad_u64_u32 v[22:23], s[8:9], v15, s78, v[22:23]
	v_mov_b32_e32 v17, v22
	v_lshl_add_u64 v[16:17], v[16:17], 2, s[34:35]
	v_lshl_add_u64 v[16:17], v[94:95], 2, v[16:17]
	s_waitcnt lgkmcnt(0)
	v_pk_mul_f32 v[22:23], v[6:7], v[0:1] op_sel_hi:[1,0]
	v_pk_mul_f32 v[24:25], v[8:9], v[0:1] op_sel_hi:[1,0]
	global_store_dwordx4 v[16:17], v[22:25], off
	s_mov_b64 s[8:9], 0

; DI unsigned pk2(float a, float b) { f32x2 v; v[0] = a; v[1] = b; return __builtin_bit_cast(unsigned, __builtin_convertvector(v, bf16v2)); }
; DI float shx_(float v, int m) { return __int_as_float(__builtin_amdgcn_ds_bpermute((lane_pinned_() ^ m) << 2, __float_as_int(v))); }
; DI int shx_(int v, int m) { return __builtin_amdgcn_ds_bpermute((lane_pinned_() ^ m) << 2, v); }
; DI void gemm_tile(const GD& g, int pm, int pn, bf16_t* shm) {
;     ...
; #pragma unroll
;         for (int q = 0; q < 4; ++q) {
;           const int row_l = (pb8 * 4 + q) * 4 + (lane >> 4);
;           float4 v = *reinterpret_cast<const float4*>(stgw + row_l * 68 + c4);
;           const int grow = brow + ai * HALF + wr * 64 + row_l;
;           if (g.epi == 0) {
;             if (g.rowscale) {
;               const float rr = rsc[ai * HALF + wr * 64 + row_l];
;               v.x *= rr; v.y *= rr; v.z *= rr; v.w *= rr;
;             }
;             u32x2 o2; o2[0] = pk2(v.x, v.y); o2[1] = pk2(v.z, v.w);
;             *reinterpret_cast<u32x2*>((bf16_t*)g.C + (long)grow * ldc + gcol) = o2;
;           } else if (g.epi == 2) {
;             const float rr = rsc[ai * HALF + wr * 64 + row_l];
;             v.x *= rr; v.y *= rr; v.z *= rr; v.w *= rr;
;             *reinterpret_cast<float4*>((float*)g.C + (long)grow * ldc + gcol) = v;
;           } else {
;             float4 x = xs[q];
;             x.x += v.x; x.y += v.y; x.z += v.z; x.w += v.w;
;             *reinterpret_cast<float4*>((float*)g.C + (long)grow * ldc + gcol) = x;
;             if (g.gnext) {
;               u32x2 o2; o2[0] = pk2(x.x * gn.x, x.y * gn.y); o2[1] = pk2(x.z * gn.z, x.w * gn.w);
;               *reinterpret_cast<u32x2*>(g.hbout + (long)grow * DM + gcol) = o2;
;               float sq = (x.x * x.x + x.y * x.y) + (x.z * x.z + x.w * x.w);
;               sq += shx_(sq, 1); sq += shx_(sq, 2); sq += shx_(sq, 4); sq += shx_(sq, 8);
;               if ((lane & 15) == 0) g.ss[(long)grow * 32 + pn * 4 + wc] = sq;
;             }
.LBB0_1265:
	v_mad_u64_u32 v[16:17], s[2:3], v14, s78, 0
	v_mov_b32_e32 v0, v17
	v_mad_u64_u32 v[22:23], s[2:3], v15, s78, v[0:1]
	v_mov_b32_e32 v17, v22
	v_lshl_add_u64 v[16:17], v[16:17], 2, s[34:35]
	s_waitcnt lgkmcnt(0)
	v_pk_add_f32 v[10:11], v[10:11], v[6:7]
	v_pk_add_f32 v[12:13], v[12:13], v[8:9]
	v_lshl_add_u64 v[16:17], v[94:95], 2, v[16:17]
	s_cmp_eq_u64 s[80:81], 0
	global_store_dwordx4 v[16:17], v[10:13], off
	s_cbranch_scc1 .LBB0_1269
	v_pk_mul_f32 v[16:17], v[18:19], v[10:11]
	v_pk_mul_f32 v[22:23], v[20:21], v[12:13]
	v_cvt_pk_bf16_f32 v16, v16, v17
	v_cvt_pk_bf16_f32 v17, v22, v23
	v_lshlrev_b64 v[22:23], 12, v[14:15]
	v_pk_mul_f32 v[10:11], v[10:11], v[10:11]
	v_pk_mul_f32 v[12:13], v[12:13], v[12:13]
	v_lshl_add_u64 v[22:23], s[20:21], 0, v[22:23]
	v_add_f32_e32 v0, v12, v13
	v_add_f32_e32 v10, v10, v11
	v_lshl_add_u64 v[22:23], v[94:95], 1, v[22:23]
	v_add_f32_e32 v0, v10, v0
	v_mov_b32_e32 v10, v208
	global_store_dwordx2 v[22:23], v[16:17], off
	s_nop 0
	v_lshlrev_b32_e32 v10, 2, v10
	v_xor_b32_e32 v10, 4, v10
	ds_bpermute_b32 v10, v10, v0
	s_waitcnt lgkmcnt(0)
	v_add_f32_e32 v0, v0, v10
	v_mov_b32_e32 v10, v208
	s_nop 0
	v_lshlrev_b32_e32 v10, 2, v10
	v_xor_b32_e32 v10, 8, v10
	ds_bpermute_b32 v10, v10, v0
	s_waitcnt lgkmcnt(0)
	v_add_f32_e32 v0, v0, v10
	v_mov_b32_e32 v10, v208
	s_nop 0
	v_lshlrev_b32_e32 v10, 2, v10
	v_xor_b32_e32 v10, 16, v10
	ds_bpermute_b32 v10, v10, v0
	s_waitcnt lgkmcnt(0)
	v_add_f32_e32 v10, v0, v10
	v_mov_b32_e32 v0, v208
	s_nop 0
	v_lshlrev_b32_e32 v0, 2, v0
	v_xor_b32_e32 v0, 32, v0
	ds_bpermute_b32 v11, v0, v10
	s_and_saveexec_b64 s[2:3], s[4:5]
	s_cbranch_execz .LBB0_1268
	v_lshlrev_b64 v[12:13], 7, v[14:15]
	v_lshl_add_u64 v[12:13], s[42:43], 0, v[12:13]
	v_lshl_add_u64 v[12:13], s[0:1], 2, v[12:13]
	v_lshlrev_b32_e32 v0, 2, v139
	v_lshl_add_u64 v[12:13], v[12:13], 0, v[0:1]
	s_waitcnt lgkmcnt(0)
	v_add_f32_e32 v0, v10, v11
	global_store_dword v[12:13], v0, off

; DI unsigned pk2(float a, float b) { f32x2 v; v[0] = a; v[1] = b; return __builtin_bit_cast(unsigned, __builtin_convertvector(v, bf16v2)); }
; DI void gemm_tile(const GD& g, int pm, int pn, bf16_t* shm) {
;     ...
;           float4 v = *reinterpret_cast<const float4*>(stgw + row_l * 68 + c4);
;           const int grow = brow + ai * HALF + wr * 64 + row_l;
;           if (g.epi == 0) {
;             if (g.rowscale) {
;               const float rr = rsc[ai * HALF + wr * 64 + row_l];
;               v.x *= rr; v.y *= rr; v.z *= rr; v.w *= rr;
;             }
;             u32x2 o2; o2[0] = pk2(v.x, v.y); o2[1] = pk2(v.z, v.w);
;             *reinterpret_cast<u32x2*>((bf16_t*)g.C + (long)grow * ldc + gcol) = o2;
;           } else if (g.epi == 2) {
;             const float rr = rsc[ai * HALF + wr * 64 + row_l];
;             v.x *= rr; v.y *= rr; v.z *= rr; v.w *= rr;
;             *reinterpret_cast<float4*>((float*)g.C + (long)grow * ldc + gcol) = v;
.LBB0_1275:
	s_waitcnt lgkmcnt(0)
	v_cvt_pk_bf16_f32 v6, v6, v7
	v_cvt_pk_bf16_f32 v7, v8, v9
	v_mad_u64_u32 v[8:9], s[2:3], v14, s78, 0
	v_mov_b32_e32 v0, v9
	v_mad_u64_u32 v[10:11], s[2:3], v15, s78, v[0:1]
	v_mov_b32_e32 v9, v10
	v_lshl_add_u64 v[8:9], v[8:9], 1, s[34:35]
	v_lshl_add_u64 v[8:9], v[94:95], 1, v[8:9]
	global_store_dwordx2 v[8:9], v[6:7], off
.LBB0_1276:
	s_waitcnt lgkmcnt(0)
	ds_read_b128 v[6:9], v35 offset:16320
	v_or3_b32 v10, v138, v34, 60
	s_mov_b64 s[10:11], -1
	s_mov_b64 s[2:3], 0
	s_cmp_lt_i32 s48, 2
	s_mov_b64 s[8:9], 0
	s_cbranch_scc1 .LBB0_1286
	s_cmp_eq_u32 s48, 2
	s_mov_b64 s[8:9], -1
	s_cbranch_scc0 .LBB0_1279
	v_lshl_add_u32 v0, v138, 2, v98
	ds_read_b32 v0, v0 offset:752
	v_mad_u64_u32 v[12:13], s[8:9], v10, s78, 0
	v_ashrrev_i32_e32 v11, 31, v10
	v_mov_b32_e32 v14, v13
	v_mad_u64_u32 v[14:15], s[8:9], v11, s78, v[14:15]
	v_mov_b32_e32 v13, v14
	v_lshl_add_u64 v[12:13], v[12:13], 2, s[34:35]
	v_lshl_add_u64 v[16:17], v[94:95], 2, v[12:13]
	s_waitcnt lgkmcnt(0)
	v_pk_mul_f32 v[12:13], v[6:7], v[0:1] op_sel_hi:[1,0]
	v_pk_mul_f32 v[14:15], v[8:9], v[0:1] op_sel_hi:[1,0]
	global_store_dwordx4 v[16:17], v[12:15], off
	s_mov_b64 s[8:9], 0

; DI unsigned pk2(float a, float b) { f32x2 v; v[0] = a; v[1] = b; return __builtin_bit_cast(unsigned, __builtin_convertvector(v, bf16v2)); }
; DI float shx_(float v, int m) { return __int_as_float(__builtin_amdgcn_ds_bpermute((lane_pinned_() ^ m) << 2, __float_as_int(v))); }
; DI int shx_(int v, int m) { return __builtin_amdgcn_ds_bpermute((lane_pinned_() ^ m) << 2, v); }
; DI void gemm_tile(const GD& g, int pm, int pn, bf16_t* shm) {
;     ...
; #pragma unroll
;         for (int q = 0; q < 4; ++q) {
;           const int row_l = (pb8 * 4 + q) * 4 + (lane >> 4);
;           float4 v = *reinterpret_cast<const float4*>(stgw + row_l * 68 + c4);
;           const int grow = brow + ai * HALF + wr * 64 + row_l;
;           if (g.epi == 0) {
;             if (g.rowscale) {
;               const float rr = rsc[ai * HALF + wr * 64 + row_l];
;               v.x *= rr; v.y *= rr; v.z *= rr; v.w *= rr;
;             }
;             u32x2 o2; o2[0] = pk2(v.x, v.y); o2[1] = pk2(v.z, v.w);
;             *reinterpret_cast<u32x2*>((bf16_t*)g.C + (long)grow * ldc + gcol) = o2;
;           } else if (g.epi == 2) {
;             const float rr = rsc[ai * HALF + wr * 64 + row_l];
;             v.x *= rr; v.y *= rr; v.z *= rr; v.w *= rr;
;             *reinterpret_cast<float4*>((float*)g.C + (long)grow * ldc + gcol) = v;
;           } else {
;             float4 x = xs[q];
;             x.x += v.x; x.y += v.y; x.z += v.z; x.w += v.w;
;             *reinterpret_cast<float4*>((float*)g.C + (long)grow * ldc + gcol) = x;
;             if (g.gnext) {
;               u32x2 o2; o2[0] = pk2(x.x * gn.x, x.y * gn.y); o2[1] = pk2(x.z * gn.z, x.w * gn.w);
;               *reinterpret_cast<u32x2*>(g.hbout + (long)grow * DM + gcol) = o2;
;               float sq = (x.x * x.x + x.y * x.y) + (x.z * x.z + x.w * x.w);
;               sq += shx_(sq, 1); sq += shx_(sq, 2); sq += shx_(sq, 4); sq += shx_(sq, 8);
;               if ((lane & 15) == 0) g.ss[(long)grow * 32 + pn * 4 + wc] = sq;
;             }
.LBB0_1281:
	v_mad_u64_u32 v[12:13], s[2:3], v10, s78, 0
	v_mov_b32_e32 v0, v13
	v_mad_u64_u32 v[14:15], s[2:3], v11, s78, v[0:1]
	v_mov_b32_e32 v13, v14
	v_lshl_add_u64 v[12:13], v[12:13], 2, s[34:35]
	s_waitcnt lgkmcnt(0)
	v_pk_add_f32 v[2:3], v[2:3], v[6:7]
	v_pk_add_f32 v[4:5], v[4:5], v[8:9]
	v_lshl_add_u64 v[12:13], v[94:95], 2, v[12:13]
	s_cmp_eq_u64 s[80:81], 0
	global_store_dwordx4 v[12:13], v[2:5], off
	s_cbranch_scc1 .LBB0_1285
	v_pk_mul_f32 v[12:13], v[18:19], v[2:3]
	v_pk_mul_f32 v[14:15], v[20:21], v[4:5]
	v_cvt_pk_bf16_f32 v12, v12, v13
	v_cvt_pk_bf16_f32 v13, v14, v15
	v_lshlrev_b64 v[14:15], 12, v[10:11]
	v_pk_mul_f32 v[2:3], v[2:3], v[2:3]
	v_pk_mul_f32 v[4:5], v[4:5], v[4:5]
	v_lshl_add_u64 v[14:15], s[20:21], 0, v[14:15]
	v_add_f32_e32 v0, v4, v5
	v_add_f32_e32 v2, v2, v3
	v_lshl_add_u64 v[14:15], v[94:95], 1, v[14:15]
	v_add_f32_e32 v0, v2, v0
	v_mov_b32_e32 v2, v208
	global_store_dwordx2 v[14:15], v[12:13], off
	s_nop 0
	v_lshlrev_b32_e32 v2, 2, v2
	v_xor_b32_e32 v2, 4, v2
	ds_bpermute_b32 v2, v2, v0
	s_waitcnt lgkmcnt(0)
	v_add_f32_e32 v0, v0, v2
	v_mov_b32_e32 v2, v208
	s_nop 0
	v_lshlrev_b32_e32 v2, 2, v2
	v_xor_b32_e32 v2, 8, v2
	ds_bpermute_b32 v2, v2, v0
	s_waitcnt lgkmcnt(0)
	v_add_f32_e32 v0, v0, v2
	v_mov_b32_e32 v2, v208
	s_nop 0
	v_lshlrev_b32_e32 v2, 2, v2
	v_xor_b32_e32 v2, 16, v2
	ds_bpermute_b32 v2, v2, v0
	s_waitcnt lgkmcnt(0)
	v_add_f32_e32 v2, v0, v2
	v_mov_b32_e32 v0, v208
	s_nop 0
	v_lshlrev_b32_e32 v0, 2, v0
	v_xor_b32_e32 v0, 32, v0
	ds_bpermute_b32 v3, v0, v2
	s_and_saveexec_b64 s[2:3], s[4:5]
	s_cbranch_execz .LBB0_1284
	v_lshlrev_b64 v[4:5], 7, v[10:11]
	v_lshl_add_u64 v[4:5], s[42:43], 0, v[4:5]
	v_lshl_add_u64 v[4:5], s[0:1], 2, v[4:5]
	v_lshlrev_b32_e32 v0, 2, v139
	v_lshl_add_u64 v[4:5], v[4:5], 0, v[0:1]
	s_waitcnt lgkmcnt(0)
	v_add_f32_e32 v0, v2, v3
	global_store_dword v[4:5], v0, off
